# GEMM mainloops: loop-carried pointer/counter SALU updates moved from the last MMA tail (before the loop-closing barrier) to the head of the last load part
# speedup vs baseline: 1.0128x; 1.0038x over previous
; #define PG8_STAGE(bufoff, gbase, voff) do { _Pragma("unroll") for (int _i = 0; _i < 2; ++_i) \
;         __builtin_amdgcn_global_load_lds((const unsigned*)((const char*)(gbase) + (voff)[_i]), (LAS unsigned*)(lds + (bufoff) + ldsw + _i * 8192), 16, 0, 0); } while (0)
; #define PG8_LDA(dst, b, h) do { _Pragma("unroll") for (int m = 0; m < 4; ++m) _Pragma("unroll") for (int k = 0; k < 2; ++k) dst[m][k] = *(const LAS bf16x8*)(lds + PG8_SA(b, h) + aoff + m * 2048 + k * 1024); } while (0)
; #define PG8_LDB(dst, b, h) do { _Pragma("unroll") for (int n = 0; n < 2; ++n) _Pragma("unroll") for (int k = 0; k < 2; ++k) dst[n][k] = *(const LAS bf16x8*)(lds + PG8_SB(b, h) + boff + n * 2048 + k * 1024); } while (0)
; #define PG8_MMA(ai, bj, At, Bt) do { __builtin_amdgcn_s_setprio(1); _Pragma("unroll") for (int m = 0; m < 4; ++m) _Pragma("unroll") for (int n = 0; n < 2; ++n) _Pragma("unroll") for (int k = 0; k < 2; ++k) \
;         acc[ai][bj][m][n] = __builtin_amdgcn_mfma_f32_16x16x32_bf16(Bt[n][k], At[m][k], acc[ai][bj][m][n], 0, 0, 0); __builtin_amdgcn_s_setprio(0); } while (0)
; #define PG8_WAIT_V(n) asm volatile("s_waitcnt vmcnt(" #n ")" ::: "memory")
; #define PG8_WAIT_L(n) asm volatile("s_waitcnt lgkmcnt(" #n ")" ::: "memory")
; #define PG8_BAR __builtin_amdgcn_s_barrier()
; template <class Epi>
; __device__ __forceinline__ void gemm_phase(LAS unsigned char* lds, const Gemm g, const StaticOrder& S, const Epi& E, const int tid) {
;     ...
;             const bool last = (t == nt - 2);
;             const char* a1 = cA + (size_t)(t + 1) * kstep;
;             const char* a2 = last ? nA : cA + (size_t)(t + 2) * kstep; const char* b2 = last ? nB : cB + (size_t)(t + 2) * kstep;
;             const char* a3 = a2 + kstep; const char* b3 = b2 + kstep;
;             PG8_LDB(B0, 0, 0); PG8_SCHED; PG8_LDA(At, 0, 0); PG8_STAGE(PG8_SA(1, 1), a1 + hstep, voffA);
;             PG8_WAIT_L(8); PG8_BAR; PG8_WAIT_L(0); PG8_MMA(0, 0, At, B0); PG8_BAR; PG8_SCHED;
;             PG8_LDB(B1, 0, 1); PG8_STAGE(PG8_SB(0, 0), b2, voffB);
;             PG8_BAR; PG8_WAIT_L(0); PG8_MMA(0, 1, At, B1); PG8_BAR;
;             PG8_LDA(At, 0, 1); PG8_STAGE(PG8_SA(0, 0), a2, voffA);
;             PG8_BAR; PG8_WAIT_L(0); PG8_MMA(1, 0, At, B0); PG8_BAR; PG8_SCHED;
;             PG8_STAGE(PG8_SB(0, 1), b2 + hstep, voffB);
;             PG8_WAIT_V(6); PG8_BAR; PG8_MMA(1, 1, At, B1); PG8_BAR;
.Lgprio0:
.LBB0_40:
	s_add_u32 s20, s18, 0xffe00080
	s_addc_u32 s21, s19, -1
	s_add_i32 s50, 0, 0x10000
	v_add_u32_e32 v70, s50, v173
	ds_read_b128 v[50:53], v70
	ds_read_b128 v[54:57], v70 offset:1024
	ds_read_b128 v[66:69], v70 offset:2048
	ds_read_b128 v[70:73], v70 offset:3072
	s_cmpk_eq_i32 s49, 0x7c
	s_cselect_b32 s23, s13, s21
	s_cselect_b32 s22, s44, s20
	s_cselect_b32 s21, s11, s48
	s_cselect_b32 s20, s45, s47
	s_add_i32 m0, s3, 0xc000
	ds_read_b128 v[176:179], v174
	ds_read_b128 v[180:183], v174 offset:1024
	ds_read_b128 v[184:187], v174 offset:2048
	ds_read_b128 v[188:191], v174 offset:3072
	ds_read_b128 v[192:195], v174 offset:4096
	ds_read_b128 v[196:199], v174 offset:5120
	ds_read_b128 v[210:213], v174 offset:6144
	ds_read_b128 v[214:217], v174 offset:7168
	global_load_lds_dwordx4 v168, s[18:19]
	v_lshl_add_u64 v[170:171], s[18:19], 0, v[166:167]
	s_add_i32 m0, s3, 0xe000
	s_nop 0
	global_load_lds_dwordx4 v[170:171], off
	s_waitcnt lgkmcnt(8)
	s_barrier
	s_waitcnt lgkmcnt(0)
	v_mfma_f32_16x16x32_bf16 v[142:145], v[50:53], v[176:179], v[142:145]
	v_mfma_f32_16x16x32_bf16 v[138:141], v[66:69], v[176:179], v[138:141]
	v_mfma_f32_16x16x32_bf16 v[126:129], v[50:53], v[184:187], v[126:129]
	v_mfma_f32_16x16x32_bf16 v[122:125], v[66:69], v[184:187], v[122:125]
	v_mfma_f32_16x16x32_bf16 v[110:113], v[50:53], v[192:195], v[110:113]
	v_mfma_f32_16x16x32_bf16 v[106:109], v[66:69], v[192:195], v[106:109]
	v_mfma_f32_16x16x32_bf16 v[94:97], v[50:53], v[210:213], v[94:97]
	v_mfma_f32_16x16x32_bf16 v[90:93], v[66:69], v[210:213], v[90:93]
	v_mfma_f32_16x16x32_bf16 v[142:145], v[54:57], v[180:183], v[142:145]
	v_mfma_f32_16x16x32_bf16 v[138:141], v[70:73], v[180:183], v[138:141]
	v_mfma_f32_16x16x32_bf16 v[126:129], v[54:57], v[188:191], v[126:129]
	v_mfma_f32_16x16x32_bf16 v[122:125], v[70:73], v[188:191], v[122:125]
	v_mfma_f32_16x16x32_bf16 v[110:113], v[54:57], v[196:199], v[110:113]
	v_mfma_f32_16x16x32_bf16 v[106:109], v[70:73], v[196:199], v[106:109]
	v_mfma_f32_16x16x32_bf16 v[94:97], v[54:57], v[214:217], v[94:97]
	v_mfma_f32_16x16x32_bf16 v[90:93], v[70:73], v[214:217], v[90:93]
	s_barrier
	s_add_i32 s54, 0, 0x14000
	v_add_u32_e32 v170, s54, v173
	s_add_i32 s50, s50, s31
	ds_read_b128 v[218:221], v170
	ds_read_b128 v[222:225], v170 offset:1024
	ds_read_b128 v[226:229], v170 offset:2048
	ds_read_b128 v[230:233], v170 offset:3072
	v_lshl_add_u64 v[170:171], s[20:21], 0, v[0:1]
	s_mov_b32 m0, s50
	v_lshl_add_u64 v[200:201], s[20:21], 0, v[164:165]
	global_load_lds_dwordx4 v[170:171], off
	s_add_i32 m0, s50, 0x2000
	s_nop 0
	global_load_lds_dwordx4 v[200:201], off
	s_barrier
	s_waitcnt lgkmcnt(0)
	v_mfma_f32_16x16x32_bf16 v[134:137], v[218:221], v[176:179], v[134:137]
	v_mfma_f32_16x16x32_bf16 v[130:133], v[226:229], v[176:179], v[130:133]
	v_mfma_f32_16x16x32_bf16 v[118:121], v[218:221], v[184:187], v[118:121]
	v_mfma_f32_16x16x32_bf16 v[114:117], v[226:229], v[184:187], v[114:117]
	v_mfma_f32_16x16x32_bf16 v[102:105], v[218:221], v[192:195], v[102:105]
	v_mfma_f32_16x16x32_bf16 v[98:101], v[226:229], v[192:195], v[98:101]
	v_mfma_f32_16x16x32_bf16 v[86:89], v[218:221], v[210:213], v[86:89]
	v_mfma_f32_16x16x32_bf16 v[82:85], v[226:229], v[210:213], v[82:85]
	v_mfma_f32_16x16x32_bf16 v[134:137], v[222:225], v[180:183], v[134:137]
	v_mfma_f32_16x16x32_bf16 v[130:133], v[230:233], v[180:183], v[130:133]
	v_mfma_f32_16x16x32_bf16 v[118:121], v[222:225], v[188:191], v[118:121]
	v_mfma_f32_16x16x32_bf16 v[114:117], v[230:233], v[188:191], v[114:117]
	v_mfma_f32_16x16x32_bf16 v[102:105], v[222:225], v[196:199], v[102:105]
	v_mfma_f32_16x16x32_bf16 v[98:101], v[230:233], v[196:199], v[98:101]
	v_mfma_f32_16x16x32_bf16 v[86:89], v[222:225], v[214:217], v[86:89]
	v_mfma_f32_16x16x32_bf16 v[82:85], v[230:233], v[214:217], v[82:85]
	s_mov_b32 m0, s3
	v_lshl_add_u64 v[234:235], s[22:23], 0, v[160:161]
	s_barrier
	ds_read_b128 v[176:179], v174 offset:16384
	ds_read_b128 v[180:183], v174 offset:17408
	ds_read_b128 v[184:187], v174 offset:18432
	ds_read_b128 v[188:191], v174 offset:19456
	ds_read_b128 v[192:195], v174 offset:20480
	ds_read_b128 v[196:199], v174 offset:21504
	ds_read_b128 v[210:213], v174 offset:22528
	ds_read_b128 v[214:217], v174 offset:23552
	global_load_lds_dwordx4 v[234:235], off
	v_lshl_add_u64 v[236:237], s[22:23], 0, v[162:163]
	s_mov_b32 m0, s34
	s_nop 0
	global_load_lds_dwordx4 v[236:237], off
	s_barrier
	s_waitcnt lgkmcnt(0)
	v_mfma_f32_16x16x32_bf16 v[78:81], v[50:53], v[176:179], v[78:81]
	v_mfma_f32_16x16x32_bf16 v[74:77], v[66:69], v[176:179], v[74:77]
	v_mfma_f32_16x16x32_bf16 v[46:49], v[50:53], v[184:187], v[46:49]
	v_mfma_f32_16x16x32_bf16 v[42:45], v[66:69], v[184:187], v[42:45]
	v_mfma_f32_16x16x32_bf16 v[30:33], v[50:53], v[192:195], v[30:33]
	v_mfma_f32_16x16x32_bf16 v[26:29], v[66:69], v[192:195], v[26:29]
	v_mfma_f32_16x16x32_bf16 v[14:17], v[50:53], v[210:213], v[14:17]
	v_mfma_f32_16x16x32_bf16 v[10:13], v[66:69], v[210:213], v[10:13]
	v_mfma_f32_16x16x32_bf16 v[78:81], v[54:57], v[180:183], v[78:81]
	v_mfma_f32_16x16x32_bf16 v[74:77], v[70:73], v[180:183], v[74:77]
	v_mfma_f32_16x16x32_bf16 v[46:49], v[54:57], v[188:191], v[46:49]
	v_mfma_f32_16x16x32_bf16 v[42:45], v[70:73], v[188:191], v[42:45]
	v_mfma_f32_16x16x32_bf16 v[30:33], v[54:57], v[196:199], v[30:33]
	v_mfma_f32_16x16x32_bf16 v[26:29], v[70:73], v[196:199], v[26:29]
	v_mfma_f32_16x16x32_bf16 v[14:17], v[54:57], v[214:217], v[14:17]
	v_mfma_f32_16x16x32_bf16 v[10:13], v[70:73], v[214:217], v[10:13]
	s_barrier
	s_add_u32 s52, s20, 0x200000
	s_addc_u32 s53, s21, 0
	s_add_i32 s50, s54, s31
	s_mov_b32 m0, s50
	s_nop 0
	global_load_lds_dwordx4 v0, s[52:53]
	s_add_i32 m0, s50, 0x2000
	s_nop 0
	global_load_lds_dwordx4 v164, s[52:53]
	s_waitcnt vmcnt(6)
	s_barrier
; #define PG8_STAGE(bufoff, gbase, voff) do { _Pragma("unroll") for (int _i = 0; _i < 2; ++_i) \
;         __builtin_amdgcn_global_load_lds((const unsigned*)((const char*)(gbase) + (voff)[_i]), (LAS unsigned*)(lds + (bufoff) + ldsw + _i * 8192), 16, 0, 0); } while (0)
; #define PG8_LDA(dst, b, h) do { _Pragma("unroll") for (int m = 0; m < 4; ++m) _Pragma("unroll") for (int k = 0; k < 2; ++k) dst[m][k] = *(const LAS bf16x8*)(lds + PG8_SA(b, h) + aoff + m * 2048 + k * 1024); } while (0)
; #define PG8_LDB(dst, b, h) do { _Pragma("unroll") for (int n = 0; n < 2; ++n) _Pragma("unroll") for (int k = 0; k < 2; ++k) dst[n][k] = *(const LAS bf16x8*)(lds + PG8_SB(b, h) + boff + n * 2048 + k * 1024); } while (0)
; #define PG8_MMA(ai, bj, At, Bt) do { __builtin_amdgcn_s_setprio(1); _Pragma("unroll") for (int m = 0; m < 4; ++m) _Pragma("unroll") for (int n = 0; n < 2; ++n) _Pragma("unroll") for (int k = 0; k < 2; ++k) \
;         acc[ai][bj][m][n] = __builtin_amdgcn_mfma_f32_16x16x32_bf16(Bt[n][k], At[m][k], acc[ai][bj][m][n], 0, 0, 0); __builtin_amdgcn_s_setprio(0); } while (0)
; #define PG8_WAIT_V(n) asm volatile("s_waitcnt vmcnt(" #n ")" ::: "memory")
; #define PG8_WAIT_L(n) asm volatile("s_waitcnt lgkmcnt(" #n ")" ::: "memory")
; #define PG8_BAR __builtin_amdgcn_s_barrier()
; #define PG8_SCHED __builtin_amdgcn_sched_barrier(0)
; template <class Epi>
; __device__ __forceinline__ void gemm_phase(LAS unsigned char* lds, const Gemm g, const StaticOrder& S, const Epi& E, const int tid) {
;     ...
;             PG8_WAIT_V(6); PG8_BAR; PG8_MMA(1, 1, At, B1); PG8_BAR;
;             PG8_LDB(B0, 1, 0); PG8_SCHED; PG8_LDA(At, 1, 0); PG8_STAGE(PG8_SA(0, 1), a2 + hstep, voffA);
;             PG8_WAIT_L(8); PG8_BAR; PG8_WAIT_L(0); PG8_MMA(0, 0, At, B0); PG8_BAR; PG8_SCHED;
;             PG8_LDB(B1, 1, 1); PG8_STAGE(PG8_SB(1, 0), b3, voffB);
;             PG8_BAR; PG8_WAIT_L(0); PG8_MMA(0, 1, At, B1); PG8_BAR;
;             PG8_LDA(At, 1, 1); PG8_STAGE(PG8_SA(1, 0), a3, voffA);
	v_mfma_f32_16x16x32_bf16 v[38:41], v[218:221], v[184:187], v[38:41]
	v_mfma_f32_16x16x32_bf16 v[34:37], v[226:229], v[184:187], v[34:37]
	v_mfma_f32_16x16x32_bf16 v[22:25], v[218:221], v[192:195], v[22:25]
	v_mfma_f32_16x16x32_bf16 v[18:21], v[226:229], v[192:195], v[18:21]
	v_mfma_f32_16x16x32_bf16 v[6:9], v[218:221], v[210:213], v[6:9]
	v_mfma_f32_16x16x32_bf16 v[2:5], v[226:229], v[210:213], v[2:5]
	v_mfma_f32_16x16x32_bf16 v[50:53], v[218:221], v[176:179], v[62:65]
	v_mfma_f32_16x16x32_bf16 v[54:57], v[226:229], v[176:179], v[58:61]
	v_mfma_f32_16x16x32_bf16 v[38:41], v[222:225], v[188:191], v[38:41]
	v_mfma_f32_16x16x32_bf16 v[34:37], v[230:233], v[188:191], v[34:37]
	v_mfma_f32_16x16x32_bf16 v[22:25], v[222:225], v[196:199], v[22:25]
	v_mfma_f32_16x16x32_bf16 v[18:21], v[230:233], v[196:199], v[18:21]
	v_mfma_f32_16x16x32_bf16 v[6:9], v[222:225], v[214:217], v[6:9]
	v_mfma_f32_16x16x32_bf16 v[2:5], v[230:233], v[214:217], v[2:5]
	v_mfma_f32_16x16x32_bf16 v[50:53], v[222:225], v[180:183], v[50:53]
	v_mfma_f32_16x16x32_bf16 v[54:57], v[230:233], v[180:183], v[54:57]
	s_add_i32 s50, 0, 0x18000
	v_add_u32_e32 v70, s50, v173
	s_barrier
	ds_read_b128 v[58:61], v70
	ds_read_b128 v[62:65], v70 offset:1024
	ds_read_b128 v[66:69], v70 offset:2048
	ds_read_b128 v[70:73], v70 offset:3072
	s_add_u32 s22, s22, 0x200000
	s_addc_u32 s23, s23, 0
	s_mov_b32 m0, s35
	ds_read_b128 v[176:179], v174 offset:32768
	ds_read_b128 v[180:183], v174 offset:33792
	ds_read_b128 v[184:187], v174 offset:34816
	ds_read_b128 v[188:191], v174 offset:35840
	ds_read_b128 v[192:195], v174 offset:36864
	ds_read_b128 v[196:199], v174 offset:37888
	ds_read_b128 v[210:213], v174 offset:38912
	ds_read_b128 v[214:217], v174 offset:39936
	global_load_lds_dwordx4 v160, s[22:23]
	s_mov_b32 m0, s36
	s_nop 0
	global_load_lds_dwordx4 v162, s[22:23]
	s_waitcnt lgkmcnt(8)
	s_barrier
	s_waitcnt lgkmcnt(0)
	v_mfma_f32_16x16x32_bf16 v[142:145], v[58:61], v[176:179], v[142:145]
	v_mfma_f32_16x16x32_bf16 v[138:141], v[66:69], v[176:179], v[138:141]
	v_mfma_f32_16x16x32_bf16 v[126:129], v[58:61], v[184:187], v[126:129]
	v_mfma_f32_16x16x32_bf16 v[122:125], v[66:69], v[184:187], v[122:125]
	v_mfma_f32_16x16x32_bf16 v[110:113], v[58:61], v[192:195], v[110:113]
	v_mfma_f32_16x16x32_bf16 v[106:109], v[66:69], v[192:195], v[106:109]
	v_mfma_f32_16x16x32_bf16 v[94:97], v[58:61], v[210:213], v[94:97]
	v_mfma_f32_16x16x32_bf16 v[90:93], v[66:69], v[210:213], v[90:93]
	v_mfma_f32_16x16x32_bf16 v[142:145], v[62:65], v[180:183], v[142:145]
	v_mfma_f32_16x16x32_bf16 v[138:141], v[70:73], v[180:183], v[138:141]
	v_mfma_f32_16x16x32_bf16 v[126:129], v[62:65], v[188:191], v[126:129]
	v_mfma_f32_16x16x32_bf16 v[122:125], v[70:73], v[188:191], v[122:125]
	v_mfma_f32_16x16x32_bf16 v[110:113], v[62:65], v[196:199], v[110:113]
	v_mfma_f32_16x16x32_bf16 v[106:109], v[70:73], v[196:199], v[106:109]
	v_mfma_f32_16x16x32_bf16 v[94:97], v[62:65], v[214:217], v[94:97]
	v_mfma_f32_16x16x32_bf16 v[90:93], v[70:73], v[214:217], v[90:93]
	s_barrier
	s_add_i32 s22, 0, 0x1c000
	s_add_i32 s23, s50, s31
	v_add_u32_e32 v175, s22, v173
	v_lshl_add_u64 v[170:171], v[170:171], 0, s[56:57]
	s_mov_b32 m0, s23
	ds_read_b128 v[218:221], v175
	ds_read_b128 v[222:225], v175 offset:1024
	ds_read_b128 v[226:229], v175 offset:2048
	ds_read_b128 v[230:233], v175 offset:3072
	global_load_lds_dwordx4 v[170:171], off
	v_lshl_add_u64 v[170:171], v[200:201], 0, s[56:57]
	s_add_i32 m0, s23, 0x2000
	s_nop 0
	global_load_lds_dwordx4 v[170:171], off
	s_barrier
	s_waitcnt lgkmcnt(0)
	v_mfma_f32_16x16x32_bf16 v[134:137], v[218:221], v[176:179], v[134:137]
	v_mfma_f32_16x16x32_bf16 v[130:133], v[226:229], v[176:179], v[130:133]
	v_mfma_f32_16x16x32_bf16 v[118:121], v[218:221], v[184:187], v[118:121]
	v_mfma_f32_16x16x32_bf16 v[114:117], v[226:229], v[184:187], v[114:117]
	v_mfma_f32_16x16x32_bf16 v[102:105], v[218:221], v[192:195], v[102:105]
	v_mfma_f32_16x16x32_bf16 v[98:101], v[226:229], v[192:195], v[98:101]
	v_mfma_f32_16x16x32_bf16 v[86:89], v[218:221], v[210:213], v[86:89]
	v_mfma_f32_16x16x32_bf16 v[82:85], v[226:229], v[210:213], v[82:85]
	v_mfma_f32_16x16x32_bf16 v[134:137], v[222:225], v[180:183], v[134:137]
	v_mfma_f32_16x16x32_bf16 v[130:133], v[230:233], v[180:183], v[130:133]
	v_mfma_f32_16x16x32_bf16 v[118:121], v[222:225], v[188:191], v[118:121]
	v_mfma_f32_16x16x32_bf16 v[114:117], v[230:233], v[188:191], v[114:117]
	v_mfma_f32_16x16x32_bf16 v[102:105], v[222:225], v[196:199], v[102:105]
	v_mfma_f32_16x16x32_bf16 v[98:101], v[230:233], v[196:199], v[98:101]
	v_mfma_f32_16x16x32_bf16 v[86:89], v[222:225], v[214:217], v[86:89]
	v_mfma_f32_16x16x32_bf16 v[82:85], v[230:233], v[214:217], v[82:85]
	s_mov_b32 m0, s39
	v_lshl_add_u64 v[170:171], v[234:235], 0, s[56:57]
	s_barrier
	ds_read_b128 v[176:179], v174 offset:49152
	ds_read_b128 v[180:183], v174 offset:50176
	ds_read_b128 v[184:187], v174 offset:51200
	ds_read_b128 v[188:191], v174 offset:52224
	ds_read_b128 v[192:195], v174 offset:53248
	ds_read_b128 v[196:199], v174 offset:54272
	ds_read_b128 v[210:213], v174 offset:55296
	ds_read_b128 v[214:217], v174 offset:56320
	global_load_lds_dwordx4 v[170:171], off
	v_lshl_add_u64 v[170:171], v[236:237], 0, s[56:57]
	s_mov_b32 m0, s40
	s_nop 0
	global_load_lds_dwordx4 v[170:171], off
	s_barrier
; __device__ __forceinline__ unsigned pk2(float lo, float hi) { f32x2 v = {lo, hi}; return __builtin_bit_cast(unsigned, __builtin_convertvector(v, bf16x2_t)); }
; __device__ __forceinline__ float bf_lo(unsigned w) { return __uint_as_float(w << 16); }
;     __device__ __forceinline__ void operator()(const f32x4 (&acc)[2][2][4][2], const Unit& u, int wr, int wc, int fr, int fq) const {
;         asm volatile("" : "+v"(fr), "+v"(fq));
;         const int row0 = u.pm * BM + wr * 64 + fr, col0 = u.pn * BM + wc * 32 + 8 * fq;
;         const float* gp = gate + (size_t)(u.pm >> 5) * 12288 + col0;
;         f32x4 gv[2][2];
; #pragma unroll
;         for (int bj = 0; bj < 2; ++bj)
; #pragma unroll
;             for (int n = 0; n < 2; ++n) gv[bj][n] = *(const f32x4*)(gp + bj * HALF + 4 * n);
; #pragma unroll
;         for (int ai = 0; ai < 2; ++ai)
; #pragma unroll
;             for (int m = 0; m < 4; ++m) {
;                 const size_t ro = (size_t)(row0 + ai * HALF + m * 16) * DM + col0;
; #pragma unroll
;                 for (int bj = 0; bj < 2; ++bj) {
;                     f32x4 r0, r1;
;                     if (RB) { const u32x4 rw = *(const u32x4*)((const bf16_t*)resid + ro + bj * HALF);
;                         r0 = (f32x4){bf_lo(rw.x), bf_hi(rw.x), bf_lo(rw.y), bf_hi(rw.y)}; r1 = (f32x4){bf_lo(rw.z), bf_hi(rw.z), bf_lo(rw.w), bf_hi(rw.w)}; }
;                     else { r0 = *(const f32x4*)((const float*)resid + ro + bj * HALF); r1 = *(const f32x4*)((const float*)resid + ro + bj * HALF + 4); }
;                     const f32x4 v0 = r0 + gv[bj][0] * acc[ai][bj][m][0], v1 = r1 + gv[bj][1] * acc[ai][bj][m][1];
;                     if (OB) { u32x4 w; w.x = pk2(v0[0], v0[1]); w.y = pk2(v0[2], v0[3]); w.z = pk2(v1[0], v1[1]); w.w = pk2(v1[2], v1[3]); *(u32x4*)((bf16_t*)out + ro + bj * HALF) = w; }
;                     else { *(f32x4*)((float*)out + ro + bj * HALF) = v0; *(f32x4*)((float*)out + ro + bj * HALF + 4) = v1; }
; template <class Epi>
; __device__ __forceinline__ void gemm_phase(LAS unsigned char* lds, const Gemm g, const StaticOrder& S, const Epi& E, const int tid) {
;     ...
;             PG8_BAR; PG8_WAIT_L(0); PG8_MMA(1, 0, At, B0); PG8_BAR; PG8_SCHED;
;             PG8_STAGE(PG8_SB(1, 1), b3 + hstep, voffB);
;             PG8_WAIT_V(6); PG8_BAR; PG8_MMA(1, 1, At, B1); PG8_BAR;
;         }
;         E(acc, cur, wr, wc, fr, fq);
	s_waitcnt lgkmcnt(0)
	v_mfma_f32_16x16x32_bf16 v[78:81], v[58:61], v[176:179], v[78:81]
	v_mfma_f32_16x16x32_bf16 v[74:77], v[66:69], v[176:179], v[74:77]
	v_mfma_f32_16x16x32_bf16 v[46:49], v[58:61], v[184:187], v[46:49]
	v_mfma_f32_16x16x32_bf16 v[42:45], v[66:69], v[184:187], v[42:45]
	v_mfma_f32_16x16x32_bf16 v[30:33], v[58:61], v[192:195], v[30:33]
	v_mfma_f32_16x16x32_bf16 v[26:29], v[66:69], v[192:195], v[26:29]
	v_mfma_f32_16x16x32_bf16 v[14:17], v[58:61], v[210:213], v[14:17]
	v_mfma_f32_16x16x32_bf16 v[10:13], v[66:69], v[210:213], v[10:13]
	v_mfma_f32_16x16x32_bf16 v[78:81], v[62:65], v[180:183], v[78:81]
	v_mfma_f32_16x16x32_bf16 v[74:77], v[70:73], v[180:183], v[74:77]
	v_mfma_f32_16x16x32_bf16 v[46:49], v[62:65], v[188:191], v[46:49]
	v_mfma_f32_16x16x32_bf16 v[42:45], v[70:73], v[188:191], v[42:45]
	v_mfma_f32_16x16x32_bf16 v[30:33], v[62:65], v[196:199], v[30:33]
	v_mfma_f32_16x16x32_bf16 v[26:29], v[70:73], v[196:199], v[26:29]
	v_mfma_f32_16x16x32_bf16 v[14:17], v[62:65], v[214:217], v[14:17]
	v_mfma_f32_16x16x32_bf16 v[10:13], v[70:73], v[214:217], v[10:13]
	s_barrier
	s_add_i32 s49, s49, 2
	s_add_u32 s47, s47, 0x100
	s_addc_u32 s48, s48, 0
	s_add_u32 s18, s18, 0x100
	s_addc_u32 s19, s19, 0
	s_add_u32 s20, s20, 0x200080
	s_addc_u32 s21, s21, 0
	s_add_i32 s22, s22, s31
	s_mov_b32 m0, s22
	s_nop 0
	global_load_lds_dwordx4 v0, s[20:21]
	s_add_i32 m0, s22, 0x2000
	s_nop 0
	global_load_lds_dwordx4 v164, s[20:21]
	s_waitcnt vmcnt(6)
	s_barrier
	v_mfma_f32_16x16x32_bf16 v[50:53], v[218:221], v[176:179], v[50:53]
	v_mfma_f32_16x16x32_bf16 v[62:65], v[222:225], v[180:183], v[50:53]
	v_mfma_f32_16x16x32_bf16 v[50:53], v[226:229], v[176:179], v[54:57]
	v_mfma_f32_16x16x32_bf16 v[38:41], v[218:221], v[184:187], v[38:41]
	v_mfma_f32_16x16x32_bf16 v[34:37], v[226:229], v[184:187], v[34:37]
	v_mfma_f32_16x16x32_bf16 v[22:25], v[218:221], v[192:195], v[22:25]
	v_mfma_f32_16x16x32_bf16 v[18:21], v[226:229], v[192:195], v[18:21]
	v_mfma_f32_16x16x32_bf16 v[6:9], v[218:221], v[210:213], v[6:9]
	v_mfma_f32_16x16x32_bf16 v[2:5], v[226:229], v[210:213], v[2:5]
	v_mfma_f32_16x16x32_bf16 v[58:61], v[230:233], v[180:183], v[50:53]
	v_mfma_f32_16x16x32_bf16 v[38:41], v[222:225], v[188:191], v[38:41]
	v_mfma_f32_16x16x32_bf16 v[34:37], v[230:233], v[188:191], v[34:37]
	v_mfma_f32_16x16x32_bf16 v[22:25], v[222:225], v[196:199], v[22:25]
	v_mfma_f32_16x16x32_bf16 v[18:21], v[230:233], v[196:199], v[18:21]
	v_mfma_f32_16x16x32_bf16 v[6:9], v[222:225], v[214:217], v[6:9]
	v_mfma_f32_16x16x32_bf16 v[2:5], v[230:233], v[214:217], v[2:5]
	s_cmpk_gt_u32 s49, 0x7d
	s_barrier
	s_cbranch_scc0 .LBB0_40
	s_setprio 0
	s_lshl_b32 s11, s2, 8
	s_lshl_b32 s13, s43, 8
	v_mov_b32_e32 v50, v172
	v_mov_b32_e32 v175, v159
	s_add_i32 s11, s11, s37
	s_or_b32 s13, s13, s38
	s_ashr_i32 s2, s2, 5
	s_mov_b32 s43, s10
	v_lshl_add_u32 v170, v50, 3, s13
	s_mul_hi_i32 s13, s2, 0xc000
	s_mul_i32 s2, s2, 0xc000
	v_add_u32_e32 v176, s11, v175
	s_add_u32 s18, s27, s2
	v_ashrrev_i32_e32 v177, 31, v176
	s_addc_u32 s19, s28, s13
	v_ashrrev_i32_e32 v171, 31, v170
	v_lshlrev_b64 v[176:177], 11, v[176:177]
	v_lshl_add_u64 v[54:55], v[170:171], 2, s[18:19]
	v_lshl_add_u64 v[170:171], v[176:177], 0, v[170:171]
	v_lshl_add_u64 v[180:181], v[170:171], 1, s[8:9]
	global_load_dwordx4 v[66:69], v[54:55], off offset:16
	global_load_dwordx4 v[70:73], v[54:55], off
	global_load_dwordx4 v[50:53], v[54:55], off offset:528
	s_nop 0
	global_load_dwordx4 v[54:57], v[54:55], off offset:512
	v_lshlrev_b32_e32 v175, 1, v170
	v_lshlrev_b32_e32 v200, 2, v170
	s_mov_b64 s[92:93], s[8:9]
	s_mov_b64 s[94:95], s[6:7]
	global_load_dwordx4 v[184:187], v175, s[92:93]
	global_load_dwordx4 v[188:191], v175, s[92:93] offset:256
	s_add_u32 s92, s92, 0x10000
	s_addc_u32 s93, s93, 0
	global_load_dwordx4 v[192:195], v175, s[92:93]
	global_load_dwordx4 v[196:199], v175, s[92:93] offset:256
	s_add_u32 s92, s92, 0x10000
	s_addc_u32 s93, s93, 0
	global_load_dwordx4 v[210:213], v175, s[92:93]
	global_load_dwordx4 v[214:217], v175, s[92:93] offset:256
	s_add_u32 s92, s92, 0x10000
	s_addc_u32 s93, s93, 0
	global_load_dwordx4 v[218:221], v175, s[92:93]
	global_load_dwordx4 v[222:225], v175, s[92:93] offset:256
	s_add_u32 s92, s92, 0x50000
	s_addc_u32 s93, s93, 0
	global_load_dwordx4 v[226:229], v175, s[92:93]
	global_load_dwordx4 v[230:233], v175, s[92:93] offset:256
	s_add_u32 s92, s92, 0x10000
	s_addc_u32 s93, s93, 0
	global_load_dwordx4 v[234:237], v175, s[92:93]
	s_waitcnt vmcnt(10)
	v_lshlrev_b32_e32 v176, 16, v184
	v_and_b32_e32 v177, 0xffff0000, v184
	v_lshlrev_b32_e32 v178, 16, v185
	v_and_b32_e32 v179, 0xffff0000, v185
	v_lshlrev_b32_e32 v180, 16, v186
	v_and_b32_e32 v181, 0xffff0000, v186
	v_lshlrev_b32_e32 v182, 16, v187
	v_and_b32_e32 v183, 0xffff0000, v187
	v_pk_fma_f32 v[142:143], v[142:143], v[70:71], v[176:177]
	v_pk_fma_f32 v[144:145], v[144:145], v[72:73], v[178:179]
	v_pk_fma_f32 v[138:139], v[138:139], v[66:67], v[180:181]
	v_pk_fma_f32 v[140:141], v[140:141], v[68:69], v[182:183]
	global_load_dwordx4 v[184:187], v175, s[92:93] offset:256
	global_store_dwordx4 v200, v[142:145], s[94:95]
	global_store_dwordx4 v200, v[138:141], s[94:95] offset:16
	s_waitcnt vmcnt(12)
	v_lshlrev_b32_e32 v176, 16, v188
	v_and_b32_e32 v177, 0xffff0000, v188
	v_lshlrev_b32_e32 v178, 16, v189
	v_and_b32_e32 v179, 0xffff0000, v189
	v_lshlrev_b32_e32 v180, 16, v190
	v_and_b32_e32 v181, 0xffff0000, v190
	v_lshlrev_b32_e32 v182, 16, v191
	v_and_b32_e32 v183, 0xffff0000, v191
	v_pk_fma_f32 v[134:135], v[134:135], v[54:55], v[176:177]
	v_pk_fma_f32 v[136:137], v[136:137], v[56:57], v[178:179]
	v_pk_fma_f32 v[130:131], v[130:131], v[50:51], v[180:181]
	v_pk_fma_f32 v[132:133], v[132:133], v[52:53], v[182:183]
	s_add_u32 s92, s92, 0x10000
	s_addc_u32 s93, s93, 0
	global_load_dwordx4 v[188:191], v175, s[92:93]
	global_store_dwordx4 v200, v[134:137], s[94:95] offset:512
	global_store_dwordx4 v200, v[130:133], s[94:95] offset:528
	s_waitcnt vmcnt(14)
; __device__ __forceinline__ unsigned pk2(float lo, float hi) { f32x2 v = {lo, hi}; return __builtin_bit_cast(unsigned, __builtin_convertvector(v, bf16x2_t)); }
; __device__ __forceinline__ float bf_lo(unsigned w) { return __uint_as_float(w << 16); }
; __device__ __forceinline__ float bf_hi(unsigned w) { return __uint_as_float(w & 0xffff0000u); }
;     __device__ __forceinline__ void operator()(const f32x4 (&acc)[2][2][4][2], const Unit& u, int wr, int wc, int fr, int fq) const {
;     ...
; #pragma unroll
;                 for (int bj = 0; bj < 2; ++bj) {
;                     f32x4 r0, r1;
;                     if (RB) { const u32x4 rw = *(const u32x4*)((const bf16_t*)resid + ro + bj * HALF);
;                         r0 = (f32x4){bf_lo(rw.x), bf_hi(rw.x), bf_lo(rw.y), bf_hi(rw.y)}; r1 = (f32x4){bf_lo(rw.z), bf_hi(rw.z), bf_lo(rw.w), bf_hi(rw.w)}; }
;                     else { r0 = *(const f32x4*)((const float*)resid + ro + bj * HALF); r1 = *(const f32x4*)((const float*)resid + ro + bj * HALF + 4); }
;                     const f32x4 v0 = r0 + gv[bj][0] * acc[ai][bj][m][0], v1 = r1 + gv[bj][1] * acc[ai][bj][m][1];
;                     if (OB) { u32x4 w; w.x = pk2(v0[0], v0[1]); w.y = pk2(v0[2], v0[3]); w.z = pk2(v1[0], v1[1]); w.w = pk2(v1[2], v1[3]); *(u32x4*)((bf16_t*)out + ro + bj * HALF) = w; }
;                     else { *(f32x4*)((float*)out + ro + bj * HALF) = v0; *(f32x4*)((float*)out + ro + bj * HALF + 4) = v1; }
;                 }
	v_lshlrev_b32_e32 v176, 16, v192
	v_and_b32_e32 v177, 0xffff0000, v192
	v_lshlrev_b32_e32 v178, 16, v193
	v_and_b32_e32 v179, 0xffff0000, v193
	v_lshlrev_b32_e32 v180, 16, v194
	v_and_b32_e32 v181, 0xffff0000, v194
	v_lshlrev_b32_e32 v182, 16, v195
	v_and_b32_e32 v183, 0xffff0000, v195
	v_pk_fma_f32 v[126:127], v[126:127], v[70:71], v[176:177]
	v_pk_fma_f32 v[128:129], v[128:129], v[72:73], v[178:179]
	v_pk_fma_f32 v[122:123], v[122:123], v[66:67], v[180:181]
	v_pk_fma_f32 v[124:125], v[124:125], v[68:69], v[182:183]
	global_load_dwordx4 v[192:195], v175, s[92:93] offset:256
	s_add_u32 s94, s94, 0x20000
	s_addc_u32 s95, s95, 0
	global_store_dwordx4 v200, v[126:129], s[94:95]
	global_store_dwordx4 v200, v[122:125], s[94:95] offset:16
	s_waitcnt vmcnt(16)
	v_lshlrev_b32_e32 v176, 16, v196
	v_and_b32_e32 v177, 0xffff0000, v196
	v_lshlrev_b32_e32 v178, 16, v197
	v_and_b32_e32 v179, 0xffff0000, v197
	v_lshlrev_b32_e32 v180, 16, v198
	v_and_b32_e32 v181, 0xffff0000, v198
	v_lshlrev_b32_e32 v182, 16, v199
	v_and_b32_e32 v183, 0xffff0000, v199
	v_pk_fma_f32 v[118:119], v[118:119], v[54:55], v[176:177]
	v_pk_fma_f32 v[120:121], v[120:121], v[56:57], v[178:179]
	v_pk_fma_f32 v[114:115], v[114:115], v[50:51], v[180:181]
	v_pk_fma_f32 v[116:117], v[116:117], v[52:53], v[182:183]
	s_add_u32 s92, s92, 0x10000
	s_addc_u32 s93, s93, 0
	global_load_dwordx4 v[196:199], v175, s[92:93]
	global_store_dwordx4 v200, v[118:121], s[94:95] offset:512
	global_store_dwordx4 v200, v[114:117], s[94:95] offset:528
	s_waitcnt vmcnt(18)
	v_lshlrev_b32_e32 v176, 16, v210
	v_and_b32_e32 v177, 0xffff0000, v210
	v_lshlrev_b32_e32 v178, 16, v211
	v_and_b32_e32 v179, 0xffff0000, v211
	v_lshlrev_b32_e32 v180, 16, v212
	v_and_b32_e32 v181, 0xffff0000, v212
	v_lshlrev_b32_e32 v182, 16, v213
	v_and_b32_e32 v183, 0xffff0000, v213
	v_pk_fma_f32 v[110:111], v[110:111], v[70:71], v[176:177]
	v_pk_fma_f32 v[112:113], v[112:113], v[72:73], v[178:179]
	v_pk_fma_f32 v[106:107], v[106:107], v[66:67], v[180:181]
	v_pk_fma_f32 v[108:109], v[108:109], v[68:69], v[182:183]
	global_load_dwordx4 v[210:213], v175, s[92:93] offset:256
	s_add_u32 s94, s94, 0x20000
	s_addc_u32 s95, s95, 0
	global_store_dwordx4 v200, v[110:113], s[94:95]
	global_store_dwordx4 v200, v[106:109], s[94:95] offset:16
	s_waitcnt vmcnt(20)
	v_lshlrev_b32_e32 v176, 16, v214
	v_and_b32_e32 v177, 0xffff0000, v214
	v_lshlrev_b32_e32 v178, 16, v215
	v_and_b32_e32 v179, 0xffff0000, v215
	v_lshlrev_b32_e32 v180, 16, v216
	v_and_b32_e32 v181, 0xffff0000, v216
	v_lshlrev_b32_e32 v182, 16, v217
	v_and_b32_e32 v183, 0xffff0000, v217
	v_pk_fma_f32 v[102:103], v[102:103], v[54:55], v[176:177]
	v_pk_fma_f32 v[104:105], v[104:105], v[56:57], v[178:179]
	v_pk_fma_f32 v[98:99], v[98:99], v[50:51], v[180:181]
	v_pk_fma_f32 v[100:101], v[100:101], v[52:53], v[182:183]
	global_store_dwordx4 v200, v[102:105], s[94:95] offset:512
	global_store_dwordx4 v200, v[98:101], s[94:95] offset:528
	s_waitcnt vmcnt(21)
	v_lshlrev_b32_e32 v176, 16, v218
	v_and_b32_e32 v177, 0xffff0000, v218
	v_lshlrev_b32_e32 v178, 16, v219
	v_and_b32_e32 v179, 0xffff0000, v219
	v_lshlrev_b32_e32 v180, 16, v220
	v_and_b32_e32 v181, 0xffff0000, v220
	v_lshlrev_b32_e32 v182, 16, v221
	v_and_b32_e32 v183, 0xffff0000, v221
	v_pk_fma_f32 v[94:95], v[94:95], v[70:71], v[176:177]
	v_pk_fma_f32 v[96:97], v[96:97], v[72:73], v[178:179]
	v_pk_fma_f32 v[90:91], v[90:91], v[66:67], v[180:181]
	v_pk_fma_f32 v[92:93], v[92:93], v[68:69], v[182:183]
	s_add_u32 s94, s94, 0x20000
	s_addc_u32 s95, s95, 0
	global_store_dwordx4 v200, v[94:97], s[94:95]
	global_store_dwordx4 v200, v[90:93], s[94:95] offset:16
	s_waitcnt vmcnt(22)
	v_lshlrev_b32_e32 v176, 16, v222
	v_and_b32_e32 v177, 0xffff0000, v222
	v_lshlrev_b32_e32 v178, 16, v223
	v_and_b32_e32 v179, 0xffff0000, v223
	v_lshlrev_b32_e32 v180, 16, v224
	v_and_b32_e32 v181, 0xffff0000, v224
	v_lshlrev_b32_e32 v182, 16, v225
	v_and_b32_e32 v183, 0xffff0000, v225
	v_pk_fma_f32 v[86:87], v[86:87], v[54:55], v[176:177]
	v_pk_fma_f32 v[88:89], v[88:89], v[56:57], v[178:179]
	v_pk_fma_f32 v[82:83], v[82:83], v[50:51], v[180:181]
	v_pk_fma_f32 v[84:85], v[84:85], v[52:53], v[182:183]
	global_store_dwordx4 v200, v[86:89], s[94:95] offset:512
	global_store_dwordx4 v200, v[82:85], s[94:95] offset:528
	s_waitcnt vmcnt(23)
	v_lshlrev_b32_e32 v176, 16, v226
	v_and_b32_e32 v177, 0xffff0000, v226
	v_lshlrev_b32_e32 v178, 16, v227
	v_and_b32_e32 v179, 0xffff0000, v227
	v_lshlrev_b32_e32 v180, 16, v228
	v_and_b32_e32 v181, 0xffff0000, v228
	v_lshlrev_b32_e32 v182, 16, v229
	v_and_b32_e32 v183, 0xffff0000, v229
	v_pk_fma_f32 v[78:79], v[78:79], v[70:71], v[176:177]
	v_pk_fma_f32 v[80:81], v[80:81], v[72:73], v[178:179]
	v_pk_fma_f32 v[74:75], v[74:75], v[66:67], v[180:181]
	v_pk_fma_f32 v[76:77], v[76:77], v[68:69], v[182:183]
	s_add_u32 s94, s94, 0xa0000
	s_addc_u32 s95, s95, 0
	global_store_dwordx4 v200, v[78:81], s[94:95]
	global_store_dwordx4 v200, v[74:77], s[94:95] offset:16
	s_waitcnt vmcnt(24)
; __device__ __forceinline__ unsigned pk2(float lo, float hi) { f32x2 v = {lo, hi}; return __builtin_bit_cast(unsigned, __builtin_convertvector(v, bf16x2_t)); }
; __device__ __forceinline__ float bf_lo(unsigned w) { return __uint_as_float(w << 16); }
; __device__ __forceinline__ float bf_hi(unsigned w) { return __uint_as_float(w & 0xffff0000u); }
; #define PG8_WAIT_V(n) asm volatile("s_waitcnt vmcnt(" #n ")" ::: "memory")
; #define PG8_BAR __builtin_amdgcn_s_barrier()
;     __device__ __forceinline__ void operator()(const f32x4 (&acc)[2][2][4][2], const Unit& u, int wr, int wc, int fr, int fq) const {
;     ...
; #pragma unroll
;                 for (int bj = 0; bj < 2; ++bj) {
;                     f32x4 r0, r1;
;                     if (RB) { const u32x4 rw = *(const u32x4*)((const bf16_t*)resid + ro + bj * HALF);
;                         r0 = (f32x4){bf_lo(rw.x), bf_hi(rw.x), bf_lo(rw.y), bf_hi(rw.y)}; r1 = (f32x4){bf_lo(rw.z), bf_hi(rw.z), bf_lo(rw.w), bf_hi(rw.w)}; }
;                     else { r0 = *(const f32x4*)((const float*)resid + ro + bj * HALF); r1 = *(const f32x4*)((const float*)resid + ro + bj * HALF + 4); }
;                     const f32x4 v0 = r0 + gv[bj][0] * acc[ai][bj][m][0], v1 = r1 + gv[bj][1] * acc[ai][bj][m][1];
;                     if (OB) { u32x4 w; w.x = pk2(v0[0], v0[1]); w.y = pk2(v0[2], v0[3]); w.z = pk2(v1[0], v1[1]); w.w = pk2(v1[2], v1[3]); *(u32x4*)((bf16_t*)out + ro + bj * HALF) = w; }
;                     else { *(f32x4*)((float*)out + ro + bj * HALF) = v0; *(f32x4*)((float*)out + ro + bj * HALF + 4) = v1; }
;                 }
; template <class Epi>
; __device__ __forceinline__ void gemm_phase(LAS unsigned char* lds, const Gemm g, const StaticOrder& S, const Epi& E, const int tid) {
;     ...
;         E(acc, cur, wr, wc, fr, fq);
;         if (!has_next) break;
; #pragma unroll
;         for (int a = 0; a < 2; ++a)
; #pragma unroll
;             for (int b = 0; b < 2; ++b)
; #pragma unroll
;                 for (int m = 0; m < 4; ++m)
; #pragma unroll
;                     for (int n = 0; n < 2; ++n) acc[a][b][m][n] = (f32x4){0.f, 0.f, 0.f, 0.f};
;         cur = nxt; cA = nA; cB = nB; ++ui;
;     }
;     PG8_WAIT_V(0);
;     if (wr == 0) PG8_BAR;
;     PG8_BAR;
	v_lshlrev_b32_e32 v176, 16, v230
	v_and_b32_e32 v177, 0xffff0000, v230
	v_lshlrev_b32_e32 v178, 16, v231
	v_and_b32_e32 v179, 0xffff0000, v231
	v_lshlrev_b32_e32 v180, 16, v232
	v_and_b32_e32 v181, 0xffff0000, v232
	v_lshlrev_b32_e32 v182, 16, v233
	v_and_b32_e32 v183, 0xffff0000, v233
	v_pk_fma_f32 v[62:63], v[62:63], v[54:55], v[176:177]
	v_pk_fma_f32 v[64:65], v[64:65], v[56:57], v[178:179]
	v_pk_fma_f32 v[58:59], v[58:59], v[50:51], v[180:181]
	v_pk_fma_f32 v[60:61], v[60:61], v[52:53], v[182:183]
	global_store_dwordx4 v200, v[62:65], s[94:95] offset:512
	global_store_dwordx4 v200, v[58:61], s[94:95] offset:528
	s_waitcnt vmcnt(25)
	v_lshlrev_b32_e32 v176, 16, v234
	v_and_b32_e32 v177, 0xffff0000, v234
	v_lshlrev_b32_e32 v178, 16, v235
	v_and_b32_e32 v179, 0xffff0000, v235
	v_lshlrev_b32_e32 v180, 16, v236
	v_and_b32_e32 v181, 0xffff0000, v236
	v_lshlrev_b32_e32 v182, 16, v237
	v_and_b32_e32 v183, 0xffff0000, v237
	v_pk_fma_f32 v[46:47], v[46:47], v[70:71], v[176:177]
	v_pk_fma_f32 v[48:49], v[48:49], v[72:73], v[178:179]
	v_pk_fma_f32 v[42:43], v[42:43], v[66:67], v[180:181]
	v_pk_fma_f32 v[44:45], v[44:45], v[68:69], v[182:183]
	s_add_u32 s94, s94, 0x20000
	s_addc_u32 s95, s95, 0
	global_store_dwordx4 v200, v[46:49], s[94:95]
	global_store_dwordx4 v200, v[42:45], s[94:95] offset:16
	s_waitcnt vmcnt(26)
	v_lshlrev_b32_e32 v176, 16, v184
	v_and_b32_e32 v177, 0xffff0000, v184
	v_lshlrev_b32_e32 v178, 16, v185
	v_and_b32_e32 v179, 0xffff0000, v185
	v_lshlrev_b32_e32 v180, 16, v186
	v_and_b32_e32 v181, 0xffff0000, v186
	v_lshlrev_b32_e32 v182, 16, v187
	v_and_b32_e32 v183, 0xffff0000, v187
	v_pk_fma_f32 v[38:39], v[38:39], v[54:55], v[176:177]
	v_pk_fma_f32 v[40:41], v[40:41], v[56:57], v[178:179]
	v_pk_fma_f32 v[34:35], v[34:35], v[50:51], v[180:181]
	v_pk_fma_f32 v[36:37], v[36:37], v[52:53], v[182:183]
	global_store_dwordx4 v200, v[38:41], s[94:95] offset:512
	global_store_dwordx4 v200, v[34:37], s[94:95] offset:528
	s_waitcnt vmcnt(25)
	v_lshlrev_b32_e32 v176, 16, v188
	v_and_b32_e32 v177, 0xffff0000, v188
	v_lshlrev_b32_e32 v178, 16, v189
	v_and_b32_e32 v179, 0xffff0000, v189
	v_lshlrev_b32_e32 v180, 16, v190
	v_and_b32_e32 v181, 0xffff0000, v190
	v_lshlrev_b32_e32 v182, 16, v191
	v_and_b32_e32 v183, 0xffff0000, v191
	v_pk_fma_f32 v[30:31], v[30:31], v[70:71], v[176:177]
	v_pk_fma_f32 v[32:33], v[32:33], v[72:73], v[178:179]
	v_pk_fma_f32 v[26:27], v[26:27], v[66:67], v[180:181]
	v_pk_fma_f32 v[28:29], v[28:29], v[68:69], v[182:183]
	s_add_u32 s94, s94, 0x20000
	s_addc_u32 s95, s95, 0
	global_store_dwordx4 v200, v[30:33], s[94:95]
	global_store_dwordx4 v200, v[26:29], s[94:95] offset:16
	s_waitcnt vmcnt(24)
	v_lshlrev_b32_e32 v176, 16, v192
	v_and_b32_e32 v177, 0xffff0000, v192
	v_lshlrev_b32_e32 v178, 16, v193
	v_and_b32_e32 v179, 0xffff0000, v193
	v_lshlrev_b32_e32 v180, 16, v194
	v_and_b32_e32 v181, 0xffff0000, v194
	v_lshlrev_b32_e32 v182, 16, v195
	v_and_b32_e32 v183, 0xffff0000, v195
	v_pk_fma_f32 v[22:23], v[22:23], v[54:55], v[176:177]
	v_pk_fma_f32 v[24:25], v[24:25], v[56:57], v[178:179]
	v_pk_fma_f32 v[18:19], v[18:19], v[50:51], v[180:181]
	v_pk_fma_f32 v[20:21], v[20:21], v[52:53], v[182:183]
	global_store_dwordx4 v200, v[22:25], s[94:95] offset:512
	global_store_dwordx4 v200, v[18:21], s[94:95] offset:528
	s_waitcnt vmcnt(23)
	v_lshlrev_b32_e32 v176, 16, v196
	v_and_b32_e32 v177, 0xffff0000, v196
	v_lshlrev_b32_e32 v178, 16, v197
	v_and_b32_e32 v179, 0xffff0000, v197
	v_lshlrev_b32_e32 v180, 16, v198
	v_and_b32_e32 v181, 0xffff0000, v198
	v_lshlrev_b32_e32 v182, 16, v199
	v_and_b32_e32 v183, 0xffff0000, v199
	v_pk_fma_f32 v[14:15], v[14:15], v[70:71], v[176:177]
	v_pk_fma_f32 v[16:17], v[16:17], v[72:73], v[178:179]
	v_pk_fma_f32 v[10:11], v[10:11], v[66:67], v[180:181]
	v_pk_fma_f32 v[12:13], v[12:13], v[68:69], v[182:183]
	s_add_u32 s94, s94, 0x20000
	s_addc_u32 s95, s95, 0
	global_store_dwordx4 v200, v[14:17], s[94:95]
	global_store_dwordx4 v200, v[10:13], s[94:95] offset:16
	s_waitcnt vmcnt(22)
	v_lshlrev_b32_e32 v176, 16, v210
	v_and_b32_e32 v177, 0xffff0000, v210
	v_lshlrev_b32_e32 v178, 16, v211
	v_and_b32_e32 v179, 0xffff0000, v211
	v_lshlrev_b32_e32 v180, 16, v212
	v_and_b32_e32 v181, 0xffff0000, v212
	v_lshlrev_b32_e32 v182, 16, v213
	v_and_b32_e32 v183, 0xffff0000, v213
	v_pk_fma_f32 v[6:7], v[6:7], v[54:55], v[176:177]
	v_pk_fma_f32 v[8:9], v[8:9], v[56:57], v[178:179]
	v_pk_fma_f32 v[2:3], v[2:3], v[50:51], v[180:181]
	v_pk_fma_f32 v[4:5], v[4:5], v[52:53], v[182:183]
	global_store_dwordx4 v200, v[6:9], s[94:95] offset:512
	global_store_dwordx4 v200, v[2:5], s[94:95] offset:528
	s_mov_b32 s2, s12
	s_mov_b64 s[20:21], s[14:15]
	s_mov_b64 s[18:19], s[16:17]
	s_and_b64 vcc, exec, s[4:5]
	s_nop 1
	s_cbranch_vccz .LBB0_33
	s_waitcnt vmcnt(0)
	s_cmpk_gt_u32 s29, 0xff
	s_cbranch_scc1 .LBB0_44
	s_barrier

; #define PG8_STAGE(bufoff, gbase, voff) do { _Pragma("unroll") for (int _i = 0; _i < 2; ++_i) \
;         __builtin_amdgcn_global_load_lds((const unsigned*)((const char*)(gbase) + (voff)[_i]), (LAS unsigned*)(lds + (bufoff) + ldsw + _i * 8192), 16, 0, 0); } while (0)
; #define PG8_LDA(dst, b, h) do { _Pragma("unroll") for (int m = 0; m < 4; ++m) _Pragma("unroll") for (int k = 0; k < 2; ++k) dst[m][k] = *(const LAS bf16x8*)(lds + PG8_SA(b, h) + aoff + m * 2048 + k * 1024); } while (0)
; #define PG8_LDB(dst, b, h) do { _Pragma("unroll") for (int n = 0; n < 2; ++n) _Pragma("unroll") for (int k = 0; k < 2; ++k) dst[n][k] = *(const LAS bf16x8*)(lds + PG8_SB(b, h) + boff + n * 2048 + k * 1024); } while (0)
; #define PG8_MMA(ai, bj, At, Bt) do { __builtin_amdgcn_s_setprio(1); _Pragma("unroll") for (int m = 0; m < 4; ++m) _Pragma("unroll") for (int n = 0; n < 2; ++n) _Pragma("unroll") for (int k = 0; k < 2; ++k) \
;         acc[ai][bj][m][n] = __builtin_amdgcn_mfma_f32_16x16x32_bf16(Bt[n][k], At[m][k], acc[ai][bj][m][n], 0, 0, 0); __builtin_amdgcn_s_setprio(0); } while (0)
; #define PG8_WAIT_V(n) asm volatile("s_waitcnt vmcnt(" #n ")" ::: "memory")
; #define PG8_WAIT_L(n) asm volatile("s_waitcnt lgkmcnt(" #n ")" ::: "memory")
; #define PG8_BAR __builtin_amdgcn_s_barrier()
; template <class Epi>
; __device__ __forceinline__ void gemm_phase(LAS unsigned char* lds, const Gemm g, const StaticOrder& S, const Epi& E, const int tid) {
;     ...
;             const bool last = (t == nt - 2);
;             const char* a1 = cA + (size_t)(t + 1) * kstep;
;             const char* a2 = last ? nA : cA + (size_t)(t + 2) * kstep; const char* b2 = last ? nB : cB + (size_t)(t + 2) * kstep;
;             const char* a3 = a2 + kstep; const char* b3 = b2 + kstep;
;             PG8_LDB(B0, 0, 0); PG8_SCHED; PG8_LDA(At, 0, 0); PG8_STAGE(PG8_SA(1, 1), a1 + hstep, voffA);
;             PG8_WAIT_L(8); PG8_BAR; PG8_WAIT_L(0); PG8_MMA(0, 0, At, B0); PG8_BAR; PG8_SCHED;
;             PG8_LDB(B1, 0, 1); PG8_STAGE(PG8_SB(0, 0), b2, voffB);
;             PG8_BAR; PG8_WAIT_L(0); PG8_MMA(0, 1, At, B1); PG8_BAR;
;             PG8_LDA(At, 0, 1); PG8_STAGE(PG8_SA(0, 0), a2, voffA);
;             PG8_BAR; PG8_WAIT_L(0); PG8_MMA(1, 0, At, B0); PG8_BAR; PG8_SCHED;
;             PG8_STAGE(PG8_SB(0, 1), b2 + hstep, voffB);
;             PG8_WAIT_V(6); PG8_BAR; PG8_MMA(1, 1, At, B1); PG8_BAR;
.Lgprio1:
.LBB0_62:
	s_add_u32 s20, s18, 0xffe00080
	s_addc_u32 s21, s19, -1
	s_add_i32 s50, 0, 0x10000
	v_add_u32_e32 v62, s50, v173
	ds_read_b128 v[42:45], v62
	ds_read_b128 v[46:49], v62 offset:1024
	ds_read_b128 v[58:61], v62 offset:2048
	ds_read_b128 v[62:65], v62 offset:3072
	s_cmpk_eq_i32 s49, 0x7c
	s_cselect_b32 s23, s13, s21
	s_cselect_b32 s22, s44, s20
	s_cselect_b32 s21, s11, s48
	s_cselect_b32 s20, s45, s47
	s_add_i32 m0, s3, 0xc000
	ds_read_b128 v[176:179], v174
	ds_read_b128 v[180:183], v174 offset:1024
	ds_read_b128 v[184:187], v174 offset:2048
	ds_read_b128 v[188:191], v174 offset:3072
	ds_read_b128 v[192:195], v174 offset:4096
	ds_read_b128 v[196:199], v174 offset:5120
	ds_read_b128 v[210:213], v174 offset:6144
	ds_read_b128 v[214:217], v174 offset:7168
	global_load_lds_dwordx4 v168, s[18:19]
	v_lshl_add_u64 v[170:171], s[18:19], 0, v[166:167]
	s_add_i32 m0, s3, 0xe000
	s_nop 0
	global_load_lds_dwordx4 v[170:171], off
	s_waitcnt lgkmcnt(8)
	s_barrier
	s_waitcnt lgkmcnt(0)
	v_mfma_f32_16x16x32_bf16 v[142:145], v[42:45], v[176:179], v[142:145]
	v_mfma_f32_16x16x32_bf16 v[138:141], v[58:61], v[176:179], v[138:141]
	v_mfma_f32_16x16x32_bf16 v[126:129], v[42:45], v[184:187], v[126:129]
	v_mfma_f32_16x16x32_bf16 v[122:125], v[58:61], v[184:187], v[122:125]
	v_mfma_f32_16x16x32_bf16 v[110:113], v[42:45], v[192:195], v[110:113]
	v_mfma_f32_16x16x32_bf16 v[106:109], v[58:61], v[192:195], v[106:109]
	v_mfma_f32_16x16x32_bf16 v[94:97], v[42:45], v[210:213], v[94:97]
	v_mfma_f32_16x16x32_bf16 v[90:93], v[58:61], v[210:213], v[90:93]
	v_mfma_f32_16x16x32_bf16 v[142:145], v[46:49], v[180:183], v[142:145]
	v_mfma_f32_16x16x32_bf16 v[138:141], v[62:65], v[180:183], v[138:141]
	v_mfma_f32_16x16x32_bf16 v[126:129], v[46:49], v[188:191], v[126:129]
	v_mfma_f32_16x16x32_bf16 v[122:125], v[62:65], v[188:191], v[122:125]
	v_mfma_f32_16x16x32_bf16 v[110:113], v[46:49], v[196:199], v[110:113]
	v_mfma_f32_16x16x32_bf16 v[106:109], v[62:65], v[196:199], v[106:109]
	v_mfma_f32_16x16x32_bf16 v[94:97], v[46:49], v[214:217], v[94:97]
	v_mfma_f32_16x16x32_bf16 v[90:93], v[62:65], v[214:217], v[90:93]
	s_barrier
	s_add_i32 s54, 0, 0x14000
	v_add_u32_e32 v170, s54, v173
	s_add_i32 s50, s50, s31
	ds_read_b128 v[218:221], v170
	ds_read_b128 v[222:225], v170 offset:1024
	ds_read_b128 v[226:229], v170 offset:2048
	ds_read_b128 v[230:233], v170 offset:3072
	v_lshl_add_u64 v[170:171], s[20:21], 0, v[0:1]
	s_mov_b32 m0, s50
	v_lshl_add_u64 v[200:201], s[20:21], 0, v[164:165]
	global_load_lds_dwordx4 v[170:171], off
	s_add_i32 m0, s50, 0x2000
	s_nop 0
	global_load_lds_dwordx4 v[200:201], off
	s_barrier
	s_waitcnt lgkmcnt(0)
	v_mfma_f32_16x16x32_bf16 v[134:137], v[218:221], v[176:179], v[134:137]
	v_mfma_f32_16x16x32_bf16 v[130:133], v[226:229], v[176:179], v[130:133]
	v_mfma_f32_16x16x32_bf16 v[118:121], v[218:221], v[184:187], v[118:121]
	v_mfma_f32_16x16x32_bf16 v[114:117], v[226:229], v[184:187], v[114:117]
	v_mfma_f32_16x16x32_bf16 v[102:105], v[218:221], v[192:195], v[102:105]
	v_mfma_f32_16x16x32_bf16 v[98:101], v[226:229], v[192:195], v[98:101]
	v_mfma_f32_16x16x32_bf16 v[86:89], v[218:221], v[210:213], v[86:89]
	v_mfma_f32_16x16x32_bf16 v[82:85], v[226:229], v[210:213], v[82:85]
	v_mfma_f32_16x16x32_bf16 v[134:137], v[222:225], v[180:183], v[134:137]
	v_mfma_f32_16x16x32_bf16 v[130:133], v[230:233], v[180:183], v[130:133]
	v_mfma_f32_16x16x32_bf16 v[118:121], v[222:225], v[188:191], v[118:121]
	v_mfma_f32_16x16x32_bf16 v[114:117], v[230:233], v[188:191], v[114:117]
	v_mfma_f32_16x16x32_bf16 v[102:105], v[222:225], v[196:199], v[102:105]
	v_mfma_f32_16x16x32_bf16 v[98:101], v[230:233], v[196:199], v[98:101]
	v_mfma_f32_16x16x32_bf16 v[86:89], v[222:225], v[214:217], v[86:89]
	v_mfma_f32_16x16x32_bf16 v[82:85], v[230:233], v[214:217], v[82:85]
	s_mov_b32 m0, s3
	v_lshl_add_u64 v[234:235], s[22:23], 0, v[160:161]
	s_barrier
	ds_read_b128 v[176:179], v174 offset:16384
	ds_read_b128 v[180:183], v174 offset:17408
	ds_read_b128 v[184:187], v174 offset:18432
	ds_read_b128 v[188:191], v174 offset:19456
	ds_read_b128 v[192:195], v174 offset:20480
	ds_read_b128 v[196:199], v174 offset:21504
	ds_read_b128 v[210:213], v174 offset:22528
	ds_read_b128 v[214:217], v174 offset:23552
	global_load_lds_dwordx4 v[234:235], off
	v_lshl_add_u64 v[236:237], s[22:23], 0, v[162:163]
	s_mov_b32 m0, s34
	s_nop 0
	global_load_lds_dwordx4 v[236:237], off
	s_barrier
	s_waitcnt lgkmcnt(0)
	v_mfma_f32_16x16x32_bf16 v[78:81], v[42:45], v[176:179], v[78:81]
	v_mfma_f32_16x16x32_bf16 v[74:77], v[58:61], v[176:179], v[74:77]
	v_mfma_f32_16x16x32_bf16 v[54:57], v[42:45], v[184:187], v[54:57]
	v_mfma_f32_16x16x32_bf16 v[50:53], v[58:61], v[184:187], v[50:53]
	v_mfma_f32_16x16x32_bf16 v[30:33], v[42:45], v[192:195], v[30:33]
	v_mfma_f32_16x16x32_bf16 v[26:29], v[58:61], v[192:195], v[26:29]
	v_mfma_f32_16x16x32_bf16 v[14:17], v[42:45], v[210:213], v[14:17]
	v_mfma_f32_16x16x32_bf16 v[10:13], v[58:61], v[210:213], v[10:13]
	v_mfma_f32_16x16x32_bf16 v[78:81], v[46:49], v[180:183], v[78:81]
	v_mfma_f32_16x16x32_bf16 v[74:77], v[62:65], v[180:183], v[74:77]
	v_mfma_f32_16x16x32_bf16 v[54:57], v[46:49], v[188:191], v[54:57]
	v_mfma_f32_16x16x32_bf16 v[50:53], v[62:65], v[188:191], v[50:53]
	v_mfma_f32_16x16x32_bf16 v[30:33], v[46:49], v[196:199], v[30:33]
	v_mfma_f32_16x16x32_bf16 v[26:29], v[62:65], v[196:199], v[26:29]
	v_mfma_f32_16x16x32_bf16 v[14:17], v[46:49], v[214:217], v[14:17]
	v_mfma_f32_16x16x32_bf16 v[10:13], v[62:65], v[214:217], v[10:13]
	s_barrier
	s_add_u32 s52, s20, 0x200000
	s_addc_u32 s53, s21, 0
	s_add_i32 s50, s54, s31
	s_mov_b32 m0, s50
	s_nop 0
	global_load_lds_dwordx4 v0, s[52:53]
	s_add_i32 m0, s50, 0x2000
	s_nop 0
	global_load_lds_dwordx4 v164, s[52:53]
	s_waitcnt vmcnt(6)
	s_barrier
; #define PG8_STAGE(bufoff, gbase, voff) do { _Pragma("unroll") for (int _i = 0; _i < 2; ++_i) \
;         __builtin_amdgcn_global_load_lds((const unsigned*)((const char*)(gbase) + (voff)[_i]), (LAS unsigned*)(lds + (bufoff) + ldsw + _i * 8192), 16, 0, 0); } while (0)
; #define PG8_LDA(dst, b, h) do { _Pragma("unroll") for (int m = 0; m < 4; ++m) _Pragma("unroll") for (int k = 0; k < 2; ++k) dst[m][k] = *(const LAS bf16x8*)(lds + PG8_SA(b, h) + aoff + m * 2048 + k * 1024); } while (0)
; #define PG8_LDB(dst, b, h) do { _Pragma("unroll") for (int n = 0; n < 2; ++n) _Pragma("unroll") for (int k = 0; k < 2; ++k) dst[n][k] = *(const LAS bf16x8*)(lds + PG8_SB(b, h) + boff + n * 2048 + k * 1024); } while (0)
; #define PG8_MMA(ai, bj, At, Bt) do { __builtin_amdgcn_s_setprio(1); _Pragma("unroll") for (int m = 0; m < 4; ++m) _Pragma("unroll") for (int n = 0; n < 2; ++n) _Pragma("unroll") for (int k = 0; k < 2; ++k) \
;         acc[ai][bj][m][n] = __builtin_amdgcn_mfma_f32_16x16x32_bf16(Bt[n][k], At[m][k], acc[ai][bj][m][n], 0, 0, 0); __builtin_amdgcn_s_setprio(0); } while (0)
; #define PG8_WAIT_V(n) asm volatile("s_waitcnt vmcnt(" #n ")" ::: "memory")
; #define PG8_WAIT_L(n) asm volatile("s_waitcnt lgkmcnt(" #n ")" ::: "memory")
; #define PG8_BAR __builtin_amdgcn_s_barrier()
; #define PG8_SCHED __builtin_amdgcn_sched_barrier(0)
; template <class Epi>
; __device__ __forceinline__ void gemm_phase(LAS unsigned char* lds, const Gemm g, const StaticOrder& S, const Epi& E, const int tid) {
;     ...
;             PG8_WAIT_V(6); PG8_BAR; PG8_MMA(1, 1, At, B1); PG8_BAR;
;             PG8_LDB(B0, 1, 0); PG8_SCHED; PG8_LDA(At, 1, 0); PG8_STAGE(PG8_SA(0, 1), a2 + hstep, voffA);
;             PG8_WAIT_L(8); PG8_BAR; PG8_WAIT_L(0); PG8_MMA(0, 0, At, B0); PG8_BAR; PG8_SCHED;
;             PG8_LDB(B1, 1, 1); PG8_STAGE(PG8_SB(1, 0), b3, voffB);
;             PG8_BAR; PG8_WAIT_L(0); PG8_MMA(0, 1, At, B1); PG8_BAR;
;             PG8_LDA(At, 1, 1); PG8_STAGE(PG8_SA(1, 0), a3, voffA);
	v_mfma_f32_16x16x32_bf16 v[38:41], v[218:221], v[184:187], v[38:41]
	v_mfma_f32_16x16x32_bf16 v[34:37], v[226:229], v[184:187], v[34:37]
	v_mfma_f32_16x16x32_bf16 v[22:25], v[218:221], v[192:195], v[22:25]
	v_mfma_f32_16x16x32_bf16 v[18:21], v[226:229], v[192:195], v[18:21]
	v_mfma_f32_16x16x32_bf16 v[6:9], v[218:221], v[210:213], v[6:9]
	v_mfma_f32_16x16x32_bf16 v[2:5], v[226:229], v[210:213], v[2:5]
	v_mfma_f32_16x16x32_bf16 v[42:45], v[218:221], v[176:179], v[70:73]
	v_mfma_f32_16x16x32_bf16 v[46:49], v[226:229], v[176:179], v[66:69]
	v_mfma_f32_16x16x32_bf16 v[38:41], v[222:225], v[188:191], v[38:41]
	v_mfma_f32_16x16x32_bf16 v[34:37], v[230:233], v[188:191], v[34:37]
	v_mfma_f32_16x16x32_bf16 v[22:25], v[222:225], v[196:199], v[22:25]
	v_mfma_f32_16x16x32_bf16 v[18:21], v[230:233], v[196:199], v[18:21]
	v_mfma_f32_16x16x32_bf16 v[6:9], v[222:225], v[214:217], v[6:9]
	v_mfma_f32_16x16x32_bf16 v[2:5], v[230:233], v[214:217], v[2:5]
	v_mfma_f32_16x16x32_bf16 v[42:45], v[222:225], v[180:183], v[42:45]
	v_mfma_f32_16x16x32_bf16 v[46:49], v[230:233], v[180:183], v[46:49]
	s_add_i32 s50, 0, 0x18000
	v_add_u32_e32 v70, s50, v173
	s_barrier
	ds_read_b128 v[58:61], v70
	ds_read_b128 v[62:65], v70 offset:1024
	ds_read_b128 v[66:69], v70 offset:2048
	ds_read_b128 v[70:73], v70 offset:3072
	s_add_u32 s22, s22, 0x200000
	s_addc_u32 s23, s23, 0
	s_mov_b32 m0, s35
	ds_read_b128 v[176:179], v174 offset:32768
	ds_read_b128 v[180:183], v174 offset:33792
	ds_read_b128 v[184:187], v174 offset:34816
	ds_read_b128 v[188:191], v174 offset:35840
	ds_read_b128 v[192:195], v174 offset:36864
	ds_read_b128 v[196:199], v174 offset:37888
	ds_read_b128 v[210:213], v174 offset:38912
	ds_read_b128 v[214:217], v174 offset:39936
	global_load_lds_dwordx4 v160, s[22:23]
	s_mov_b32 m0, s36
	s_nop 0
	global_load_lds_dwordx4 v162, s[22:23]
	s_waitcnt lgkmcnt(8)
	s_barrier
	s_waitcnt lgkmcnt(0)
	v_mfma_f32_16x16x32_bf16 v[142:145], v[58:61], v[176:179], v[142:145]
	v_mfma_f32_16x16x32_bf16 v[138:141], v[66:69], v[176:179], v[138:141]
	v_mfma_f32_16x16x32_bf16 v[126:129], v[58:61], v[184:187], v[126:129]
	v_mfma_f32_16x16x32_bf16 v[122:125], v[66:69], v[184:187], v[122:125]
	v_mfma_f32_16x16x32_bf16 v[110:113], v[58:61], v[192:195], v[110:113]
	v_mfma_f32_16x16x32_bf16 v[106:109], v[66:69], v[192:195], v[106:109]
	v_mfma_f32_16x16x32_bf16 v[94:97], v[58:61], v[210:213], v[94:97]
	v_mfma_f32_16x16x32_bf16 v[90:93], v[66:69], v[210:213], v[90:93]
	v_mfma_f32_16x16x32_bf16 v[142:145], v[62:65], v[180:183], v[142:145]
	v_mfma_f32_16x16x32_bf16 v[138:141], v[70:73], v[180:183], v[138:141]
	v_mfma_f32_16x16x32_bf16 v[126:129], v[62:65], v[188:191], v[126:129]
	v_mfma_f32_16x16x32_bf16 v[122:125], v[70:73], v[188:191], v[122:125]
	v_mfma_f32_16x16x32_bf16 v[110:113], v[62:65], v[196:199], v[110:113]
	v_mfma_f32_16x16x32_bf16 v[106:109], v[70:73], v[196:199], v[106:109]
	v_mfma_f32_16x16x32_bf16 v[94:97], v[62:65], v[214:217], v[94:97]
	v_mfma_f32_16x16x32_bf16 v[90:93], v[70:73], v[214:217], v[90:93]
	s_barrier
	s_add_i32 s22, 0, 0x1c000
	s_add_i32 s23, s50, s31
	v_add_u32_e32 v175, s22, v173
	v_lshl_add_u64 v[170:171], v[170:171], 0, s[56:57]
	s_mov_b32 m0, s23
	ds_read_b128 v[218:221], v175
	ds_read_b128 v[222:225], v175 offset:1024
	ds_read_b128 v[226:229], v175 offset:2048
	ds_read_b128 v[230:233], v175 offset:3072
	global_load_lds_dwordx4 v[170:171], off
	v_lshl_add_u64 v[170:171], v[200:201], 0, s[56:57]
	s_add_i32 m0, s23, 0x2000
	s_nop 0
	global_load_lds_dwordx4 v[170:171], off
	s_barrier
	s_waitcnt lgkmcnt(0)
	v_mfma_f32_16x16x32_bf16 v[134:137], v[218:221], v[176:179], v[134:137]
	v_mfma_f32_16x16x32_bf16 v[130:133], v[226:229], v[176:179], v[130:133]
	v_mfma_f32_16x16x32_bf16 v[118:121], v[218:221], v[184:187], v[118:121]
	v_mfma_f32_16x16x32_bf16 v[114:117], v[226:229], v[184:187], v[114:117]
	v_mfma_f32_16x16x32_bf16 v[102:105], v[218:221], v[192:195], v[102:105]
	v_mfma_f32_16x16x32_bf16 v[98:101], v[226:229], v[192:195], v[98:101]
	v_mfma_f32_16x16x32_bf16 v[86:89], v[218:221], v[210:213], v[86:89]
	v_mfma_f32_16x16x32_bf16 v[82:85], v[226:229], v[210:213], v[82:85]
	v_mfma_f32_16x16x32_bf16 v[134:137], v[222:225], v[180:183], v[134:137]
	v_mfma_f32_16x16x32_bf16 v[130:133], v[230:233], v[180:183], v[130:133]
	v_mfma_f32_16x16x32_bf16 v[118:121], v[222:225], v[188:191], v[118:121]
	v_mfma_f32_16x16x32_bf16 v[114:117], v[230:233], v[188:191], v[114:117]
	v_mfma_f32_16x16x32_bf16 v[102:105], v[222:225], v[196:199], v[102:105]
	v_mfma_f32_16x16x32_bf16 v[98:101], v[230:233], v[196:199], v[98:101]
	v_mfma_f32_16x16x32_bf16 v[86:89], v[222:225], v[214:217], v[86:89]
	v_mfma_f32_16x16x32_bf16 v[82:85], v[230:233], v[214:217], v[82:85]
	s_mov_b32 m0, s39
	v_lshl_add_u64 v[170:171], v[234:235], 0, s[56:57]
	s_barrier
	ds_read_b128 v[176:179], v174 offset:49152
	ds_read_b128 v[180:183], v174 offset:50176
	ds_read_b128 v[184:187], v174 offset:51200
	ds_read_b128 v[188:191], v174 offset:52224
	ds_read_b128 v[192:195], v174 offset:53248
	ds_read_b128 v[196:199], v174 offset:54272
	ds_read_b128 v[210:213], v174 offset:55296
	ds_read_b128 v[214:217], v174 offset:56320
	global_load_lds_dwordx4 v[170:171], off
	v_lshl_add_u64 v[170:171], v[236:237], 0, s[56:57]
	s_mov_b32 m0, s40
	s_nop 0
	global_load_lds_dwordx4 v[170:171], off
	s_barrier
; __device__ __forceinline__ unsigned pk2(float lo, float hi) { f32x2 v = {lo, hi}; return __builtin_bit_cast(unsigned, __builtin_convertvector(v, bf16x2_t)); }
; __device__ __forceinline__ float bf_lo(unsigned w) { return __uint_as_float(w << 16); }
; __device__ __forceinline__ float bf_hi(unsigned w) { return __uint_as_float(w & 0xffff0000u); }
; #define PG8_BAR __builtin_amdgcn_s_barrier()
;     __device__ __forceinline__ void operator()(const f32x4 (&acc)[2][2][4][2], const Unit& u, int wr, int wc, int fr, int fq) const {
;         asm volatile("" : "+v"(fr), "+v"(fq));
;         const int row0 = u.pm * BM + wr * 64 + fr, col0 = u.pn * BM + wc * 32 + 8 * fq;
;         const float* gp = gate + (size_t)(u.pm >> 5) * 12288 + col0;
;         f32x4 gv[2][2];
; #pragma unroll
;         for (int bj = 0; bj < 2; ++bj)
; #pragma unroll
;             for (int n = 0; n < 2; ++n) gv[bj][n] = *(const f32x4*)(gp + bj * HALF + 4 * n);
; #pragma unroll
;         for (int ai = 0; ai < 2; ++ai)
; #pragma unroll
;             for (int m = 0; m < 4; ++m) {
;                 const size_t ro = (size_t)(row0 + ai * HALF + m * 16) * DM + col0;
; #pragma unroll
;                 for (int bj = 0; bj < 2; ++bj) {
;                     f32x4 r0, r1;
;                     if (RB) { const u32x4 rw = *(const u32x4*)((const bf16_t*)resid + ro + bj * HALF);
;                         r0 = (f32x4){bf_lo(rw.x), bf_hi(rw.x), bf_lo(rw.y), bf_hi(rw.y)}; r1 = (f32x4){bf_lo(rw.z), bf_hi(rw.z), bf_lo(rw.w), bf_hi(rw.w)}; }
;                     else { r0 = *(const f32x4*)((const float*)resid + ro + bj * HALF); r1 = *(const f32x4*)((const float*)resid + ro + bj * HALF + 4); }
;                     const f32x4 v0 = r0 + gv[bj][0] * acc[ai][bj][m][0], v1 = r1 + gv[bj][1] * acc[ai][bj][m][1];
;                     if (OB) { u32x4 w; w.x = pk2(v0[0], v0[1]); w.y = pk2(v0[2], v0[3]); w.z = pk2(v1[0], v1[1]); w.w = pk2(v1[2], v1[3]); *(u32x4*)((bf16_t*)out + ro + bj * HALF) = w; }
; template <class Epi>
; __device__ __forceinline__ void gemm_phase(LAS unsigned char* lds, const Gemm g, const StaticOrder& S, const Epi& E, const int tid) {
;     ...
;             PG8_BAR; PG8_WAIT_L(0); PG8_MMA(1, 0, At, B0); PG8_BAR; PG8_SCHED;
;             PG8_STAGE(PG8_SB(1, 1), b3 + hstep, voffB);
;             PG8_WAIT_V(6); PG8_BAR; PG8_MMA(1, 1, At, B1); PG8_BAR;
;         }
;         E(acc, cur, wr, wc, fr, fq);
	s_waitcnt lgkmcnt(0)
	v_mfma_f32_16x16x32_bf16 v[78:81], v[58:61], v[176:179], v[78:81]
	v_mfma_f32_16x16x32_bf16 v[74:77], v[66:69], v[176:179], v[74:77]
	v_mfma_f32_16x16x32_bf16 v[54:57], v[58:61], v[184:187], v[54:57]
	v_mfma_f32_16x16x32_bf16 v[50:53], v[66:69], v[184:187], v[50:53]
	v_mfma_f32_16x16x32_bf16 v[30:33], v[58:61], v[192:195], v[30:33]
	v_mfma_f32_16x16x32_bf16 v[26:29], v[66:69], v[192:195], v[26:29]
	v_mfma_f32_16x16x32_bf16 v[14:17], v[58:61], v[210:213], v[14:17]
	v_mfma_f32_16x16x32_bf16 v[10:13], v[66:69], v[210:213], v[10:13]
	v_mfma_f32_16x16x32_bf16 v[78:81], v[62:65], v[180:183], v[78:81]
	v_mfma_f32_16x16x32_bf16 v[74:77], v[70:73], v[180:183], v[74:77]
	v_mfma_f32_16x16x32_bf16 v[54:57], v[62:65], v[188:191], v[54:57]
	v_mfma_f32_16x16x32_bf16 v[50:53], v[70:73], v[188:191], v[50:53]
	v_mfma_f32_16x16x32_bf16 v[30:33], v[62:65], v[196:199], v[30:33]
	v_mfma_f32_16x16x32_bf16 v[26:29], v[70:73], v[196:199], v[26:29]
	v_mfma_f32_16x16x32_bf16 v[14:17], v[62:65], v[214:217], v[14:17]
	v_mfma_f32_16x16x32_bf16 v[10:13], v[70:73], v[214:217], v[10:13]
	s_barrier
	s_add_i32 s49, s49, 2
	s_add_u32 s47, s47, 0x100
	s_addc_u32 s48, s48, 0
	s_add_u32 s18, s18, 0x100
	s_addc_u32 s19, s19, 0
	s_add_u32 s20, s20, 0x200080
	s_addc_u32 s21, s21, 0
	s_add_i32 s22, s22, s31
	s_mov_b32 m0, s22
	s_nop 0
	global_load_lds_dwordx4 v0, s[20:21]
	s_add_i32 m0, s22, 0x2000
	s_nop 0
	global_load_lds_dwordx4 v164, s[20:21]
	s_waitcnt vmcnt(6)
	s_barrier
	v_mfma_f32_16x16x32_bf16 v[42:45], v[218:221], v[176:179], v[42:45]
	v_mfma_f32_16x16x32_bf16 v[70:73], v[222:225], v[180:183], v[42:45]
	v_mfma_f32_16x16x32_bf16 v[42:45], v[226:229], v[176:179], v[46:49]
	v_mfma_f32_16x16x32_bf16 v[38:41], v[218:221], v[184:187], v[38:41]
	v_mfma_f32_16x16x32_bf16 v[34:37], v[226:229], v[184:187], v[34:37]
	v_mfma_f32_16x16x32_bf16 v[22:25], v[218:221], v[192:195], v[22:25]
	v_mfma_f32_16x16x32_bf16 v[18:21], v[226:229], v[192:195], v[18:21]
	v_mfma_f32_16x16x32_bf16 v[6:9], v[218:221], v[210:213], v[6:9]
	v_mfma_f32_16x16x32_bf16 v[2:5], v[226:229], v[210:213], v[2:5]
	v_mfma_f32_16x16x32_bf16 v[66:69], v[230:233], v[180:183], v[42:45]
	v_mfma_f32_16x16x32_bf16 v[38:41], v[222:225], v[188:191], v[38:41]
	v_mfma_f32_16x16x32_bf16 v[34:37], v[230:233], v[188:191], v[34:37]
	v_mfma_f32_16x16x32_bf16 v[22:25], v[222:225], v[196:199], v[22:25]
	v_mfma_f32_16x16x32_bf16 v[18:21], v[230:233], v[196:199], v[18:21]
	v_mfma_f32_16x16x32_bf16 v[6:9], v[222:225], v[214:217], v[6:9]
	v_mfma_f32_16x16x32_bf16 v[2:5], v[230:233], v[214:217], v[2:5]
	s_cmpk_gt_u32 s49, 0x7d
	s_barrier
	s_cbranch_scc0 .LBB0_62
	s_setprio 0
	s_lshl_b32 s11, s2, 8
	s_lshl_b32 s13, s43, 8
	v_mov_b32_e32 v175, v172
	v_mov_b32_e32 v42, v159
	s_add_i32 s11, s11, s37
	s_or_b32 s13, s13, s38
	s_ashr_i32 s2, s2, 5
	s_mov_b32 s43, s10
	v_lshl_add_u32 v170, v42, 3, s13
	s_mul_hi_i32 s13, s2, 0xc000
	s_mul_i32 s2, s2, 0xc000
	v_add_u32_e32 v176, s11, v175
	s_add_u32 s18, s27, s2
	v_ashrrev_i32_e32 v177, 31, v176
	s_addc_u32 s19, s28, s13
	v_ashrrev_i32_e32 v171, 31, v170
	v_lshlrev_b64 v[176:177], 11, v[176:177]
	v_lshl_add_u64 v[46:47], v[170:171], 2, s[18:19]
	v_lshl_add_u64 v[170:171], v[176:177], 0, v[170:171]
	v_lshlrev_b64 v[170:171], 1, v[170:171]
	v_lshl_add_u64 v[180:181], s[8:9], 0, v[170:171]
	global_load_dwordx4 v[58:61], v[46:47], off offset:16
	global_load_dwordx4 v[62:65], v[46:47], off
	global_load_dwordx4 v[42:45], v[46:47], off offset:528
	s_nop 0
	global_load_dwordx4 v[46:49], v[46:47], off offset:512
	s_mov_b64 s[92:93], s[8:9]
	s_mov_b64 s[94:95], s[6:7]
	global_load_dwordx4 v[184:187], v170, s[92:93]
	global_load_dwordx4 v[188:191], v170, s[92:93] offset:256
	s_add_u32 s92, s92, 0x10000
	s_addc_u32 s93, s93, 0
	global_load_dwordx4 v[192:195], v170, s[92:93]
	global_load_dwordx4 v[196:199], v170, s[92:93] offset:256
	s_add_u32 s92, s92, 0x10000
	s_addc_u32 s93, s93, 0
	global_load_dwordx4 v[210:213], v170, s[92:93]
	global_load_dwordx4 v[214:217], v170, s[92:93] offset:256
	s_add_u32 s92, s92, 0x10000
	s_addc_u32 s93, s93, 0
	global_load_dwordx4 v[218:221], v170, s[92:93]
	global_load_dwordx4 v[222:225], v170, s[92:93] offset:256
	s_add_u32 s92, s92, 0x50000
	s_addc_u32 s93, s93, 0
	global_load_dwordx4 v[226:229], v170, s[92:93]
	global_load_dwordx4 v[230:233], v170, s[92:93] offset:256
	s_add_u32 s92, s92, 0x10000
	s_addc_u32 s93, s93, 0
	global_load_dwordx4 v[234:237], v170, s[92:93]
	s_waitcnt vmcnt(10)
	v_lshlrev_b32_e32 v176, 16, v184
	v_and_b32_e32 v177, 0xffff0000, v184
	v_lshlrev_b32_e32 v178, 16, v185
	v_and_b32_e32 v179, 0xffff0000, v185
	v_lshlrev_b32_e32 v180, 16, v186
	v_and_b32_e32 v181, 0xffff0000, v186
	v_lshlrev_b32_e32 v182, 16, v187
	v_and_b32_e32 v183, 0xffff0000, v187
	v_pk_fma_f32 v[142:143], v[142:143], v[62:63], v[176:177]
	v_pk_fma_f32 v[144:145], v[144:145], v[64:65], v[178:179]
	v_pk_fma_f32 v[138:139], v[138:139], v[58:59], v[180:181]
	v_pk_fma_f32 v[140:141], v[140:141], v[60:61], v[182:183]
	global_load_dwordx4 v[184:187], v170, s[92:93] offset:256
	v_cvt_pk_bf16_f32 v142, v142, v143
	v_cvt_pk_bf16_f32 v143, v144, v145
	v_cvt_pk_bf16_f32 v144, v138, v139
	v_cvt_pk_bf16_f32 v145, v140, v141
	global_store_dwordx4 v170, v[142:145], s[94:95]
	s_waitcnt vmcnt(11)
; __device__ __forceinline__ unsigned pk2(float lo, float hi) { f32x2 v = {lo, hi}; return __builtin_bit_cast(unsigned, __builtin_convertvector(v, bf16x2_t)); }
; __device__ __forceinline__ float bf_lo(unsigned w) { return __uint_as_float(w << 16); }
; __device__ __forceinline__ float bf_hi(unsigned w) { return __uint_as_float(w & 0xffff0000u); }
;     __device__ __forceinline__ void operator()(const f32x4 (&acc)[2][2][4][2], const Unit& u, int wr, int wc, int fr, int fq) const {
;     ...
; #pragma unroll
;                 for (int bj = 0; bj < 2; ++bj) {
;                     f32x4 r0, r1;
;                     if (RB) { const u32x4 rw = *(const u32x4*)((const bf16_t*)resid + ro + bj * HALF);
;                         r0 = (f32x4){bf_lo(rw.x), bf_hi(rw.x), bf_lo(rw.y), bf_hi(rw.y)}; r1 = (f32x4){bf_lo(rw.z), bf_hi(rw.z), bf_lo(rw.w), bf_hi(rw.w)}; }
;                     else { r0 = *(const f32x4*)((const float*)resid + ro + bj * HALF); r1 = *(const f32x4*)((const float*)resid + ro + bj * HALF + 4); }
;                     const f32x4 v0 = r0 + gv[bj][0] * acc[ai][bj][m][0], v1 = r1 + gv[bj][1] * acc[ai][bj][m][1];
;                     if (OB) { u32x4 w; w.x = pk2(v0[0], v0[1]); w.y = pk2(v0[2], v0[3]); w.z = pk2(v1[0], v1[1]); w.w = pk2(v1[2], v1[3]); *(u32x4*)((bf16_t*)out + ro + bj * HALF) = w; }
;                     else { *(f32x4*)((float*)out + ro + bj * HALF) = v0; *(f32x4*)((float*)out + ro + bj * HALF + 4) = v1; }
;                 }
	v_lshlrev_b32_e32 v176, 16, v188
	v_and_b32_e32 v177, 0xffff0000, v188
	v_lshlrev_b32_e32 v178, 16, v189
	v_and_b32_e32 v179, 0xffff0000, v189
	v_lshlrev_b32_e32 v180, 16, v190
	v_and_b32_e32 v181, 0xffff0000, v190
	v_lshlrev_b32_e32 v182, 16, v191
	v_and_b32_e32 v183, 0xffff0000, v191
	v_pk_fma_f32 v[134:135], v[134:135], v[46:47], v[176:177]
	v_pk_fma_f32 v[136:137], v[136:137], v[48:49], v[178:179]
	v_pk_fma_f32 v[130:131], v[130:131], v[42:43], v[180:181]
	v_pk_fma_f32 v[132:133], v[132:133], v[44:45], v[182:183]
	s_add_u32 s92, s92, 0x10000
	s_addc_u32 s93, s93, 0
	global_load_dwordx4 v[188:191], v170, s[92:93]
	v_cvt_pk_bf16_f32 v134, v134, v135
	v_cvt_pk_bf16_f32 v135, v136, v137
	v_cvt_pk_bf16_f32 v136, v130, v131
	v_cvt_pk_bf16_f32 v137, v132, v133
	global_store_dwordx4 v170, v[134:137], s[94:95] offset:256
	s_waitcnt vmcnt(12)
	v_lshlrev_b32_e32 v176, 16, v192
	v_and_b32_e32 v177, 0xffff0000, v192
	v_lshlrev_b32_e32 v178, 16, v193
	v_and_b32_e32 v179, 0xffff0000, v193
	v_lshlrev_b32_e32 v180, 16, v194
	v_and_b32_e32 v181, 0xffff0000, v194
	v_lshlrev_b32_e32 v182, 16, v195
	v_and_b32_e32 v183, 0xffff0000, v195
	v_pk_fma_f32 v[126:127], v[126:127], v[62:63], v[176:177]
	v_pk_fma_f32 v[128:129], v[128:129], v[64:65], v[178:179]
	v_pk_fma_f32 v[122:123], v[122:123], v[58:59], v[180:181]
	v_pk_fma_f32 v[124:125], v[124:125], v[60:61], v[182:183]
	global_load_dwordx4 v[192:195], v170, s[92:93] offset:256
	s_add_u32 s94, s94, 0x10000
	s_addc_u32 s95, s95, 0
	v_cvt_pk_bf16_f32 v126, v126, v127
	v_cvt_pk_bf16_f32 v127, v128, v129
	v_cvt_pk_bf16_f32 v128, v122, v123
	v_cvt_pk_bf16_f32 v129, v124, v125
	global_store_dwordx4 v170, v[126:129], s[94:95]
	s_waitcnt vmcnt(13)
	v_lshlrev_b32_e32 v176, 16, v196
	v_and_b32_e32 v177, 0xffff0000, v196
	v_lshlrev_b32_e32 v178, 16, v197
	v_and_b32_e32 v179, 0xffff0000, v197
	v_lshlrev_b32_e32 v180, 16, v198
	v_and_b32_e32 v181, 0xffff0000, v198
	v_lshlrev_b32_e32 v182, 16, v199
	v_and_b32_e32 v183, 0xffff0000, v199
	v_pk_fma_f32 v[118:119], v[118:119], v[46:47], v[176:177]
	v_pk_fma_f32 v[120:121], v[120:121], v[48:49], v[178:179]
	v_pk_fma_f32 v[114:115], v[114:115], v[42:43], v[180:181]
	v_pk_fma_f32 v[116:117], v[116:117], v[44:45], v[182:183]
	s_add_u32 s92, s92, 0x10000
	s_addc_u32 s93, s93, 0
	global_load_dwordx4 v[196:199], v170, s[92:93]
	v_cvt_pk_bf16_f32 v118, v118, v119
	v_cvt_pk_bf16_f32 v119, v120, v121
	v_cvt_pk_bf16_f32 v120, v114, v115
	v_cvt_pk_bf16_f32 v121, v116, v117
	global_store_dwordx4 v170, v[118:121], s[94:95] offset:256
	s_waitcnt vmcnt(14)
	v_lshlrev_b32_e32 v176, 16, v210
	v_and_b32_e32 v177, 0xffff0000, v210
	v_lshlrev_b32_e32 v178, 16, v211
	v_and_b32_e32 v179, 0xffff0000, v211
	v_lshlrev_b32_e32 v180, 16, v212
	v_and_b32_e32 v181, 0xffff0000, v212
	v_lshlrev_b32_e32 v182, 16, v213
	v_and_b32_e32 v183, 0xffff0000, v213
	v_pk_fma_f32 v[110:111], v[110:111], v[62:63], v[176:177]
	v_pk_fma_f32 v[112:113], v[112:113], v[64:65], v[178:179]
	v_pk_fma_f32 v[106:107], v[106:107], v[58:59], v[180:181]
	v_pk_fma_f32 v[108:109], v[108:109], v[60:61], v[182:183]
	global_load_dwordx4 v[210:213], v170, s[92:93] offset:256
	s_add_u32 s94, s94, 0x10000
	s_addc_u32 s95, s95, 0
	v_cvt_pk_bf16_f32 v110, v110, v111
	v_cvt_pk_bf16_f32 v111, v112, v113
	v_cvt_pk_bf16_f32 v112, v106, v107
	v_cvt_pk_bf16_f32 v113, v108, v109
	global_store_dwordx4 v170, v[110:113], s[94:95]
	s_waitcnt vmcnt(15)
	v_lshlrev_b32_e32 v176, 16, v214
	v_and_b32_e32 v177, 0xffff0000, v214
	v_lshlrev_b32_e32 v178, 16, v215
	v_and_b32_e32 v179, 0xffff0000, v215
	v_lshlrev_b32_e32 v180, 16, v216
	v_and_b32_e32 v181, 0xffff0000, v216
	v_lshlrev_b32_e32 v182, 16, v217
	v_and_b32_e32 v183, 0xffff0000, v217
	v_pk_fma_f32 v[102:103], v[102:103], v[46:47], v[176:177]
	v_pk_fma_f32 v[104:105], v[104:105], v[48:49], v[178:179]
	v_pk_fma_f32 v[98:99], v[98:99], v[42:43], v[180:181]
	v_pk_fma_f32 v[100:101], v[100:101], v[44:45], v[182:183]
	v_cvt_pk_bf16_f32 v102, v102, v103
	v_cvt_pk_bf16_f32 v103, v104, v105
	v_cvt_pk_bf16_f32 v104, v98, v99
	v_cvt_pk_bf16_f32 v105, v100, v101
	global_store_dwordx4 v170, v[102:105], s[94:95] offset:256
	s_waitcnt vmcnt(15)
	v_lshlrev_b32_e32 v176, 16, v218
	v_and_b32_e32 v177, 0xffff0000, v218
	v_lshlrev_b32_e32 v178, 16, v219
	v_and_b32_e32 v179, 0xffff0000, v219
	v_lshlrev_b32_e32 v180, 16, v220
	v_and_b32_e32 v181, 0xffff0000, v220
	v_lshlrev_b32_e32 v182, 16, v221
	v_and_b32_e32 v183, 0xffff0000, v221
	v_pk_fma_f32 v[94:95], v[94:95], v[62:63], v[176:177]
	v_pk_fma_f32 v[96:97], v[96:97], v[64:65], v[178:179]
	v_pk_fma_f32 v[90:91], v[90:91], v[58:59], v[180:181]
	v_pk_fma_f32 v[92:93], v[92:93], v[60:61], v[182:183]
	s_add_u32 s94, s94, 0x10000
	s_addc_u32 s95, s95, 0
	v_cvt_pk_bf16_f32 v94, v94, v95
	v_cvt_pk_bf16_f32 v95, v96, v97
	v_cvt_pk_bf16_f32 v96, v90, v91
	v_cvt_pk_bf16_f32 v97, v92, v93
	global_store_dwordx4 v170, v[94:97], s[94:95]
	s_waitcnt vmcnt(15)
	v_lshlrev_b32_e32 v176, 16, v222
	v_and_b32_e32 v177, 0xffff0000, v222
	v_lshlrev_b32_e32 v178, 16, v223
	v_and_b32_e32 v179, 0xffff0000, v223
	v_lshlrev_b32_e32 v180, 16, v224
	v_and_b32_e32 v181, 0xffff0000, v224
	v_lshlrev_b32_e32 v182, 16, v225
	v_and_b32_e32 v183, 0xffff0000, v225
	v_pk_fma_f32 v[86:87], v[86:87], v[46:47], v[176:177]
	v_pk_fma_f32 v[88:89], v[88:89], v[48:49], v[178:179]
	v_pk_fma_f32 v[82:83], v[82:83], v[42:43], v[180:181]
	v_pk_fma_f32 v[84:85], v[84:85], v[44:45], v[182:183]
	v_cvt_pk_bf16_f32 v86, v86, v87
	v_cvt_pk_bf16_f32 v87, v88, v89
	v_cvt_pk_bf16_f32 v88, v82, v83
	v_cvt_pk_bf16_f32 v89, v84, v85
	global_store_dwordx4 v170, v[86:89], s[94:95] offset:256
	s_waitcnt vmcnt(15)
; __device__ __forceinline__ unsigned pk2(float lo, float hi) { f32x2 v = {lo, hi}; return __builtin_bit_cast(unsigned, __builtin_convertvector(v, bf16x2_t)); }
; __device__ __forceinline__ float bf_lo(unsigned w) { return __uint_as_float(w << 16); }
; __device__ __forceinline__ float bf_hi(unsigned w) { return __uint_as_float(w & 0xffff0000u); }
; #define PG8_WAIT_V(n) asm volatile("s_waitcnt vmcnt(" #n ")" ::: "memory")
; #define PG8_BAR __builtin_amdgcn_s_barrier()
;     __device__ __forceinline__ void operator()(const f32x4 (&acc)[2][2][4][2], const Unit& u, int wr, int wc, int fr, int fq) const {
;     ...
; #pragma unroll
;                 for (int bj = 0; bj < 2; ++bj) {
;                     f32x4 r0, r1;
;                     if (RB) { const u32x4 rw = *(const u32x4*)((const bf16_t*)resid + ro + bj * HALF);
;                         r0 = (f32x4){bf_lo(rw.x), bf_hi(rw.x), bf_lo(rw.y), bf_hi(rw.y)}; r1 = (f32x4){bf_lo(rw.z), bf_hi(rw.z), bf_lo(rw.w), bf_hi(rw.w)}; }
;                     else { r0 = *(const f32x4*)((const float*)resid + ro + bj * HALF); r1 = *(const f32x4*)((const float*)resid + ro + bj * HALF + 4); }
;                     const f32x4 v0 = r0 + gv[bj][0] * acc[ai][bj][m][0], v1 = r1 + gv[bj][1] * acc[ai][bj][m][1];
;                     if (OB) { u32x4 w; w.x = pk2(v0[0], v0[1]); w.y = pk2(v0[2], v0[3]); w.z = pk2(v1[0], v1[1]); w.w = pk2(v1[2], v1[3]); *(u32x4*)((bf16_t*)out + ro + bj * HALF) = w; }
;                     else { *(f32x4*)((float*)out + ro + bj * HALF) = v0; *(f32x4*)((float*)out + ro + bj * HALF + 4) = v1; }
;                 }
; template <class Epi>
; __device__ __forceinline__ void gemm_phase(LAS unsigned char* lds, const Gemm g, const StaticOrder& S, const Epi& E, const int tid) {
;     ...
;         E(acc, cur, wr, wc, fr, fq);
;         if (!has_next) break;
; #pragma unroll
;         for (int a = 0; a < 2; ++a)
; #pragma unroll
;             for (int b = 0; b < 2; ++b)
; #pragma unroll
;                 for (int m = 0; m < 4; ++m)
; #pragma unroll
;                     for (int n = 0; n < 2; ++n) acc[a][b][m][n] = (f32x4){0.f, 0.f, 0.f, 0.f};
;         cur = nxt; cA = nA; cB = nB; ++ui;
;     }
;     PG8_WAIT_V(0);
;     if (wr == 0) PG8_BAR;
;     PG8_BAR;
	v_lshlrev_b32_e32 v176, 16, v226
	v_and_b32_e32 v177, 0xffff0000, v226
	v_lshlrev_b32_e32 v178, 16, v227
	v_and_b32_e32 v179, 0xffff0000, v227
	v_lshlrev_b32_e32 v180, 16, v228
	v_and_b32_e32 v181, 0xffff0000, v228
	v_lshlrev_b32_e32 v182, 16, v229
	v_and_b32_e32 v183, 0xffff0000, v229
	v_pk_fma_f32 v[78:79], v[78:79], v[62:63], v[176:177]
	v_pk_fma_f32 v[80:81], v[80:81], v[64:65], v[178:179]
	v_pk_fma_f32 v[74:75], v[74:75], v[58:59], v[180:181]
	v_pk_fma_f32 v[76:77], v[76:77], v[60:61], v[182:183]
	s_add_u32 s94, s94, 0x50000
	s_addc_u32 s95, s95, 0
	v_cvt_pk_bf16_f32 v78, v78, v79
	v_cvt_pk_bf16_f32 v79, v80, v81
	v_cvt_pk_bf16_f32 v80, v74, v75
	v_cvt_pk_bf16_f32 v81, v76, v77
	global_store_dwordx4 v170, v[78:81], s[94:95]
	s_waitcnt vmcnt(15)
	v_lshlrev_b32_e32 v176, 16, v230
	v_and_b32_e32 v177, 0xffff0000, v230
	v_lshlrev_b32_e32 v178, 16, v231
	v_and_b32_e32 v179, 0xffff0000, v231
	v_lshlrev_b32_e32 v180, 16, v232
	v_and_b32_e32 v181, 0xffff0000, v232
	v_lshlrev_b32_e32 v182, 16, v233
	v_and_b32_e32 v183, 0xffff0000, v233
	v_pk_fma_f32 v[70:71], v[70:71], v[46:47], v[176:177]
	v_pk_fma_f32 v[72:73], v[72:73], v[48:49], v[178:179]
	v_pk_fma_f32 v[66:67], v[66:67], v[42:43], v[180:181]
	v_pk_fma_f32 v[68:69], v[68:69], v[44:45], v[182:183]
	v_cvt_pk_bf16_f32 v70, v70, v71
	v_cvt_pk_bf16_f32 v71, v72, v73
	v_cvt_pk_bf16_f32 v72, v66, v67
	v_cvt_pk_bf16_f32 v73, v68, v69
	global_store_dwordx4 v170, v[70:73], s[94:95] offset:256
	s_waitcnt vmcnt(15)
	v_lshlrev_b32_e32 v176, 16, v234
	v_and_b32_e32 v177, 0xffff0000, v234
	v_lshlrev_b32_e32 v178, 16, v235
	v_and_b32_e32 v179, 0xffff0000, v235
	v_lshlrev_b32_e32 v180, 16, v236
	v_and_b32_e32 v181, 0xffff0000, v236
	v_lshlrev_b32_e32 v182, 16, v237
	v_and_b32_e32 v183, 0xffff0000, v237
	v_pk_fma_f32 v[54:55], v[54:55], v[62:63], v[176:177]
	v_pk_fma_f32 v[56:57], v[56:57], v[64:65], v[178:179]
	v_pk_fma_f32 v[50:51], v[50:51], v[58:59], v[180:181]
	v_pk_fma_f32 v[52:53], v[52:53], v[60:61], v[182:183]
	s_add_u32 s94, s94, 0x10000
	s_addc_u32 s95, s95, 0
	v_cvt_pk_bf16_f32 v54, v54, v55
	v_cvt_pk_bf16_f32 v55, v56, v57
	v_cvt_pk_bf16_f32 v56, v50, v51
	v_cvt_pk_bf16_f32 v57, v52, v53
	global_store_dwordx4 v170, v[54:57], s[94:95]
	s_waitcnt vmcnt(15)
	v_lshlrev_b32_e32 v176, 16, v184
	v_and_b32_e32 v177, 0xffff0000, v184
	v_lshlrev_b32_e32 v178, 16, v185
	v_and_b32_e32 v179, 0xffff0000, v185
	v_lshlrev_b32_e32 v180, 16, v186
	v_and_b32_e32 v181, 0xffff0000, v186
	v_lshlrev_b32_e32 v182, 16, v187
	v_and_b32_e32 v183, 0xffff0000, v187
	v_pk_fma_f32 v[38:39], v[38:39], v[46:47], v[176:177]
	v_pk_fma_f32 v[40:41], v[40:41], v[48:49], v[178:179]
	v_pk_fma_f32 v[34:35], v[34:35], v[42:43], v[180:181]
	v_pk_fma_f32 v[36:37], v[36:37], v[44:45], v[182:183]
	v_cvt_pk_bf16_f32 v38, v38, v39
	v_cvt_pk_bf16_f32 v39, v40, v41
	v_cvt_pk_bf16_f32 v40, v34, v35
	v_cvt_pk_bf16_f32 v41, v36, v37
	global_store_dwordx4 v170, v[38:41], s[94:95] offset:256
	s_waitcnt vmcnt(14)
	v_lshlrev_b32_e32 v176, 16, v188
	v_and_b32_e32 v177, 0xffff0000, v188
	v_lshlrev_b32_e32 v178, 16, v189
	v_and_b32_e32 v179, 0xffff0000, v189
	v_lshlrev_b32_e32 v180, 16, v190
	v_and_b32_e32 v181, 0xffff0000, v190
	v_lshlrev_b32_e32 v182, 16, v191
	v_and_b32_e32 v183, 0xffff0000, v191
	v_pk_fma_f32 v[30:31], v[30:31], v[62:63], v[176:177]
	v_pk_fma_f32 v[32:33], v[32:33], v[64:65], v[178:179]
	v_pk_fma_f32 v[26:27], v[26:27], v[58:59], v[180:181]
	v_pk_fma_f32 v[28:29], v[28:29], v[60:61], v[182:183]
	s_add_u32 s94, s94, 0x10000
	s_addc_u32 s95, s95, 0
	v_cvt_pk_bf16_f32 v30, v30, v31
	v_cvt_pk_bf16_f32 v31, v32, v33
	v_cvt_pk_bf16_f32 v32, v26, v27
	v_cvt_pk_bf16_f32 v33, v28, v29
	global_store_dwordx4 v170, v[30:33], s[94:95]
	s_waitcnt vmcnt(13)
	v_lshlrev_b32_e32 v176, 16, v192
	v_and_b32_e32 v177, 0xffff0000, v192
	v_lshlrev_b32_e32 v178, 16, v193
	v_and_b32_e32 v179, 0xffff0000, v193
	v_lshlrev_b32_e32 v180, 16, v194
	v_and_b32_e32 v181, 0xffff0000, v194
	v_lshlrev_b32_e32 v182, 16, v195
	v_and_b32_e32 v183, 0xffff0000, v195
	v_pk_fma_f32 v[22:23], v[22:23], v[46:47], v[176:177]
	v_pk_fma_f32 v[24:25], v[24:25], v[48:49], v[178:179]
	v_pk_fma_f32 v[18:19], v[18:19], v[42:43], v[180:181]
	v_pk_fma_f32 v[20:21], v[20:21], v[44:45], v[182:183]
	v_cvt_pk_bf16_f32 v22, v22, v23
	v_cvt_pk_bf16_f32 v23, v24, v25
	v_cvt_pk_bf16_f32 v24, v18, v19
	v_cvt_pk_bf16_f32 v25, v20, v21
	global_store_dwordx4 v170, v[22:25], s[94:95] offset:256
	s_waitcnt vmcnt(12)
	v_lshlrev_b32_e32 v176, 16, v196
	v_and_b32_e32 v177, 0xffff0000, v196
	v_lshlrev_b32_e32 v178, 16, v197
	v_and_b32_e32 v179, 0xffff0000, v197
	v_lshlrev_b32_e32 v180, 16, v198
	v_and_b32_e32 v181, 0xffff0000, v198
	v_lshlrev_b32_e32 v182, 16, v199
	v_and_b32_e32 v183, 0xffff0000, v199
	v_pk_fma_f32 v[14:15], v[14:15], v[62:63], v[176:177]
	v_pk_fma_f32 v[16:17], v[16:17], v[64:65], v[178:179]
	v_pk_fma_f32 v[10:11], v[10:11], v[58:59], v[180:181]
	v_pk_fma_f32 v[12:13], v[12:13], v[60:61], v[182:183]
	s_add_u32 s94, s94, 0x10000
	s_addc_u32 s95, s95, 0
	v_cvt_pk_bf16_f32 v14, v14, v15
	v_cvt_pk_bf16_f32 v15, v16, v17
	v_cvt_pk_bf16_f32 v16, v10, v11
	v_cvt_pk_bf16_f32 v17, v12, v13
	global_store_dwordx4 v170, v[14:17], s[94:95]
	s_waitcnt vmcnt(11)
	v_lshlrev_b32_e32 v176, 16, v210
	v_and_b32_e32 v177, 0xffff0000, v210
	v_lshlrev_b32_e32 v178, 16, v211
	v_and_b32_e32 v179, 0xffff0000, v211
	v_lshlrev_b32_e32 v180, 16, v212
	v_and_b32_e32 v181, 0xffff0000, v212
	v_lshlrev_b32_e32 v182, 16, v213
	v_and_b32_e32 v183, 0xffff0000, v213
	v_pk_fma_f32 v[6:7], v[6:7], v[46:47], v[176:177]
	v_pk_fma_f32 v[8:9], v[8:9], v[48:49], v[178:179]
	v_pk_fma_f32 v[2:3], v[2:3], v[42:43], v[180:181]
	v_pk_fma_f32 v[4:5], v[4:5], v[44:45], v[182:183]
	v_cvt_pk_bf16_f32 v6, v6, v7
	v_cvt_pk_bf16_f32 v7, v8, v9
	v_cvt_pk_bf16_f32 v8, v2, v3
	v_cvt_pk_bf16_f32 v9, v4, v5
	global_store_dwordx4 v170, v[6:9], s[94:95] offset:256
	s_mov_b32 s2, s12
	s_mov_b64 s[20:21], s[14:15]
	s_mov_b64 s[18:19], s[16:17]
	s_and_b64 vcc, exec, s[4:5]
	s_nop 1
	s_cbranch_vccz .LBB0_55
	s_waitcnt vmcnt(0)
	s_cmpk_gt_u32 s29, 0xff
	s_cbranch_scc1 .LBB0_66
	s_barrier

; #define PG8_STAGE(bufoff, gbase, voff) do { _Pragma("unroll") for (int _i = 0; _i < 2; ++_i) \
;         __builtin_amdgcn_global_load_lds((const unsigned*)((const char*)(gbase) + (voff)[_i]), (LAS unsigned*)(lds + (bufoff) + ldsw + _i * 8192), 16, 0, 0); } while (0)
; #define PG8_LDA(dst, b, h) do { _Pragma("unroll") for (int m = 0; m < 4; ++m) _Pragma("unroll") for (int k = 0; k < 2; ++k) dst[m][k] = *(const LAS bf16x8*)(lds + PG8_SA(b, h) + aoff + m * 2048 + k * 1024); } while (0)
; #define PG8_LDB(dst, b, h) do { _Pragma("unroll") for (int n = 0; n < 2; ++n) _Pragma("unroll") for (int k = 0; k < 2; ++k) dst[n][k] = *(const LAS bf16x8*)(lds + PG8_SB(b, h) + boff + n * 2048 + k * 1024); } while (0)
; #define PG8_MMA(ai, bj, At, Bt) do { __builtin_amdgcn_s_setprio(1); _Pragma("unroll") for (int m = 0; m < 4; ++m) _Pragma("unroll") for (int n = 0; n < 2; ++n) _Pragma("unroll") for (int k = 0; k < 2; ++k) \
;         acc[ai][bj][m][n] = __builtin_amdgcn_mfma_f32_16x16x32_bf16(Bt[n][k], At[m][k], acc[ai][bj][m][n], 0, 0, 0); __builtin_amdgcn_s_setprio(0); } while (0)
; #define PG8_WAIT_L(n) asm volatile("s_waitcnt lgkmcnt(" #n ")" ::: "memory")
; #define PG8_BAR __builtin_amdgcn_s_barrier()
; #define PG8_SCHED __builtin_amdgcn_sched_barrier(0)
; template <class Epi>
; __device__ __forceinline__ void gemm_phase(LAS unsigned char* lds, const Gemm g, const StaticOrder& S, const Epi& E, const int tid) {
;     ...
;             const bool last = (t == nt - 2);
;             const char* a1 = cA + (size_t)(t + 1) * kstep;
;             const char* a2 = last ? nA : cA + (size_t)(t + 2) * kstep; const char* b2 = last ? nB : cB + (size_t)(t + 2) * kstep;
;             const char* a3 = a2 + kstep; const char* b3 = b2 + kstep;
;             PG8_LDB(B0, 0, 0); PG8_SCHED; PG8_LDA(At, 0, 0); PG8_STAGE(PG8_SA(1, 1), a1 + hstep, voffA);
;             PG8_WAIT_L(8); PG8_BAR; PG8_WAIT_L(0); PG8_MMA(0, 0, At, B0); PG8_BAR; PG8_SCHED;
;             PG8_LDB(B1, 0, 1); PG8_STAGE(PG8_SB(0, 0), b2, voffB);
;             PG8_BAR; PG8_WAIT_L(0); PG8_MMA(0, 1, At, B1); PG8_BAR;
;             PG8_LDA(At, 0, 1); PG8_STAGE(PG8_SA(0, 0), a2, voffA);
;             PG8_BAR; PG8_WAIT_L(0); PG8_MMA(1, 0, At, B0); PG8_BAR; PG8_SCHED;
.Lgprio2:
.LBB0_84:
	s_add_u32 s18, s16, 0xfff80080
	s_addc_u32 s19, s17, -1
	s_add_i32 s45, 0, 0x10000
	v_add_u32_e32 v140, s45, v144
	ds_read_b128 v[160:163], v140
	ds_read_b128 v[164:167], v140 offset:1024
	ds_read_b128 v[168:171], v140 offset:2048
	ds_read_b128 v[172:175], v140 offset:3072
	s_cmp_eq_u32 s44, 28
	s_cselect_b32 s21, s9, s19
	s_cselect_b32 s20, s40, s18
	s_cselect_b32 s19, s7, s43
	s_cselect_b32 s18, s41, s42
	s_add_i32 m0, s15, 0xc000
	ds_read_b128 v[176:179], v145
	ds_read_b128 v[180:183], v145 offset:1024
	ds_read_b128 v[184:187], v145 offset:2048
	ds_read_b128 v[188:191], v145 offset:3072
	ds_read_b128 v[192:195], v145 offset:4096
	ds_read_b128 v[196:199], v145 offset:5120
	ds_read_b128 v[210:213], v145 offset:6144
	ds_read_b128 v[214:217], v145 offset:7168
	global_load_lds_dwordx4 v138, s[16:17]
	v_lshl_add_u64 v[140:141], s[16:17], 0, v[136:137]
	s_add_i32 m0, s15, 0xe000
	s_nop 0
	global_load_lds_dwordx4 v[140:141], off
	s_waitcnt lgkmcnt(8)
	s_barrier
	s_waitcnt lgkmcnt(0)
	v_mfma_f32_16x16x32_bf16 v[126:129], v[160:163], v[176:179], v[126:129]
	v_mfma_f32_16x16x32_bf16 v[122:125], v[168:171], v[176:179], v[122:125]
	v_mfma_f32_16x16x32_bf16 v[110:113], v[160:163], v[184:187], v[110:113]
	v_mfma_f32_16x16x32_bf16 v[106:109], v[168:171], v[184:187], v[106:109]
	v_mfma_f32_16x16x32_bf16 v[94:97], v[160:163], v[192:195], v[94:97]
	v_mfma_f32_16x16x32_bf16 v[90:93], v[168:171], v[192:195], v[90:93]
	v_mfma_f32_16x16x32_bf16 v[78:81], v[160:163], v[210:213], v[78:81]
	v_mfma_f32_16x16x32_bf16 v[74:77], v[168:171], v[210:213], v[74:77]
	v_mfma_f32_16x16x32_bf16 v[126:129], v[164:167], v[180:183], v[126:129]
	v_mfma_f32_16x16x32_bf16 v[122:125], v[172:175], v[180:183], v[122:125]
	v_mfma_f32_16x16x32_bf16 v[110:113], v[164:167], v[188:191], v[110:113]
	v_mfma_f32_16x16x32_bf16 v[106:109], v[172:175], v[188:191], v[106:109]
	v_mfma_f32_16x16x32_bf16 v[94:97], v[164:167], v[196:199], v[94:97]
	v_mfma_f32_16x16x32_bf16 v[90:93], v[172:175], v[196:199], v[90:93]
	v_mfma_f32_16x16x32_bf16 v[78:81], v[164:167], v[214:217], v[78:81]
	v_mfma_f32_16x16x32_bf16 v[74:77], v[172:175], v[214:217], v[74:77]
	s_barrier
	s_add_i32 s47, 0, 0x14000
	v_add_u32_e32 v140, s47, v144
	s_add_i32 s45, s45, s26
	ds_read_b128 v[218:221], v140
	ds_read_b128 v[222:225], v140 offset:1024
	ds_read_b128 v[226:229], v140 offset:2048
	ds_read_b128 v[230:233], v140 offset:3072
	v_lshl_add_u64 v[140:141], s[18:19], 0, v[0:1]
	s_mov_b32 m0, s45
	v_lshl_add_u64 v[200:201], s[18:19], 0, v[134:135]
	global_load_lds_dwordx4 v[140:141], off
	s_add_i32 m0, s45, 0x2000
	s_nop 0
	global_load_lds_dwordx4 v[200:201], off
	s_barrier
	s_waitcnt lgkmcnt(0)
	v_mfma_f32_16x16x32_bf16 v[118:121], v[218:221], v[176:179], v[118:121]
	v_mfma_f32_16x16x32_bf16 v[114:117], v[226:229], v[176:179], v[114:117]
	v_mfma_f32_16x16x32_bf16 v[102:105], v[218:221], v[184:187], v[102:105]
	v_mfma_f32_16x16x32_bf16 v[98:101], v[226:229], v[184:187], v[98:101]
	v_mfma_f32_16x16x32_bf16 v[86:89], v[218:221], v[192:195], v[86:89]
	v_mfma_f32_16x16x32_bf16 v[82:85], v[226:229], v[192:195], v[82:85]
	v_mfma_f32_16x16x32_bf16 v[70:73], v[218:221], v[210:213], v[70:73]
	v_mfma_f32_16x16x32_bf16 v[66:69], v[226:229], v[210:213], v[66:69]
	v_mfma_f32_16x16x32_bf16 v[118:121], v[222:225], v[180:183], v[118:121]
	v_mfma_f32_16x16x32_bf16 v[114:117], v[230:233], v[180:183], v[114:117]
	v_mfma_f32_16x16x32_bf16 v[102:105], v[222:225], v[188:191], v[102:105]
	v_mfma_f32_16x16x32_bf16 v[98:101], v[230:233], v[188:191], v[98:101]
	v_mfma_f32_16x16x32_bf16 v[86:89], v[222:225], v[196:199], v[86:89]
	v_mfma_f32_16x16x32_bf16 v[82:85], v[230:233], v[196:199], v[82:85]
	v_mfma_f32_16x16x32_bf16 v[70:73], v[222:225], v[214:217], v[70:73]
	v_mfma_f32_16x16x32_bf16 v[66:69], v[230:233], v[214:217], v[66:69]
	s_mov_b32 m0, s15
	v_lshl_add_u64 v[234:235], s[20:21], 0, v[130:131]
	s_barrier
	ds_read_b128 v[176:179], v145 offset:16384
	ds_read_b128 v[180:183], v145 offset:17408
	ds_read_b128 v[184:187], v145 offset:18432
	ds_read_b128 v[188:191], v145 offset:19456
	ds_read_b128 v[192:195], v145 offset:20480
	ds_read_b128 v[196:199], v145 offset:21504
	ds_read_b128 v[210:213], v145 offset:22528
	ds_read_b128 v[214:217], v145 offset:23552
	global_load_lds_dwordx4 v[234:235], off
	v_lshl_add_u64 v[236:237], s[20:21], 0, v[132:133]
	s_mov_b32 m0, s27
	s_nop 0
	global_load_lds_dwordx4 v[236:237], off
	s_barrier
	s_waitcnt lgkmcnt(0)
	v_mfma_f32_16x16x32_bf16 v[62:65], v[160:163], v[176:179], v[62:65]
	v_mfma_f32_16x16x32_bf16 v[58:61], v[168:171], v[176:179], v[58:61]
	v_mfma_f32_16x16x32_bf16 v[46:49], v[160:163], v[184:187], v[46:49]
	v_mfma_f32_16x16x32_bf16 v[42:45], v[168:171], v[184:187], v[42:45]
	v_mfma_f32_16x16x32_bf16 v[30:33], v[160:163], v[192:195], v[30:33]
	v_mfma_f32_16x16x32_bf16 v[26:29], v[168:171], v[192:195], v[26:29]
	v_mfma_f32_16x16x32_bf16 v[14:17], v[160:163], v[210:213], v[14:17]
	v_mfma_f32_16x16x32_bf16 v[10:13], v[168:171], v[210:213], v[10:13]
	v_mfma_f32_16x16x32_bf16 v[62:65], v[164:167], v[180:183], v[62:65]
	v_mfma_f32_16x16x32_bf16 v[58:61], v[172:175], v[180:183], v[58:61]
	v_mfma_f32_16x16x32_bf16 v[46:49], v[164:167], v[188:191], v[46:49]
	v_mfma_f32_16x16x32_bf16 v[42:45], v[172:175], v[188:191], v[42:45]
	v_mfma_f32_16x16x32_bf16 v[30:33], v[164:167], v[196:199], v[30:33]
	v_mfma_f32_16x16x32_bf16 v[26:29], v[172:175], v[196:199], v[26:29]
	v_mfma_f32_16x16x32_bf16 v[14:17], v[164:167], v[214:217], v[14:17]
	v_mfma_f32_16x16x32_bf16 v[10:13], v[172:175], v[214:217], v[10:13]
	s_barrier
; #define PG8_STAGE(bufoff, gbase, voff) do { _Pragma("unroll") for (int _i = 0; _i < 2; ++_i) \
;         __builtin_amdgcn_global_load_lds((const unsigned*)((const char*)(gbase) + (voff)[_i]), (LAS unsigned*)(lds + (bufoff) + ldsw + _i * 8192), 16, 0, 0); } while (0)
; #define PG8_LDA(dst, b, h) do { _Pragma("unroll") for (int m = 0; m < 4; ++m) _Pragma("unroll") for (int k = 0; k < 2; ++k) dst[m][k] = *(const LAS bf16x8*)(lds + PG8_SA(b, h) + aoff + m * 2048 + k * 1024); } while (0)
; #define PG8_LDB(dst, b, h) do { _Pragma("unroll") for (int n = 0; n < 2; ++n) _Pragma("unroll") for (int k = 0; k < 2; ++k) dst[n][k] = *(const LAS bf16x8*)(lds + PG8_SB(b, h) + boff + n * 2048 + k * 1024); } while (0)
; #define PG8_MMA(ai, bj, At, Bt) do { __builtin_amdgcn_s_setprio(1); _Pragma("unroll") for (int m = 0; m < 4; ++m) _Pragma("unroll") for (int n = 0; n < 2; ++n) _Pragma("unroll") for (int k = 0; k < 2; ++k) \
;         acc[ai][bj][m][n] = __builtin_amdgcn_mfma_f32_16x16x32_bf16(Bt[n][k], At[m][k], acc[ai][bj][m][n], 0, 0, 0); __builtin_amdgcn_s_setprio(0); } while (0)
; #define PG8_WAIT_V(n) asm volatile("s_waitcnt vmcnt(" #n ")" ::: "memory")
; #define PG8_WAIT_L(n) asm volatile("s_waitcnt lgkmcnt(" #n ")" ::: "memory")
; #define PG8_BAR __builtin_amdgcn_s_barrier()
; #define PG8_SCHED __builtin_amdgcn_sched_barrier(0)
; template <class Epi>
; __device__ __forceinline__ void gemm_phase(LAS unsigned char* lds, const Gemm g, const StaticOrder& S, const Epi& E, const int tid) {
;     ...
;             PG8_STAGE(PG8_SB(0, 1), b2 + hstep, voffB);
;             PG8_WAIT_V(6); PG8_BAR; PG8_MMA(1, 1, At, B1); PG8_BAR;
;             PG8_LDB(B0, 1, 0); PG8_SCHED; PG8_LDA(At, 1, 0); PG8_STAGE(PG8_SA(0, 1), a2 + hstep, voffA);
;             PG8_WAIT_L(8); PG8_BAR; PG8_WAIT_L(0); PG8_MMA(0, 0, At, B0); PG8_BAR; PG8_SCHED;
;             PG8_LDB(B1, 1, 1); PG8_STAGE(PG8_SB(1, 0), b3, voffB);
;             PG8_BAR; PG8_WAIT_L(0); PG8_MMA(0, 1, At, B1); PG8_BAR;
;             PG8_LDA(At, 1, 1); PG8_STAGE(PG8_SA(1, 0), a3, voffA);
	s_add_u32 s48, s18, 0x80000
	s_addc_u32 s49, s19, 0
	s_add_i32 s45, s47, s26
	s_mov_b32 m0, s45
	s_nop 0
	global_load_lds_dwordx4 v0, s[48:49]
	s_add_i32 m0, s45, 0x2000
	s_nop 0
	global_load_lds_dwordx4 v134, s[48:49]
	s_waitcnt vmcnt(6)
	s_barrier
	v_mfma_f32_16x16x32_bf16 v[54:57], v[218:221], v[176:179], v[54:57]
	v_mfma_f32_16x16x32_bf16 v[50:53], v[226:229], v[176:179], v[50:53]
	v_mfma_f32_16x16x32_bf16 v[38:41], v[218:221], v[184:187], v[38:41]
	v_mfma_f32_16x16x32_bf16 v[34:37], v[226:229], v[184:187], v[34:37]
	v_mfma_f32_16x16x32_bf16 v[22:25], v[218:221], v[192:195], v[22:25]
	v_mfma_f32_16x16x32_bf16 v[18:21], v[226:229], v[192:195], v[18:21]
	v_mfma_f32_16x16x32_bf16 v[6:9], v[218:221], v[210:213], v[6:9]
	v_mfma_f32_16x16x32_bf16 v[2:5], v[226:229], v[210:213], v[2:5]
	v_mfma_f32_16x16x32_bf16 v[54:57], v[222:225], v[180:183], v[54:57]
	v_mfma_f32_16x16x32_bf16 v[50:53], v[230:233], v[180:183], v[50:53]
	v_mfma_f32_16x16x32_bf16 v[38:41], v[222:225], v[188:191], v[38:41]
	v_mfma_f32_16x16x32_bf16 v[34:37], v[230:233], v[188:191], v[34:37]
	v_mfma_f32_16x16x32_bf16 v[22:25], v[222:225], v[196:199], v[22:25]
	v_mfma_f32_16x16x32_bf16 v[18:21], v[230:233], v[196:199], v[18:21]
	v_mfma_f32_16x16x32_bf16 v[6:9], v[222:225], v[214:217], v[6:9]
	v_mfma_f32_16x16x32_bf16 v[2:5], v[230:233], v[214:217], v[2:5]
	s_add_i32 s45, 0, 0x18000
	v_add_u32_e32 v159, s45, v144
	s_barrier
	ds_read_b128 v[160:163], v159
	ds_read_b128 v[164:167], v159 offset:1024
	ds_read_b128 v[168:171], v159 offset:2048
	ds_read_b128 v[172:175], v159 offset:3072
	s_add_u32 s20, s20, 0x80000
	s_addc_u32 s21, s21, 0
	s_mov_b32 m0, s28
	ds_read_b128 v[176:179], v145 offset:32768
	ds_read_b128 v[180:183], v145 offset:33792
	ds_read_b128 v[184:187], v145 offset:34816
	ds_read_b128 v[188:191], v145 offset:35840
	ds_read_b128 v[192:195], v145 offset:36864
	ds_read_b128 v[196:199], v145 offset:37888
	ds_read_b128 v[210:213], v145 offset:38912
	ds_read_b128 v[214:217], v145 offset:39936
	global_load_lds_dwordx4 v130, s[20:21]
	s_mov_b32 m0, s29
	s_nop 0
	global_load_lds_dwordx4 v132, s[20:21]
	s_waitcnt lgkmcnt(8)
	s_barrier
	s_waitcnt lgkmcnt(0)
	v_mfma_f32_16x16x32_bf16 v[126:129], v[160:163], v[176:179], v[126:129]
	v_mfma_f32_16x16x32_bf16 v[122:125], v[168:171], v[176:179], v[122:125]
	v_mfma_f32_16x16x32_bf16 v[110:113], v[160:163], v[184:187], v[110:113]
	v_mfma_f32_16x16x32_bf16 v[106:109], v[168:171], v[184:187], v[106:109]
	v_mfma_f32_16x16x32_bf16 v[94:97], v[160:163], v[192:195], v[94:97]
	v_mfma_f32_16x16x32_bf16 v[90:93], v[168:171], v[192:195], v[90:93]
	v_mfma_f32_16x16x32_bf16 v[78:81], v[160:163], v[210:213], v[78:81]
	v_mfma_f32_16x16x32_bf16 v[74:77], v[168:171], v[210:213], v[74:77]
	v_mfma_f32_16x16x32_bf16 v[126:129], v[164:167], v[180:183], v[126:129]
	v_mfma_f32_16x16x32_bf16 v[122:125], v[172:175], v[180:183], v[122:125]
	v_mfma_f32_16x16x32_bf16 v[110:113], v[164:167], v[188:191], v[110:113]
	v_mfma_f32_16x16x32_bf16 v[106:109], v[172:175], v[188:191], v[106:109]
	v_mfma_f32_16x16x32_bf16 v[94:97], v[164:167], v[196:199], v[94:97]
	v_mfma_f32_16x16x32_bf16 v[90:93], v[172:175], v[196:199], v[90:93]
	v_mfma_f32_16x16x32_bf16 v[78:81], v[164:167], v[214:217], v[78:81]
	v_mfma_f32_16x16x32_bf16 v[74:77], v[172:175], v[214:217], v[74:77]
	s_barrier
	s_add_i32 s20, 0, 0x1c000
	s_add_i32 s21, s45, s26
	v_add_u32_e32 v159, s20, v144
	v_lshl_add_u64 v[140:141], v[140:141], 0, s[56:57]
	s_mov_b32 m0, s21
	ds_read_b128 v[218:221], v159
	ds_read_b128 v[222:225], v159 offset:1024
	ds_read_b128 v[226:229], v159 offset:2048
	ds_read_b128 v[230:233], v159 offset:3072
	global_load_lds_dwordx4 v[140:141], off
	v_lshl_add_u64 v[140:141], v[200:201], 0, s[56:57]
	s_add_i32 m0, s21, 0x2000
	s_nop 0
	global_load_lds_dwordx4 v[140:141], off
	s_barrier
	s_waitcnt lgkmcnt(0)
	v_mfma_f32_16x16x32_bf16 v[118:121], v[218:221], v[176:179], v[118:121]
	v_mfma_f32_16x16x32_bf16 v[114:117], v[226:229], v[176:179], v[114:117]
	v_mfma_f32_16x16x32_bf16 v[102:105], v[218:221], v[184:187], v[102:105]
	v_mfma_f32_16x16x32_bf16 v[98:101], v[226:229], v[184:187], v[98:101]
	v_mfma_f32_16x16x32_bf16 v[86:89], v[218:221], v[192:195], v[86:89]
	v_mfma_f32_16x16x32_bf16 v[82:85], v[226:229], v[192:195], v[82:85]
	v_mfma_f32_16x16x32_bf16 v[70:73], v[218:221], v[210:213], v[70:73]
	v_mfma_f32_16x16x32_bf16 v[66:69], v[226:229], v[210:213], v[66:69]
	v_mfma_f32_16x16x32_bf16 v[118:121], v[222:225], v[180:183], v[118:121]
	v_mfma_f32_16x16x32_bf16 v[114:117], v[230:233], v[180:183], v[114:117]
	v_mfma_f32_16x16x32_bf16 v[102:105], v[222:225], v[188:191], v[102:105]
	v_mfma_f32_16x16x32_bf16 v[98:101], v[230:233], v[188:191], v[98:101]
	v_mfma_f32_16x16x32_bf16 v[86:89], v[222:225], v[196:199], v[86:89]
	v_mfma_f32_16x16x32_bf16 v[82:85], v[230:233], v[196:199], v[82:85]
	v_mfma_f32_16x16x32_bf16 v[70:73], v[222:225], v[214:217], v[70:73]
	v_mfma_f32_16x16x32_bf16 v[66:69], v[230:233], v[214:217], v[66:69]
	s_mov_b32 m0, s35
	v_lshl_add_u64 v[140:141], v[234:235], 0, s[56:57]
	s_barrier
	ds_read_b128 v[176:179], v145 offset:49152
	ds_read_b128 v[180:183], v145 offset:50176
	ds_read_b128 v[184:187], v145 offset:51200
	ds_read_b128 v[188:191], v145 offset:52224
	ds_read_b128 v[192:195], v145 offset:53248
	ds_read_b128 v[196:199], v145 offset:54272
	ds_read_b128 v[210:213], v145 offset:55296
	ds_read_b128 v[214:217], v145 offset:56320
	global_load_lds_dwordx4 v[140:141], off
	v_lshl_add_u64 v[140:141], v[236:237], 0, s[56:57]
	s_mov_b32 m0, s36
	s_nop 0
	global_load_lds_dwordx4 v[140:141], off
	s_barrier
; __device__ __forceinline__ unsigned pk2(float lo, float hi) { f32x2 v = {lo, hi}; return __builtin_bit_cast(unsigned, __builtin_convertvector(v, bf16x2_t)); }
; #define PG8_STAGE(bufoff, gbase, voff) do { _Pragma("unroll") for (int _i = 0; _i < 2; ++_i) \
;         __builtin_amdgcn_global_load_lds((const unsigned*)((const char*)(gbase) + (voff)[_i]), (LAS unsigned*)(lds + (bufoff) + ldsw + _i * 8192), 16, 0, 0); } while (0)
; #define PG8_MMA(ai, bj, At, Bt) do { __builtin_amdgcn_s_setprio(1); _Pragma("unroll") for (int m = 0; m < 4; ++m) _Pragma("unroll") for (int n = 0; n < 2; ++n) _Pragma("unroll") for (int k = 0; k < 2; ++k) \
;         acc[ai][bj][m][n] = __builtin_amdgcn_mfma_f32_16x16x32_bf16(Bt[n][k], At[m][k], acc[ai][bj][m][n], 0, 0, 0); __builtin_amdgcn_s_setprio(0); } while (0)
; #define PG8_WAIT_V(n) asm volatile("s_waitcnt vmcnt(" #n ")" ::: "memory")
; #define PG8_WAIT_L(n) asm volatile("s_waitcnt lgkmcnt(" #n ")" ::: "memory")
; #define PG8_BAR __builtin_amdgcn_s_barrier()
;     __device__ __forceinline__ void operator()(const f32x4 (&acc)[2][2][4][2], const Unit& u, int wr, int wc, int fr, int fq) const {
;     ...
;         const int row0 = u.pm * BM + wr * 64 + fr, col0 = u.pn * BM + wc * 32 + 8 * fq;
; #pragma unroll
;         for (int ai = 0; ai < 2; ++ai)
; #pragma unroll
;             for (int m = 0; m < 4; ++m) {
;                 bf16_t* rowp = O + (size_t)(row0 + ai * HALF + m * 16) * ldc + col0;
; #pragma unroll
;                 for (int bj = 0; bj < 2; ++bj) {
;                     f32x4 v0 = acc[ai][bj][m][0], v1 = acc[ai][bj][m][1];
; #pragma unroll
;                     for (int j = 0; j < 4; ++j) { const float a = fmaxf(v0[j], 0.f), b = fmaxf(v1[j], 0.f); v0[j] = a * a; v1[j] = b * b; }
;                     u32x4 w; w.x = pk2(v0[0], v0[1]); w.y = pk2(v0[2], v0[3]); w.z = pk2(v1[0], v1[1]); w.w = pk2(v1[2], v1[3]);
;                     *(u32x4*)(rowp + bj * HALF) = w;
;                 }
; template <class Epi>
; __device__ __forceinline__ void gemm_phase(LAS unsigned char* lds, const Gemm g, const StaticOrder& S, const Epi& E, const int tid) {
;     ...
;             PG8_BAR; PG8_WAIT_L(0); PG8_MMA(1, 0, At, B0); PG8_BAR; PG8_SCHED;
;             PG8_STAGE(PG8_SB(1, 1), b3 + hstep, voffB);
;             PG8_WAIT_V(6); PG8_BAR; PG8_MMA(1, 1, At, B1); PG8_BAR;
;         }
;         E(acc, cur, wr, wc, fr, fq);
	s_waitcnt lgkmcnt(0)
	v_mfma_f32_16x16x32_bf16 v[62:65], v[160:163], v[176:179], v[62:65]
	v_mfma_f32_16x16x32_bf16 v[58:61], v[168:171], v[176:179], v[58:61]
	v_mfma_f32_16x16x32_bf16 v[46:49], v[160:163], v[184:187], v[46:49]
	v_mfma_f32_16x16x32_bf16 v[42:45], v[168:171], v[184:187], v[42:45]
	v_mfma_f32_16x16x32_bf16 v[30:33], v[160:163], v[192:195], v[30:33]
	v_mfma_f32_16x16x32_bf16 v[26:29], v[168:171], v[192:195], v[26:29]
	v_mfma_f32_16x16x32_bf16 v[14:17], v[160:163], v[210:213], v[14:17]
	v_mfma_f32_16x16x32_bf16 v[10:13], v[168:171], v[210:213], v[10:13]
	v_mfma_f32_16x16x32_bf16 v[62:65], v[164:167], v[180:183], v[62:65]
	v_mfma_f32_16x16x32_bf16 v[58:61], v[172:175], v[180:183], v[58:61]
	v_mfma_f32_16x16x32_bf16 v[46:49], v[164:167], v[188:191], v[46:49]
	v_mfma_f32_16x16x32_bf16 v[42:45], v[172:175], v[188:191], v[42:45]
	v_mfma_f32_16x16x32_bf16 v[30:33], v[164:167], v[196:199], v[30:33]
	v_mfma_f32_16x16x32_bf16 v[26:29], v[172:175], v[196:199], v[26:29]
	v_mfma_f32_16x16x32_bf16 v[14:17], v[164:167], v[214:217], v[14:17]
	v_mfma_f32_16x16x32_bf16 v[10:13], v[172:175], v[214:217], v[10:13]
	s_barrier
	s_add_i32 s44, s44, 2
	s_add_u32 s42, s42, 0x100
	s_addc_u32 s43, s43, 0
	s_add_u32 s16, s16, 0x100
	s_addc_u32 s17, s17, 0
	s_add_u32 s18, s18, 0x80080
	s_addc_u32 s19, s19, 0
	s_add_i32 s20, s20, s26
	s_mov_b32 m0, s20
	s_nop 0
	global_load_lds_dwordx4 v0, s[18:19]
	v_lshl_add_u64 v[140:141], s[18:19], 0, v[134:135]
	s_add_i32 m0, s20, 0x2000
	s_nop 0
	global_load_lds_dwordx4 v[140:141], off
	s_waitcnt vmcnt(6)
	s_barrier
	v_mfma_f32_16x16x32_bf16 v[54:57], v[218:221], v[176:179], v[54:57]
	v_mfma_f32_16x16x32_bf16 v[50:53], v[226:229], v[176:179], v[50:53]
	v_mfma_f32_16x16x32_bf16 v[38:41], v[218:221], v[184:187], v[38:41]
	v_mfma_f32_16x16x32_bf16 v[34:37], v[226:229], v[184:187], v[34:37]
	v_mfma_f32_16x16x32_bf16 v[22:25], v[218:221], v[192:195], v[22:25]
	v_mfma_f32_16x16x32_bf16 v[18:21], v[226:229], v[192:195], v[18:21]
	v_mfma_f32_16x16x32_bf16 v[6:9], v[218:221], v[210:213], v[6:9]
	v_mfma_f32_16x16x32_bf16 v[2:5], v[226:229], v[210:213], v[2:5]
	v_mfma_f32_16x16x32_bf16 v[54:57], v[222:225], v[180:183], v[54:57]
	v_mfma_f32_16x16x32_bf16 v[50:53], v[230:233], v[180:183], v[50:53]
	v_mfma_f32_16x16x32_bf16 v[38:41], v[222:225], v[188:191], v[38:41]
	v_mfma_f32_16x16x32_bf16 v[34:37], v[230:233], v[188:191], v[34:37]
	v_mfma_f32_16x16x32_bf16 v[22:25], v[222:225], v[196:199], v[22:25]
	v_mfma_f32_16x16x32_bf16 v[18:21], v[230:233], v[196:199], v[18:21]
	v_mfma_f32_16x16x32_bf16 v[6:9], v[222:225], v[214:217], v[6:9]
	v_mfma_f32_16x16x32_bf16 v[2:5], v[230:233], v[214:217], v[2:5]
	s_cmp_gt_u32 s44, 29
	s_barrier
	s_cbranch_scc0 .LBB0_84
	s_setprio 0
	v_mov_b32_e32 v141, v143
	v_mov_b32_e32 v140, v142
	s_lshl_b32 s7, s14, 8
	s_add_i32 s7, s7, s31
	v_add_u32_e32 v140, s7, v140
	s_lshl_b32 s7, s39, 8
	s_or_b32 s7, s7, s34
	v_lshl_add_u32 v160, v141, 3, s7
	v_ashrrev_i32_e32 v141, 31, v140
	v_lshlrev_b64 v[140:141], 14, v[140:141]
	v_max_f32_e32 v122, v122, v122
	v_max_f32_e32 v123, v123, v123
	v_ashrrev_i32_e32 v161, 31, v160
	v_lshl_add_u64 v[140:141], s[2:3], 0, v[140:141]
	v_max_f32_e32 v122, 0, v122
	v_max_f32_e32 v123, 0, v123
	v_lshl_add_u64 v[140:141], v[160:161], 1, v[140:141]
	v_pk_mul_f32 v[160:161], v[122:123], v[122:123]
	v_max_f32_e32 v123, v124, v124
	v_max_f32_e32 v126, v126, v126
	v_max_f32_e32 v127, v127, v127
	v_max_f32_e32 v122, v128, v128
	v_max_f32_e32 v124, 0, v123
	v_max_f32_e32 v123, v129, v129
	v_max_f32_e32 v125, v125, v125
	v_max_f32_e32 v126, 0, v126
	v_max_f32_e32 v127, 0, v127
	v_max_f32_e32 v122, 0, v122
	v_max_f32_e32 v123, 0, v123
	v_max_f32_e32 v125, 0, v125
	v_pk_mul_f32 v[126:127], v[126:127], v[126:127]
	v_pk_mul_f32 v[128:129], v[122:123], v[122:123]
	v_pk_mul_f32 v[162:163], v[124:125], v[124:125]
	v_max_f32_e32 v114, v114, v114
	v_max_f32_e32 v115, v115, v115
	v_cvt_pk_bf16_f32 v122, v126, v127
	v_cvt_pk_bf16_f32 v123, v128, v129
	v_cvt_pk_bf16_f32 v124, v160, v161
	v_cvt_pk_bf16_f32 v125, v162, v163
	v_max_f32_e32 v114, 0, v114
	v_max_f32_e32 v115, 0, v115
	global_store_dwordx4 v[140:141], v[122:125], off
	v_max_f32_e32 v118, v118, v118
	v_max_f32_e32 v119, v119, v119
	v_pk_mul_f32 v[122:123], v[114:115], v[114:115]
	v_max_f32_e32 v115, v116, v116
	v_max_f32_e32 v114, v120, v120
	v_max_f32_e32 v116, 0, v115
	v_max_f32_e32 v115, v121, v121
	v_max_f32_e32 v117, v117, v117
	v_max_f32_e32 v118, 0, v118
	v_max_f32_e32 v119, 0, v119
	v_max_f32_e32 v114, 0, v114
	v_max_f32_e32 v115, 0, v115
	v_max_f32_e32 v117, 0, v117
	v_pk_mul_f32 v[118:119], v[118:119], v[118:119]
	v_pk_mul_f32 v[120:121], v[114:115], v[114:115]
	v_pk_mul_f32 v[124:125], v[116:117], v[116:117]
	v_max_f32_e32 v106, v106, v106
	v_max_f32_e32 v107, v107, v107
	v_cvt_pk_bf16_f32 v114, v118, v119
	v_cvt_pk_bf16_f32 v115, v120, v121
	v_cvt_pk_bf16_f32 v116, v122, v123
	v_cvt_pk_bf16_f32 v117, v124, v125
	v_max_f32_e32 v106, 0, v106
	v_max_f32_e32 v107, 0, v107
	global_store_dwordx4 v[140:141], v[114:117], off offset:256
	v_max_f32_e32 v110, v110, v110
	v_max_f32_e32 v111, v111, v111
	v_pk_mul_f32 v[116:117], v[106:107], v[106:107]
	v_max_f32_e32 v107, v108, v108
	v_max_f32_e32 v110, 0, v110
	v_max_f32_e32 v111, 0, v111
	v_max_f32_e32 v106, v112, v112
	v_max_f32_e32 v108, 0, v107
	v_max_f32_e32 v107, v113, v113
	v_max_f32_e32 v109, v109, v109
	v_pk_mul_f32 v[110:111], v[110:111], v[110:111]
	v_max_f32_e32 v106, 0, v106
	v_max_f32_e32 v107, 0, v107
	v_max_f32_e32 v109, 0, v109
	s_mov_b32 s7, 0x40000
	v_pk_mul_f32 v[112:113], v[106:107], v[106:107]
	v_pk_mul_f32 v[118:119], v[108:109], v[108:109]
	v_cvt_pk_bf16_f32 v106, v110, v111
; __device__ __forceinline__ unsigned pk2(float lo, float hi) { f32x2 v = {lo, hi}; return __builtin_bit_cast(unsigned, __builtin_convertvector(v, bf16x2_t)); }
;     __device__ __forceinline__ void operator()(const f32x4 (&acc)[2][2][4][2], const Unit& u, int wr, int wc, int fr, int fq) const {
;     ...
;         for (int ai = 0; ai < 2; ++ai)
; #pragma unroll
;             for (int m = 0; m < 4; ++m) {
;                 bf16_t* rowp = O + (size_t)(row0 + ai * HALF + m * 16) * ldc + col0;
; #pragma unroll
;                 for (int bj = 0; bj < 2; ++bj) {
;                     f32x4 v0 = acc[ai][bj][m][0], v1 = acc[ai][bj][m][1];
; #pragma unroll
;                     for (int j = 0; j < 4; ++j) { const float a = fmaxf(v0[j], 0.f), b = fmaxf(v1[j], 0.f); v0[j] = a * a; v1[j] = b * b; }
;                     u32x4 w; w.x = pk2(v0[0], v0[1]); w.y = pk2(v0[2], v0[3]); w.z = pk2(v1[0], v1[1]); w.w = pk2(v1[2], v1[3]);
;                     *(u32x4*)(rowp + bj * HALF) = w;
;                 }
	v_add_co_u32_e32 v110, vcc, s7, v140
	v_max_f32_e32 v98, v98, v98
	v_max_f32_e32 v99, v99, v99
	v_cvt_pk_bf16_f32 v107, v112, v113
	v_cvt_pk_bf16_f32 v108, v116, v117
	v_cvt_pk_bf16_f32 v109, v118, v119
	v_addc_co_u32_e32 v111, vcc, 0, v141, vcc
	v_max_f32_e32 v98, 0, v98
	v_max_f32_e32 v99, 0, v99
	global_store_dwordx4 v[110:111], v[106:109], off
	v_max_f32_e32 v102, v102, v102
	v_max_f32_e32 v103, v103, v103
	v_pk_mul_f32 v[106:107], v[98:99], v[98:99]
	v_max_f32_e32 v99, v100, v100
	v_max_f32_e32 v98, v104, v104
	v_max_f32_e32 v100, 0, v99
	v_max_f32_e32 v99, v105, v105
	v_max_f32_e32 v101, v101, v101
	v_max_f32_e32 v102, 0, v102
	v_max_f32_e32 v103, 0, v103
	v_max_f32_e32 v98, 0, v98
	v_max_f32_e32 v99, 0, v99
	v_max_f32_e32 v101, 0, v101
	s_mov_b64 s[16:17], 0x40000
	v_pk_mul_f32 v[102:103], v[102:103], v[102:103]
	v_pk_mul_f32 v[104:105], v[98:99], v[98:99]
	v_pk_mul_f32 v[108:109], v[100:101], v[100:101]
	v_max_f32_e32 v90, v90, v90
	v_max_f32_e32 v91, v91, v91
	v_lshl_add_u64 v[114:115], v[140:141], 0, s[16:17]
	v_cvt_pk_bf16_f32 v98, v102, v103
	v_cvt_pk_bf16_f32 v99, v104, v105
	v_cvt_pk_bf16_f32 v100, v106, v107
	v_cvt_pk_bf16_f32 v101, v108, v109
	v_max_f32_e32 v90, 0, v90
	v_max_f32_e32 v91, 0, v91
	global_store_dwordx4 v[114:115], v[98:101], off offset:256
	v_max_f32_e32 v94, v94, v94
	v_max_f32_e32 v95, v95, v95
	v_pk_mul_f32 v[100:101], v[90:91], v[90:91]
	v_max_f32_e32 v91, v92, v92
	v_max_f32_e32 v94, 0, v94
	v_max_f32_e32 v95, 0, v95
	v_max_f32_e32 v90, v96, v96
	v_max_f32_e32 v92, 0, v91
	v_max_f32_e32 v91, v97, v97
	v_max_f32_e32 v93, v93, v93
	v_pk_mul_f32 v[94:95], v[94:95], v[94:95]
	v_max_f32_e32 v90, 0, v90
	v_max_f32_e32 v91, 0, v91
	v_max_f32_e32 v93, 0, v93
	s_mov_b32 s7, 0x80000
	v_pk_mul_f32 v[96:97], v[90:91], v[90:91]
	v_pk_mul_f32 v[102:103], v[92:93], v[92:93]
	v_cvt_pk_bf16_f32 v90, v94, v95
	v_add_co_u32_e32 v94, vcc, s7, v140
	v_max_f32_e32 v82, v82, v82
	v_max_f32_e32 v83, v83, v83
	v_cvt_pk_bf16_f32 v91, v96, v97
	v_cvt_pk_bf16_f32 v92, v100, v101
	v_cvt_pk_bf16_f32 v93, v102, v103
	v_addc_co_u32_e32 v95, vcc, 0, v141, vcc
	v_max_f32_e32 v82, 0, v82
	v_max_f32_e32 v83, 0, v83
	global_store_dwordx4 v[94:95], v[90:93], off
	v_max_f32_e32 v86, v86, v86
	v_max_f32_e32 v87, v87, v87
	v_pk_mul_f32 v[90:91], v[82:83], v[82:83]
	v_max_f32_e32 v83, v84, v84
	v_max_f32_e32 v82, v88, v88
	v_max_f32_e32 v84, 0, v83
	v_max_f32_e32 v83, v89, v89
	v_max_f32_e32 v85, v85, v85
	v_max_f32_e32 v86, 0, v86
	v_max_f32_e32 v87, 0, v87
	v_max_f32_e32 v82, 0, v82
	v_max_f32_e32 v83, 0, v83
	v_max_f32_e32 v85, 0, v85
	s_mov_b64 s[16:17], 0x80000
	v_pk_mul_f32 v[86:87], v[86:87], v[86:87]
	v_pk_mul_f32 v[88:89], v[82:83], v[82:83]
	v_pk_mul_f32 v[92:93], v[84:85], v[84:85]
	v_max_f32_e32 v74, v74, v74
	v_max_f32_e32 v75, v75, v75
	v_lshl_add_u64 v[98:99], v[140:141], 0, s[16:17]
	v_cvt_pk_bf16_f32 v82, v86, v87
	v_cvt_pk_bf16_f32 v83, v88, v89
	v_cvt_pk_bf16_f32 v84, v90, v91
	v_cvt_pk_bf16_f32 v85, v92, v93
	v_max_f32_e32 v74, 0, v74
	v_max_f32_e32 v75, 0, v75
	global_store_dwordx4 v[98:99], v[82:85], off offset:256
	v_max_f32_e32 v78, v78, v78
	v_max_f32_e32 v79, v79, v79
	v_pk_mul_f32 v[84:85], v[74:75], v[74:75]
	v_max_f32_e32 v75, v76, v76
	v_max_f32_e32 v78, 0, v78
	v_max_f32_e32 v79, 0, v79
	v_max_f32_e32 v74, v80, v80
	v_max_f32_e32 v76, 0, v75
	v_max_f32_e32 v75, v81, v81
	v_max_f32_e32 v77, v77, v77
	v_pk_mul_f32 v[78:79], v[78:79], v[78:79]
	v_max_f32_e32 v74, 0, v74
	v_max_f32_e32 v75, 0, v75
	v_max_f32_e32 v77, 0, v77
	s_mov_b32 s7, 0xc0000
	v_pk_mul_f32 v[80:81], v[74:75], v[74:75]
	v_pk_mul_f32 v[86:87], v[76:77], v[76:77]
	v_cvt_pk_bf16_f32 v74, v78, v79
	v_add_co_u32_e32 v78, vcc, s7, v140
	v_max_f32_e32 v66, v66, v66
	v_max_f32_e32 v67, v67, v67
	v_cvt_pk_bf16_f32 v75, v80, v81
	v_cvt_pk_bf16_f32 v76, v84, v85
	v_cvt_pk_bf16_f32 v77, v86, v87
	v_addc_co_u32_e32 v79, vcc, 0, v141, vcc
	v_max_f32_e32 v66, 0, v66
	v_max_f32_e32 v67, 0, v67
	global_store_dwordx4 v[78:79], v[74:77], off
	v_max_f32_e32 v70, v70, v70
	v_max_f32_e32 v71, v71, v71
	v_pk_mul_f32 v[74:75], v[66:67], v[66:67]
	v_max_f32_e32 v67, v68, v68
	v_max_f32_e32 v66, v72, v72
	v_max_f32_e32 v68, 0, v67
	v_max_f32_e32 v67, v73, v73
	v_max_f32_e32 v69, v69, v69
	v_max_f32_e32 v70, 0, v70
	v_max_f32_e32 v71, 0, v71
	v_max_f32_e32 v66, 0, v66
	v_max_f32_e32 v67, 0, v67
	v_max_f32_e32 v69, 0, v69
	s_mov_b64 s[16:17], 0xc0000
	v_pk_mul_f32 v[70:71], v[70:71], v[70:71]
	v_pk_mul_f32 v[72:73], v[66:67], v[66:67]
	v_pk_mul_f32 v[76:77], v[68:69], v[68:69]
	v_max_f32_e32 v58, v58, v58
	v_max_f32_e32 v59, v59, v59
	v_lshl_add_u64 v[82:83], v[140:141], 0, s[16:17]
	v_cvt_pk_bf16_f32 v66, v70, v71
	v_cvt_pk_bf16_f32 v67, v72, v73
	v_cvt_pk_bf16_f32 v68, v74, v75
	v_cvt_pk_bf16_f32 v69, v76, v77
	v_max_f32_e32 v58, 0, v58
	v_max_f32_e32 v59, 0, v59
	global_store_dwordx4 v[82:83], v[66:69], off offset:256
	v_max_f32_e32 v62, v62, v62
	v_max_f32_e32 v63, v63, v63
	v_pk_mul_f32 v[68:69], v[58:59], v[58:59]
	v_max_f32_e32 v59, v60, v60
	v_max_f32_e32 v62, 0, v62
	v_max_f32_e32 v63, 0, v63
	v_max_f32_e32 v58, v64, v64
	v_max_f32_e32 v60, 0, v59
	v_max_f32_e32 v59, v65, v65
	v_max_f32_e32 v61, v61, v61
	v_pk_mul_f32 v[62:63], v[62:63], v[62:63]
	v_max_f32_e32 v58, 0, v58
	v_max_f32_e32 v59, 0, v59
	v_max_f32_e32 v61, 0, v61
	s_mov_b32 s7, 0x200000
	v_pk_mul_f32 v[64:65], v[58:59], v[58:59]
	v_pk_mul_f32 v[70:71], v[60:61], v[60:61]
	v_cvt_pk_bf16_f32 v58, v62, v63
	v_add_co_u32_e32 v62, vcc, s7, v140
	v_max_f32_e32 v50, v50, v50
	v_max_f32_e32 v51, v51, v51
	v_cvt_pk_bf16_f32 v59, v64, v65
	v_cvt_pk_bf16_f32 v60, v68, v69
	v_cvt_pk_bf16_f32 v61, v70, v71
; __device__ __forceinline__ unsigned pk2(float lo, float hi) { f32x2 v = {lo, hi}; return __builtin_bit_cast(unsigned, __builtin_convertvector(v, bf16x2_t)); }
; #define PG8_WAIT_V(n) asm volatile("s_waitcnt vmcnt(" #n ")" ::: "memory")
; #define PG8_BAR __builtin_amdgcn_s_barrier()
;     __device__ __forceinline__ void operator()(const f32x4 (&acc)[2][2][4][2], const Unit& u, int wr, int wc, int fr, int fq) const {
;     ...
;         for (int ai = 0; ai < 2; ++ai)
; #pragma unroll
;             for (int m = 0; m < 4; ++m) {
;                 bf16_t* rowp = O + (size_t)(row0 + ai * HALF + m * 16) * ldc + col0;
; #pragma unroll
;                 for (int bj = 0; bj < 2; ++bj) {
;                     f32x4 v0 = acc[ai][bj][m][0], v1 = acc[ai][bj][m][1];
; #pragma unroll
;                     for (int j = 0; j < 4; ++j) { const float a = fmaxf(v0[j], 0.f), b = fmaxf(v1[j], 0.f); v0[j] = a * a; v1[j] = b * b; }
;                     u32x4 w; w.x = pk2(v0[0], v0[1]); w.y = pk2(v0[2], v0[3]); w.z = pk2(v1[0], v1[1]); w.w = pk2(v1[2], v1[3]);
;                     *(u32x4*)(rowp + bj * HALF) = w;
;                 }
; template <class Epi>
; __device__ __forceinline__ void gemm_phase(LAS unsigned char* lds, const Gemm g, const StaticOrder& S, const Epi& E, const int tid) {
;     ...
;         E(acc, cur, wr, wc, fr, fq);
;         if (!has_next) break;
; #pragma unroll
;         for (int a = 0; a < 2; ++a)
; #pragma unroll
;             for (int b = 0; b < 2; ++b)
; #pragma unroll
;                 for (int m = 0; m < 4; ++m)
; #pragma unroll
;                     for (int n = 0; n < 2; ++n) acc[a][b][m][n] = (f32x4){0.f, 0.f, 0.f, 0.f};
;         cur = nxt; cA = nA; cB = nB; ++ui;
;     }
;     PG8_WAIT_V(0);
;     if (wr == 0) PG8_BAR;
;     PG8_BAR;
	v_addc_co_u32_e32 v63, vcc, 0, v141, vcc
	v_max_f32_e32 v50, 0, v50
	v_max_f32_e32 v51, 0, v51
	global_store_dwordx4 v[62:63], v[58:61], off
	v_max_f32_e32 v54, v54, v54
	v_max_f32_e32 v55, v55, v55
	v_pk_mul_f32 v[58:59], v[50:51], v[50:51]
	v_max_f32_e32 v51, v52, v52
	v_max_f32_e32 v50, v56, v56
	v_max_f32_e32 v52, 0, v51
	v_max_f32_e32 v51, v57, v57
	v_max_f32_e32 v53, v53, v53
	v_max_f32_e32 v54, 0, v54
	v_max_f32_e32 v55, 0, v55
	v_max_f32_e32 v50, 0, v50
	v_max_f32_e32 v51, 0, v51
	v_max_f32_e32 v53, 0, v53
	s_mov_b64 s[16:17], 0x200000
	v_pk_mul_f32 v[54:55], v[54:55], v[54:55]
	v_pk_mul_f32 v[56:57], v[50:51], v[50:51]
	v_pk_mul_f32 v[60:61], v[52:53], v[52:53]
	v_max_f32_e32 v42, v42, v42
	v_max_f32_e32 v43, v43, v43
	v_lshl_add_u64 v[66:67], v[140:141], 0, s[16:17]
	v_cvt_pk_bf16_f32 v50, v54, v55
	v_cvt_pk_bf16_f32 v51, v56, v57
	v_cvt_pk_bf16_f32 v52, v58, v59
	v_cvt_pk_bf16_f32 v53, v60, v61
	v_max_f32_e32 v42, 0, v42
	v_max_f32_e32 v43, 0, v43
	global_store_dwordx4 v[66:67], v[50:53], off offset:256
	v_max_f32_e32 v46, v46, v46
	v_max_f32_e32 v47, v47, v47
	v_pk_mul_f32 v[52:53], v[42:43], v[42:43]
	v_max_f32_e32 v43, v44, v44
	v_max_f32_e32 v46, 0, v46
	v_max_f32_e32 v47, 0, v47
	v_max_f32_e32 v42, v48, v48
	v_max_f32_e32 v44, 0, v43
	v_max_f32_e32 v43, v49, v49
	v_max_f32_e32 v45, v45, v45
	v_pk_mul_f32 v[46:47], v[46:47], v[46:47]
	v_max_f32_e32 v42, 0, v42
	v_max_f32_e32 v43, 0, v43
	v_max_f32_e32 v45, 0, v45
	s_mov_b32 s7, 0x240000
	v_pk_mul_f32 v[48:49], v[42:43], v[42:43]
	v_pk_mul_f32 v[54:55], v[44:45], v[44:45]
	v_cvt_pk_bf16_f32 v42, v46, v47
	v_add_co_u32_e32 v46, vcc, s7, v140
	v_max_f32_e32 v34, v34, v34
	v_max_f32_e32 v35, v35, v35
	v_cvt_pk_bf16_f32 v43, v48, v49
	v_cvt_pk_bf16_f32 v44, v52, v53
	v_cvt_pk_bf16_f32 v45, v54, v55
	v_addc_co_u32_e32 v47, vcc, 0, v141, vcc
	v_max_f32_e32 v34, 0, v34
	v_max_f32_e32 v35, 0, v35
	global_store_dwordx4 v[46:47], v[42:45], off
	v_max_f32_e32 v38, v38, v38
	v_max_f32_e32 v39, v39, v39
	v_pk_mul_f32 v[42:43], v[34:35], v[34:35]
	v_max_f32_e32 v35, v36, v36
	v_max_f32_e32 v34, v40, v40
	v_max_f32_e32 v36, 0, v35
	v_max_f32_e32 v35, v41, v41
	v_max_f32_e32 v37, v37, v37
	v_max_f32_e32 v38, 0, v38
	v_max_f32_e32 v39, 0, v39
	v_max_f32_e32 v34, 0, v34
	v_max_f32_e32 v35, 0, v35
	v_max_f32_e32 v37, 0, v37
	s_mov_b64 s[16:17], 0x240000
	v_pk_mul_f32 v[38:39], v[38:39], v[38:39]
	v_pk_mul_f32 v[40:41], v[34:35], v[34:35]
	v_pk_mul_f32 v[44:45], v[36:37], v[36:37]
	v_max_f32_e32 v26, v26, v26
	v_max_f32_e32 v27, v27, v27
	v_lshl_add_u64 v[50:51], v[140:141], 0, s[16:17]
	v_cvt_pk_bf16_f32 v34, v38, v39
	v_cvt_pk_bf16_f32 v35, v40, v41
	v_cvt_pk_bf16_f32 v36, v42, v43
	v_cvt_pk_bf16_f32 v37, v44, v45
	v_max_f32_e32 v26, 0, v26
	v_max_f32_e32 v27, 0, v27
	global_store_dwordx4 v[50:51], v[34:37], off offset:256
	v_max_f32_e32 v30, v30, v30
	v_max_f32_e32 v31, v31, v31
	v_pk_mul_f32 v[36:37], v[26:27], v[26:27]
	v_max_f32_e32 v27, v28, v28
	v_max_f32_e32 v30, 0, v30
	v_max_f32_e32 v31, 0, v31
	v_max_f32_e32 v26, v32, v32
	v_max_f32_e32 v28, 0, v27
	v_max_f32_e32 v27, v33, v33
	v_max_f32_e32 v29, v29, v29
	v_pk_mul_f32 v[30:31], v[30:31], v[30:31]
	v_max_f32_e32 v26, 0, v26
	v_max_f32_e32 v27, 0, v27
	v_max_f32_e32 v29, 0, v29
	s_mov_b32 s7, 0x280000
	v_pk_mul_f32 v[32:33], v[26:27], v[26:27]
	v_pk_mul_f32 v[38:39], v[28:29], v[28:29]
	v_cvt_pk_bf16_f32 v26, v30, v31
	v_add_co_u32_e32 v30, vcc, s7, v140
	v_max_f32_e32 v18, v18, v18
	v_max_f32_e32 v19, v19, v19
	v_cvt_pk_bf16_f32 v27, v32, v33
	v_cvt_pk_bf16_f32 v28, v36, v37
	v_cvt_pk_bf16_f32 v29, v38, v39
	v_addc_co_u32_e32 v31, vcc, 0, v141, vcc
	v_max_f32_e32 v18, 0, v18
	v_max_f32_e32 v19, 0, v19
	global_store_dwordx4 v[30:31], v[26:29], off
	v_max_f32_e32 v22, v22, v22
	v_max_f32_e32 v23, v23, v23
	v_pk_mul_f32 v[26:27], v[18:19], v[18:19]
	v_max_f32_e32 v19, v20, v20
	v_max_f32_e32 v18, v24, v24
	v_max_f32_e32 v20, 0, v19
	v_max_f32_e32 v19, v25, v25
	v_max_f32_e32 v21, v21, v21
	v_max_f32_e32 v22, 0, v22
	v_max_f32_e32 v23, 0, v23
	v_max_f32_e32 v18, 0, v18
	v_max_f32_e32 v19, 0, v19
	v_max_f32_e32 v21, 0, v21
	s_mov_b64 s[16:17], 0x280000
	v_pk_mul_f32 v[22:23], v[22:23], v[22:23]
	v_pk_mul_f32 v[24:25], v[18:19], v[18:19]
	v_pk_mul_f32 v[28:29], v[20:21], v[20:21]
	v_max_f32_e32 v10, v10, v10
	v_max_f32_e32 v11, v11, v11
	v_lshl_add_u64 v[34:35], v[140:141], 0, s[16:17]
	v_cvt_pk_bf16_f32 v18, v22, v23
	v_cvt_pk_bf16_f32 v19, v24, v25
	v_cvt_pk_bf16_f32 v20, v26, v27
	v_cvt_pk_bf16_f32 v21, v28, v29
	v_max_f32_e32 v10, 0, v10
	v_max_f32_e32 v11, 0, v11
	global_store_dwordx4 v[34:35], v[18:21], off offset:256
	v_max_f32_e32 v14, v14, v14
	v_max_f32_e32 v15, v15, v15
	v_pk_mul_f32 v[20:21], v[10:11], v[10:11]
	v_max_f32_e32 v11, v12, v12
	v_max_f32_e32 v14, 0, v14
	v_max_f32_e32 v15, 0, v15
	v_max_f32_e32 v10, v16, v16
	v_max_f32_e32 v12, 0, v11
	v_max_f32_e32 v11, v17, v17
	v_max_f32_e32 v13, v13, v13
	v_pk_mul_f32 v[14:15], v[14:15], v[14:15]
	v_max_f32_e32 v10, 0, v10
	v_max_f32_e32 v11, 0, v11
	v_max_f32_e32 v13, 0, v13
	s_mov_b32 s7, 0x2c0000
	v_pk_mul_f32 v[16:17], v[10:11], v[10:11]
	v_pk_mul_f32 v[22:23], v[12:13], v[12:13]
	v_cvt_pk_bf16_f32 v10, v14, v15
	v_add_co_u32_e32 v14, vcc, s7, v140
	v_max_f32_e32 v2, v2, v2
	v_max_f32_e32 v3, v3, v3
	v_cvt_pk_bf16_f32 v11, v16, v17
	v_cvt_pk_bf16_f32 v12, v20, v21
	v_cvt_pk_bf16_f32 v13, v22, v23
	v_addc_co_u32_e32 v15, vcc, 0, v141, vcc
	v_max_f32_e32 v2, 0, v2
	v_max_f32_e32 v3, 0, v3
	global_store_dwordx4 v[14:15], v[10:13], off
	v_max_f32_e32 v6, v6, v6
	v_max_f32_e32 v7, v7, v7
	v_pk_mul_f32 v[10:11], v[2:3], v[2:3]
	v_max_f32_e32 v3, v4, v4
	v_max_f32_e32 v2, v8, v8
	v_max_f32_e32 v4, 0, v3
	v_max_f32_e32 v3, v9, v9
	v_max_f32_e32 v5, v5, v5
	v_max_f32_e32 v6, 0, v6
	v_max_f32_e32 v7, 0, v7
	v_max_f32_e32 v2, 0, v2
	v_max_f32_e32 v3, 0, v3
	v_max_f32_e32 v5, 0, v5
	s_mov_b64 s[16:17], 0x2c0000
	v_pk_mul_f32 v[6:7], v[6:7], v[6:7]
	v_pk_mul_f32 v[8:9], v[2:3], v[2:3]
	v_pk_mul_f32 v[12:13], v[4:5], v[4:5]
	v_lshl_add_u64 v[18:19], v[140:141], 0, s[16:17]
	v_cvt_pk_bf16_f32 v2, v6, v7
	v_cvt_pk_bf16_f32 v3, v8, v9
	v_cvt_pk_bf16_f32 v4, v10, v11
	v_cvt_pk_bf16_f32 v5, v12, v13
	s_and_b64 vcc, exec, s[4:5]
	s_mov_b32 s39, s6
	s_mov_b32 s14, s8
	s_mov_b64 s[16:17], s[12:13]
	s_mov_b64 s[18:19], s[10:11]
	global_store_dwordx4 v[18:19], v[2:5], off offset:256
	s_cbranch_vccz .LBB0_77
	s_waitcnt vmcnt(0)
	s_cmpk_gt_u32 s0, 0xff
	s_cbranch_scc1 .LBB0_88
	s_barrier

; #define PG8_STAGE(bufoff, gbase, voff) do { _Pragma("unroll") for (int _i = 0; _i < 2; ++_i) \
;         __builtin_amdgcn_global_load_lds((const unsigned*)((const char*)(gbase) + (voff)[_i]), (LAS unsigned*)(lds + (bufoff) + ldsw + _i * 8192), 16, 0, 0); } while (0)
; #define PG8_LDA(dst, b, h) do { _Pragma("unroll") for (int m = 0; m < 4; ++m) _Pragma("unroll") for (int k = 0; k < 2; ++k) dst[m][k] = *(const LAS bf16x8*)(lds + PG8_SA(b, h) + aoff + m * 2048 + k * 1024); } while (0)
; #define PG8_LDB(dst, b, h) do { _Pragma("unroll") for (int n = 0; n < 2; ++n) _Pragma("unroll") for (int k = 0; k < 2; ++k) dst[n][k] = *(const LAS bf16x8*)(lds + PG8_SB(b, h) + boff + n * 2048 + k * 1024); } while (0)
; #define PG8_MMA(ai, bj, At, Bt) do { __builtin_amdgcn_s_setprio(1); _Pragma("unroll") for (int m = 0; m < 4; ++m) _Pragma("unroll") for (int n = 0; n < 2; ++n) _Pragma("unroll") for (int k = 0; k < 2; ++k) \
;         acc[ai][bj][m][n] = __builtin_amdgcn_mfma_f32_16x16x32_bf16(Bt[n][k], At[m][k], acc[ai][bj][m][n], 0, 0, 0); __builtin_amdgcn_s_setprio(0); } while (0)
; #define PG8_WAIT_V(n) asm volatile("s_waitcnt vmcnt(" #n ")" ::: "memory")
; #define PG8_WAIT_L(n) asm volatile("s_waitcnt lgkmcnt(" #n ")" ::: "memory")
; #define PG8_BAR __builtin_amdgcn_s_barrier()
; template <class Epi>
; __device__ __forceinline__ void gemm_phase(LAS unsigned char* lds, const Gemm g, const StaticOrder& S, const Epi& E, const int tid) {
;     ...
;             const bool last = (t == nt - 2);
;             const char* a1 = cA + (size_t)(t + 1) * kstep;
;             const char* a2 = last ? nA : cA + (size_t)(t + 2) * kstep; const char* b2 = last ? nB : cB + (size_t)(t + 2) * kstep;
;             const char* a3 = a2 + kstep; const char* b3 = b2 + kstep;
;             PG8_LDB(B0, 0, 0); PG8_SCHED; PG8_LDA(At, 0, 0); PG8_STAGE(PG8_SA(1, 1), a1 + hstep, voffA);
;             PG8_WAIT_L(8); PG8_BAR; PG8_WAIT_L(0); PG8_MMA(0, 0, At, B0); PG8_BAR; PG8_SCHED;
;             PG8_LDB(B1, 0, 1); PG8_STAGE(PG8_SB(0, 0), b2, voffB);
;             PG8_BAR; PG8_WAIT_L(0); PG8_MMA(0, 1, At, B1); PG8_BAR;
;             PG8_LDA(At, 0, 1); PG8_STAGE(PG8_SA(0, 0), a2, voffA);
;             PG8_BAR; PG8_WAIT_L(0); PG8_MMA(1, 0, At, B0); PG8_BAR; PG8_SCHED;
;             PG8_STAGE(PG8_SB(0, 1), b2 + hstep, voffB);
;             PG8_WAIT_V(6); PG8_BAR; PG8_MMA(1, 1, At, B1); PG8_BAR;
.Lgprio3:
.LBB0_119:
	s_add_u32 s20, s18, 0xfff80080
	s_addc_u32 s21, s19, -1
	s_add_i32 s50, 0, 0x10000
	v_add_u32_e32 v62, s50, v173
	ds_read_b128 v[42:45], v62
	ds_read_b128 v[46:49], v62 offset:1024
	ds_read_b128 v[58:61], v62 offset:2048
	ds_read_b128 v[62:65], v62 offset:3072
	s_cmp_eq_u32 s49, 28
	s_cselect_b32 s23, s13, s21
	s_cselect_b32 s22, s44, s20
	s_cselect_b32 s21, s11, s48
	s_cselect_b32 s20, s45, s47
	s_add_i32 m0, s3, 0xc000
	ds_read_b128 v[176:179], v174
	ds_read_b128 v[180:183], v174 offset:1024
	ds_read_b128 v[184:187], v174 offset:2048
	ds_read_b128 v[188:191], v174 offset:3072
	ds_read_b128 v[192:195], v174 offset:4096
	ds_read_b128 v[196:199], v174 offset:5120
	ds_read_b128 v[210:213], v174 offset:6144
	ds_read_b128 v[214:217], v174 offset:7168
	global_load_lds_dwordx4 v168, s[18:19]
	v_lshl_add_u64 v[170:171], s[18:19], 0, v[166:167]
	s_add_i32 m0, s3, 0xe000
	s_nop 0
	global_load_lds_dwordx4 v[170:171], off
	s_waitcnt lgkmcnt(8)
	s_barrier
	s_waitcnt lgkmcnt(0)
	v_mfma_f32_16x16x32_bf16 v[142:145], v[42:45], v[176:179], v[142:145]
	v_mfma_f32_16x16x32_bf16 v[138:141], v[58:61], v[176:179], v[138:141]
	v_mfma_f32_16x16x32_bf16 v[126:129], v[42:45], v[184:187], v[126:129]
	v_mfma_f32_16x16x32_bf16 v[122:125], v[58:61], v[184:187], v[122:125]
	v_mfma_f32_16x16x32_bf16 v[110:113], v[42:45], v[192:195], v[110:113]
	v_mfma_f32_16x16x32_bf16 v[106:109], v[58:61], v[192:195], v[106:109]
	v_mfma_f32_16x16x32_bf16 v[94:97], v[42:45], v[210:213], v[94:97]
	v_mfma_f32_16x16x32_bf16 v[90:93], v[58:61], v[210:213], v[90:93]
	v_mfma_f32_16x16x32_bf16 v[142:145], v[46:49], v[180:183], v[142:145]
	v_mfma_f32_16x16x32_bf16 v[138:141], v[62:65], v[180:183], v[138:141]
	v_mfma_f32_16x16x32_bf16 v[126:129], v[46:49], v[188:191], v[126:129]
	v_mfma_f32_16x16x32_bf16 v[122:125], v[62:65], v[188:191], v[122:125]
	v_mfma_f32_16x16x32_bf16 v[110:113], v[46:49], v[196:199], v[110:113]
	v_mfma_f32_16x16x32_bf16 v[106:109], v[62:65], v[196:199], v[106:109]
	v_mfma_f32_16x16x32_bf16 v[94:97], v[46:49], v[214:217], v[94:97]
	v_mfma_f32_16x16x32_bf16 v[90:93], v[62:65], v[214:217], v[90:93]
	s_barrier
	s_add_i32 s54, 0, 0x14000
	v_add_u32_e32 v170, s54, v173
	s_add_i32 s50, s50, s31
	ds_read_b128 v[218:221], v170
	ds_read_b128 v[222:225], v170 offset:1024
	ds_read_b128 v[226:229], v170 offset:2048
	ds_read_b128 v[230:233], v170 offset:3072
	v_lshl_add_u64 v[170:171], s[20:21], 0, v[0:1]
	s_mov_b32 m0, s50
	v_lshl_add_u64 v[200:201], s[20:21], 0, v[164:165]
	global_load_lds_dwordx4 v[170:171], off
	s_add_i32 m0, s50, 0x2000
	s_nop 0
	global_load_lds_dwordx4 v[200:201], off
	s_barrier
	s_waitcnt lgkmcnt(0)
	v_mfma_f32_16x16x32_bf16 v[134:137], v[218:221], v[176:179], v[134:137]
	v_mfma_f32_16x16x32_bf16 v[130:133], v[226:229], v[176:179], v[130:133]
	v_mfma_f32_16x16x32_bf16 v[118:121], v[218:221], v[184:187], v[118:121]
	v_mfma_f32_16x16x32_bf16 v[114:117], v[226:229], v[184:187], v[114:117]
	v_mfma_f32_16x16x32_bf16 v[102:105], v[218:221], v[192:195], v[102:105]
	v_mfma_f32_16x16x32_bf16 v[98:101], v[226:229], v[192:195], v[98:101]
	v_mfma_f32_16x16x32_bf16 v[86:89], v[218:221], v[210:213], v[86:89]
	v_mfma_f32_16x16x32_bf16 v[82:85], v[226:229], v[210:213], v[82:85]
	v_mfma_f32_16x16x32_bf16 v[134:137], v[222:225], v[180:183], v[134:137]
	v_mfma_f32_16x16x32_bf16 v[130:133], v[230:233], v[180:183], v[130:133]
	v_mfma_f32_16x16x32_bf16 v[118:121], v[222:225], v[188:191], v[118:121]
	v_mfma_f32_16x16x32_bf16 v[114:117], v[230:233], v[188:191], v[114:117]
	v_mfma_f32_16x16x32_bf16 v[102:105], v[222:225], v[196:199], v[102:105]
	v_mfma_f32_16x16x32_bf16 v[98:101], v[230:233], v[196:199], v[98:101]
	v_mfma_f32_16x16x32_bf16 v[86:89], v[222:225], v[214:217], v[86:89]
	v_mfma_f32_16x16x32_bf16 v[82:85], v[230:233], v[214:217], v[82:85]
	s_mov_b32 m0, s3
	v_lshl_add_u64 v[234:235], s[22:23], 0, v[160:161]
	s_barrier
	ds_read_b128 v[176:179], v174 offset:16384
	ds_read_b128 v[180:183], v174 offset:17408
	ds_read_b128 v[184:187], v174 offset:18432
	ds_read_b128 v[188:191], v174 offset:19456
	ds_read_b128 v[192:195], v174 offset:20480
	ds_read_b128 v[196:199], v174 offset:21504
	ds_read_b128 v[210:213], v174 offset:22528
	ds_read_b128 v[214:217], v174 offset:23552
	global_load_lds_dwordx4 v[234:235], off
	v_lshl_add_u64 v[236:237], s[22:23], 0, v[162:163]
	s_mov_b32 m0, s34
	s_nop 0
	global_load_lds_dwordx4 v[236:237], off
	s_barrier
	s_waitcnt lgkmcnt(0)
	v_mfma_f32_16x16x32_bf16 v[78:81], v[42:45], v[176:179], v[78:81]
	v_mfma_f32_16x16x32_bf16 v[74:77], v[58:61], v[176:179], v[74:77]
	v_mfma_f32_16x16x32_bf16 v[54:57], v[42:45], v[184:187], v[54:57]
	v_mfma_f32_16x16x32_bf16 v[50:53], v[58:61], v[184:187], v[50:53]
	v_mfma_f32_16x16x32_bf16 v[30:33], v[42:45], v[192:195], v[30:33]
	v_mfma_f32_16x16x32_bf16 v[26:29], v[58:61], v[192:195], v[26:29]
	v_mfma_f32_16x16x32_bf16 v[14:17], v[42:45], v[210:213], v[14:17]
	v_mfma_f32_16x16x32_bf16 v[10:13], v[58:61], v[210:213], v[10:13]
	v_mfma_f32_16x16x32_bf16 v[78:81], v[46:49], v[180:183], v[78:81]
	v_mfma_f32_16x16x32_bf16 v[74:77], v[62:65], v[180:183], v[74:77]
	v_mfma_f32_16x16x32_bf16 v[54:57], v[46:49], v[188:191], v[54:57]
	v_mfma_f32_16x16x32_bf16 v[50:53], v[62:65], v[188:191], v[50:53]
	v_mfma_f32_16x16x32_bf16 v[30:33], v[46:49], v[196:199], v[30:33]
	v_mfma_f32_16x16x32_bf16 v[26:29], v[62:65], v[196:199], v[26:29]
	v_mfma_f32_16x16x32_bf16 v[14:17], v[46:49], v[214:217], v[14:17]
	v_mfma_f32_16x16x32_bf16 v[10:13], v[62:65], v[214:217], v[10:13]
	s_barrier
	s_add_u32 s52, s20, 0x80000
	s_addc_u32 s53, s21, 0
	s_add_i32 s50, s54, s31
	s_mov_b32 m0, s50
	s_nop 0
	global_load_lds_dwordx4 v0, s[52:53]
	s_add_i32 m0, s50, 0x2000
	s_nop 0
	global_load_lds_dwordx4 v164, s[52:53]
	s_waitcnt vmcnt(6)
	s_barrier
; #define PG8_STAGE(bufoff, gbase, voff) do { _Pragma("unroll") for (int _i = 0; _i < 2; ++_i) \
;         __builtin_amdgcn_global_load_lds((const unsigned*)((const char*)(gbase) + (voff)[_i]), (LAS unsigned*)(lds + (bufoff) + ldsw + _i * 8192), 16, 0, 0); } while (0)
; #define PG8_LDA(dst, b, h) do { _Pragma("unroll") for (int m = 0; m < 4; ++m) _Pragma("unroll") for (int k = 0; k < 2; ++k) dst[m][k] = *(const LAS bf16x8*)(lds + PG8_SA(b, h) + aoff + m * 2048 + k * 1024); } while (0)
; #define PG8_LDB(dst, b, h) do { _Pragma("unroll") for (int n = 0; n < 2; ++n) _Pragma("unroll") for (int k = 0; k < 2; ++k) dst[n][k] = *(const LAS bf16x8*)(lds + PG8_SB(b, h) + boff + n * 2048 + k * 1024); } while (0)
; #define PG8_MMA(ai, bj, At, Bt) do { __builtin_amdgcn_s_setprio(1); _Pragma("unroll") for (int m = 0; m < 4; ++m) _Pragma("unroll") for (int n = 0; n < 2; ++n) _Pragma("unroll") for (int k = 0; k < 2; ++k) \
;         acc[ai][bj][m][n] = __builtin_amdgcn_mfma_f32_16x16x32_bf16(Bt[n][k], At[m][k], acc[ai][bj][m][n], 0, 0, 0); __builtin_amdgcn_s_setprio(0); } while (0)
; #define PG8_WAIT_V(n) asm volatile("s_waitcnt vmcnt(" #n ")" ::: "memory")
; #define PG8_WAIT_L(n) asm volatile("s_waitcnt lgkmcnt(" #n ")" ::: "memory")
; #define PG8_BAR __builtin_amdgcn_s_barrier()
; #define PG8_SCHED __builtin_amdgcn_sched_barrier(0)
; template <class Epi>
; __device__ __forceinline__ void gemm_phase(LAS unsigned char* lds, const Gemm g, const StaticOrder& S, const Epi& E, const int tid) {
;     ...
;             PG8_WAIT_V(6); PG8_BAR; PG8_MMA(1, 1, At, B1); PG8_BAR;
;             PG8_LDB(B0, 1, 0); PG8_SCHED; PG8_LDA(At, 1, 0); PG8_STAGE(PG8_SA(0, 1), a2 + hstep, voffA);
;             PG8_WAIT_L(8); PG8_BAR; PG8_WAIT_L(0); PG8_MMA(0, 0, At, B0); PG8_BAR; PG8_SCHED;
;             PG8_LDB(B1, 1, 1); PG8_STAGE(PG8_SB(1, 0), b3, voffB);
;             PG8_BAR; PG8_WAIT_L(0); PG8_MMA(0, 1, At, B1); PG8_BAR;
;             PG8_LDA(At, 1, 1); PG8_STAGE(PG8_SA(1, 0), a3, voffA);
;             PG8_BAR; PG8_WAIT_L(0); PG8_MMA(1, 0, At, B0); PG8_BAR; PG8_SCHED;
	v_mfma_f32_16x16x32_bf16 v[38:41], v[218:221], v[184:187], v[38:41]
	v_mfma_f32_16x16x32_bf16 v[34:37], v[226:229], v[184:187], v[34:37]
	v_mfma_f32_16x16x32_bf16 v[22:25], v[218:221], v[192:195], v[22:25]
	v_mfma_f32_16x16x32_bf16 v[18:21], v[226:229], v[192:195], v[18:21]
	v_mfma_f32_16x16x32_bf16 v[6:9], v[218:221], v[210:213], v[6:9]
	v_mfma_f32_16x16x32_bf16 v[2:5], v[226:229], v[210:213], v[2:5]
	v_mfma_f32_16x16x32_bf16 v[42:45], v[218:221], v[176:179], v[70:73]
	v_mfma_f32_16x16x32_bf16 v[46:49], v[226:229], v[176:179], v[66:69]
	v_mfma_f32_16x16x32_bf16 v[38:41], v[222:225], v[188:191], v[38:41]
	v_mfma_f32_16x16x32_bf16 v[34:37], v[230:233], v[188:191], v[34:37]
	v_mfma_f32_16x16x32_bf16 v[22:25], v[222:225], v[196:199], v[22:25]
	v_mfma_f32_16x16x32_bf16 v[18:21], v[230:233], v[196:199], v[18:21]
	v_mfma_f32_16x16x32_bf16 v[6:9], v[222:225], v[214:217], v[6:9]
	v_mfma_f32_16x16x32_bf16 v[2:5], v[230:233], v[214:217], v[2:5]
	v_mfma_f32_16x16x32_bf16 v[42:45], v[222:225], v[180:183], v[42:45]
	v_mfma_f32_16x16x32_bf16 v[46:49], v[230:233], v[180:183], v[46:49]
	s_add_i32 s50, 0, 0x18000
	v_add_u32_e32 v70, s50, v173
	s_barrier
	ds_read_b128 v[58:61], v70
	ds_read_b128 v[62:65], v70 offset:1024
	ds_read_b128 v[66:69], v70 offset:2048
	ds_read_b128 v[70:73], v70 offset:3072
	s_add_u32 s22, s22, 0x80000
	s_addc_u32 s23, s23, 0
	s_mov_b32 m0, s35
	ds_read_b128 v[176:179], v174 offset:32768
	ds_read_b128 v[180:183], v174 offset:33792
	ds_read_b128 v[184:187], v174 offset:34816
	ds_read_b128 v[188:191], v174 offset:35840
	ds_read_b128 v[192:195], v174 offset:36864
	ds_read_b128 v[196:199], v174 offset:37888
	ds_read_b128 v[210:213], v174 offset:38912
	ds_read_b128 v[214:217], v174 offset:39936
	global_load_lds_dwordx4 v160, s[22:23]
	s_mov_b32 m0, s36
	s_nop 0
	global_load_lds_dwordx4 v162, s[22:23]
	s_waitcnt lgkmcnt(8)
	s_barrier
	s_waitcnt lgkmcnt(0)
	v_mfma_f32_16x16x32_bf16 v[142:145], v[58:61], v[176:179], v[142:145]
	v_mfma_f32_16x16x32_bf16 v[138:141], v[66:69], v[176:179], v[138:141]
	v_mfma_f32_16x16x32_bf16 v[126:129], v[58:61], v[184:187], v[126:129]
	v_mfma_f32_16x16x32_bf16 v[122:125], v[66:69], v[184:187], v[122:125]
	v_mfma_f32_16x16x32_bf16 v[110:113], v[58:61], v[192:195], v[110:113]
	v_mfma_f32_16x16x32_bf16 v[106:109], v[66:69], v[192:195], v[106:109]
	v_mfma_f32_16x16x32_bf16 v[94:97], v[58:61], v[210:213], v[94:97]
	v_mfma_f32_16x16x32_bf16 v[90:93], v[66:69], v[210:213], v[90:93]
	v_mfma_f32_16x16x32_bf16 v[142:145], v[62:65], v[180:183], v[142:145]
	v_mfma_f32_16x16x32_bf16 v[138:141], v[70:73], v[180:183], v[138:141]
	v_mfma_f32_16x16x32_bf16 v[126:129], v[62:65], v[188:191], v[126:129]
	v_mfma_f32_16x16x32_bf16 v[122:125], v[70:73], v[188:191], v[122:125]
	v_mfma_f32_16x16x32_bf16 v[110:113], v[62:65], v[196:199], v[110:113]
	v_mfma_f32_16x16x32_bf16 v[106:109], v[70:73], v[196:199], v[106:109]
	v_mfma_f32_16x16x32_bf16 v[94:97], v[62:65], v[214:217], v[94:97]
	v_mfma_f32_16x16x32_bf16 v[90:93], v[70:73], v[214:217], v[90:93]
	s_barrier
	s_add_i32 s22, 0, 0x1c000
	s_add_i32 s23, s50, s31
	v_add_u32_e32 v175, s22, v173
	v_lshl_add_u64 v[170:171], v[170:171], 0, s[56:57]
	s_mov_b32 m0, s23
	ds_read_b128 v[218:221], v175
	ds_read_b128 v[222:225], v175 offset:1024
	ds_read_b128 v[226:229], v175 offset:2048
	ds_read_b128 v[230:233], v175 offset:3072
	global_load_lds_dwordx4 v[170:171], off
	v_lshl_add_u64 v[170:171], v[200:201], 0, s[56:57]
	s_add_i32 m0, s23, 0x2000
	s_nop 0
	global_load_lds_dwordx4 v[170:171], off
	s_barrier
	s_waitcnt lgkmcnt(0)
	v_mfma_f32_16x16x32_bf16 v[134:137], v[218:221], v[176:179], v[134:137]
	v_mfma_f32_16x16x32_bf16 v[130:133], v[226:229], v[176:179], v[130:133]
	v_mfma_f32_16x16x32_bf16 v[118:121], v[218:221], v[184:187], v[118:121]
	v_mfma_f32_16x16x32_bf16 v[114:117], v[226:229], v[184:187], v[114:117]
	v_mfma_f32_16x16x32_bf16 v[102:105], v[218:221], v[192:195], v[102:105]
	v_mfma_f32_16x16x32_bf16 v[98:101], v[226:229], v[192:195], v[98:101]
	v_mfma_f32_16x16x32_bf16 v[86:89], v[218:221], v[210:213], v[86:89]
	v_mfma_f32_16x16x32_bf16 v[82:85], v[226:229], v[210:213], v[82:85]
	v_mfma_f32_16x16x32_bf16 v[134:137], v[222:225], v[180:183], v[134:137]
	v_mfma_f32_16x16x32_bf16 v[130:133], v[230:233], v[180:183], v[130:133]
	v_mfma_f32_16x16x32_bf16 v[118:121], v[222:225], v[188:191], v[118:121]
	v_mfma_f32_16x16x32_bf16 v[114:117], v[230:233], v[188:191], v[114:117]
	v_mfma_f32_16x16x32_bf16 v[102:105], v[222:225], v[196:199], v[102:105]
	v_mfma_f32_16x16x32_bf16 v[98:101], v[230:233], v[196:199], v[98:101]
	v_mfma_f32_16x16x32_bf16 v[86:89], v[222:225], v[214:217], v[86:89]
	v_mfma_f32_16x16x32_bf16 v[82:85], v[230:233], v[214:217], v[82:85]
	s_mov_b32 m0, s39
	v_lshl_add_u64 v[170:171], v[234:235], 0, s[56:57]
	s_barrier
	ds_read_b128 v[176:179], v174 offset:49152
	ds_read_b128 v[180:183], v174 offset:50176
	ds_read_b128 v[184:187], v174 offset:51200
	ds_read_b128 v[188:191], v174 offset:52224
	ds_read_b128 v[192:195], v174 offset:53248
	ds_read_b128 v[196:199], v174 offset:54272
	ds_read_b128 v[210:213], v174 offset:55296
	ds_read_b128 v[214:217], v174 offset:56320
	global_load_lds_dwordx4 v[170:171], off
	v_lshl_add_u64 v[170:171], v[236:237], 0, s[56:57]
	s_mov_b32 m0, s40
	s_nop 0
	global_load_lds_dwordx4 v[170:171], off
	s_barrier
; __device__ __forceinline__ unsigned pk2(float lo, float hi) { f32x2 v = {lo, hi}; return __builtin_bit_cast(unsigned, __builtin_convertvector(v, bf16x2_t)); }
; __device__ __forceinline__ float bf_lo(unsigned w) { return __uint_as_float(w << 16); }
;     __device__ __forceinline__ void operator()(const f32x4 (&acc)[2][2][4][2], const Unit& u, int wr, int wc, int fr, int fq) const {
;         asm volatile("" : "+v"(fr), "+v"(fq));
;         const int row0 = u.pm * BM + wr * 64 + fr, col0 = u.pn * BM + wc * 32 + 8 * fq;
;         const float* gp = gate + (size_t)(u.pm >> 5) * 12288 + col0;
;         f32x4 gv[2][2];
; #pragma unroll
;         for (int bj = 0; bj < 2; ++bj)
; #pragma unroll
;             for (int n = 0; n < 2; ++n) gv[bj][n] = *(const f32x4*)(gp + bj * HALF + 4 * n);
; #pragma unroll
;         for (int ai = 0; ai < 2; ++ai)
; #pragma unroll
;             for (int m = 0; m < 4; ++m) {
;                 const size_t ro = (size_t)(row0 + ai * HALF + m * 16) * DM + col0;
; #pragma unroll
;                 for (int bj = 0; bj < 2; ++bj) {
;                     f32x4 r0, r1;
;                     if (RB) { const u32x4 rw = *(const u32x4*)((const bf16_t*)resid + ro + bj * HALF);
;                         r0 = (f32x4){bf_lo(rw.x), bf_hi(rw.x), bf_lo(rw.y), bf_hi(rw.y)}; r1 = (f32x4){bf_lo(rw.z), bf_hi(rw.z), bf_lo(rw.w), bf_hi(rw.w)}; }
;                     else { r0 = *(const f32x4*)((const float*)resid + ro + bj * HALF); r1 = *(const f32x4*)((const float*)resid + ro + bj * HALF + 4); }
;                     const f32x4 v0 = r0 + gv[bj][0] * acc[ai][bj][m][0], v1 = r1 + gv[bj][1] * acc[ai][bj][m][1];
;                     if (OB) { u32x4 w; w.x = pk2(v0[0], v0[1]); w.y = pk2(v0[2], v0[3]); w.z = pk2(v1[0], v1[1]); w.w = pk2(v1[2], v1[3]); *(u32x4*)((bf16_t*)out + ro + bj * HALF) = w; }
;                     else { *(f32x4*)((float*)out + ro + bj * HALF) = v0; *(f32x4*)((float*)out + ro + bj * HALF + 4) = v1; }
;                 }
; template <class Epi>
; __device__ __forceinline__ void gemm_phase(LAS unsigned char* lds, const Gemm g, const StaticOrder& S, const Epi& E, const int tid) {
;     ...
;             PG8_BAR; PG8_WAIT_L(0); PG8_MMA(1, 0, At, B0); PG8_BAR; PG8_SCHED;
;             PG8_STAGE(PG8_SB(1, 1), b3 + hstep, voffB);
;             PG8_WAIT_V(6); PG8_BAR; PG8_MMA(1, 1, At, B1); PG8_BAR;
;         }
;         E(acc, cur, wr, wc, fr, fq);
	s_waitcnt lgkmcnt(0)
	v_mfma_f32_16x16x32_bf16 v[78:81], v[58:61], v[176:179], v[78:81]
	v_mfma_f32_16x16x32_bf16 v[74:77], v[66:69], v[176:179], v[74:77]
	v_mfma_f32_16x16x32_bf16 v[54:57], v[58:61], v[184:187], v[54:57]
	v_mfma_f32_16x16x32_bf16 v[50:53], v[66:69], v[184:187], v[50:53]
	v_mfma_f32_16x16x32_bf16 v[30:33], v[58:61], v[192:195], v[30:33]
	v_mfma_f32_16x16x32_bf16 v[26:29], v[66:69], v[192:195], v[26:29]
	v_mfma_f32_16x16x32_bf16 v[14:17], v[58:61], v[210:213], v[14:17]
	v_mfma_f32_16x16x32_bf16 v[10:13], v[66:69], v[210:213], v[10:13]
	v_mfma_f32_16x16x32_bf16 v[78:81], v[62:65], v[180:183], v[78:81]
	v_mfma_f32_16x16x32_bf16 v[74:77], v[70:73], v[180:183], v[74:77]
	v_mfma_f32_16x16x32_bf16 v[54:57], v[62:65], v[188:191], v[54:57]
	v_mfma_f32_16x16x32_bf16 v[50:53], v[70:73], v[188:191], v[50:53]
	v_mfma_f32_16x16x32_bf16 v[30:33], v[62:65], v[196:199], v[30:33]
	v_mfma_f32_16x16x32_bf16 v[26:29], v[70:73], v[196:199], v[26:29]
	v_mfma_f32_16x16x32_bf16 v[14:17], v[62:65], v[214:217], v[14:17]
	v_mfma_f32_16x16x32_bf16 v[10:13], v[70:73], v[214:217], v[10:13]
	s_barrier
	s_add_i32 s49, s49, 2
	s_add_u32 s47, s47, 0x100
	s_addc_u32 s48, s48, 0
	s_add_u32 s18, s18, 0x100
	s_addc_u32 s19, s19, 0
	s_add_u32 s20, s20, 0x80080
	s_addc_u32 s21, s21, 0
	s_add_i32 s22, s22, s31
	s_mov_b32 m0, s22
	s_nop 0
	global_load_lds_dwordx4 v0, s[20:21]
	s_add_i32 m0, s22, 0x2000
	s_nop 0
	global_load_lds_dwordx4 v164, s[20:21]
	s_waitcnt vmcnt(6)
	s_barrier
	v_mfma_f32_16x16x32_bf16 v[42:45], v[218:221], v[176:179], v[42:45]
	v_mfma_f32_16x16x32_bf16 v[70:73], v[222:225], v[180:183], v[42:45]
	v_mfma_f32_16x16x32_bf16 v[42:45], v[226:229], v[176:179], v[46:49]
	v_mfma_f32_16x16x32_bf16 v[38:41], v[218:221], v[184:187], v[38:41]
	v_mfma_f32_16x16x32_bf16 v[34:37], v[226:229], v[184:187], v[34:37]
	v_mfma_f32_16x16x32_bf16 v[22:25], v[218:221], v[192:195], v[22:25]
	v_mfma_f32_16x16x32_bf16 v[18:21], v[226:229], v[192:195], v[18:21]
	v_mfma_f32_16x16x32_bf16 v[6:9], v[218:221], v[210:213], v[6:9]
	v_mfma_f32_16x16x32_bf16 v[2:5], v[226:229], v[210:213], v[2:5]
	v_mfma_f32_16x16x32_bf16 v[66:69], v[230:233], v[180:183], v[42:45]
	v_mfma_f32_16x16x32_bf16 v[38:41], v[222:225], v[188:191], v[38:41]
	v_mfma_f32_16x16x32_bf16 v[34:37], v[230:233], v[188:191], v[34:37]
	v_mfma_f32_16x16x32_bf16 v[22:25], v[222:225], v[196:199], v[22:25]
	v_mfma_f32_16x16x32_bf16 v[18:21], v[230:233], v[196:199], v[18:21]
	v_mfma_f32_16x16x32_bf16 v[6:9], v[222:225], v[214:217], v[6:9]
	v_mfma_f32_16x16x32_bf16 v[2:5], v[230:233], v[214:217], v[2:5]
	s_cmp_gt_u32 s49, 29
	s_barrier
	s_cbranch_scc0 .LBB0_119
	s_setprio 0
	s_lshl_b32 s11, s2, 8
	s_lshl_b32 s13, s43, 8
	v_mov_b32_e32 v175, v172
	v_mov_b32_e32 v42, v159
	s_add_i32 s11, s11, s37
	s_or_b32 s13, s13, s38
	s_ashr_i32 s2, s2, 5
	s_mov_b32 s43, s10
	v_lshl_add_u32 v170, v42, 3, s13
	s_mul_hi_i32 s13, s2, 0xc000
	s_mul_i32 s2, s2, 0xc000
	v_add_u32_e32 v176, s11, v175
	s_add_u32 s18, s27, s2
	v_ashrrev_i32_e32 v177, 31, v176
	s_addc_u32 s19, s28, s13
	v_ashrrev_i32_e32 v171, 31, v170
	v_lshlrev_b64 v[176:177], 11, v[176:177]
	v_lshl_add_u64 v[46:47], v[170:171], 2, s[18:19]
	v_lshl_add_u64 v[170:171], v[176:177], 0, v[170:171]
	v_lshlrev_b64 v[170:171], 1, v[170:171]
	v_lshl_add_u64 v[180:181], s[8:9], 0, v[170:171]
	global_load_dwordx4 v[58:61], v[46:47], off offset:16
	global_load_dwordx4 v[62:65], v[46:47], off
	global_load_dwordx4 v[42:45], v[46:47], off offset:528
	s_nop 0
	global_load_dwordx4 v[46:49], v[46:47], off offset:512
	s_mov_b64 s[92:93], s[8:9]
	s_mov_b64 s[94:95], s[6:7]
	global_load_dwordx4 v[184:187], v170, s[92:93]
	global_load_dwordx4 v[188:191], v170, s[92:93] offset:256
	s_add_u32 s92, s92, 0x10000
	s_addc_u32 s93, s93, 0
	global_load_dwordx4 v[192:195], v170, s[92:93]
	global_load_dwordx4 v[196:199], v170, s[92:93] offset:256
	s_add_u32 s92, s92, 0x10000
	s_addc_u32 s93, s93, 0
	global_load_dwordx4 v[210:213], v170, s[92:93]
	global_load_dwordx4 v[214:217], v170, s[92:93] offset:256
	s_add_u32 s92, s92, 0x10000
	s_addc_u32 s93, s93, 0
	global_load_dwordx4 v[218:221], v170, s[92:93]
	global_load_dwordx4 v[222:225], v170, s[92:93] offset:256
	s_add_u32 s92, s92, 0x50000
	s_addc_u32 s93, s93, 0
	global_load_dwordx4 v[226:229], v170, s[92:93]
	global_load_dwordx4 v[230:233], v170, s[92:93] offset:256
	s_add_u32 s92, s92, 0x10000
	s_addc_u32 s93, s93, 0
	global_load_dwordx4 v[234:237], v170, s[92:93]
	s_waitcnt vmcnt(10)
	v_lshlrev_b32_e32 v176, 16, v184
	v_and_b32_e32 v177, 0xffff0000, v184
	v_lshlrev_b32_e32 v178, 16, v185
	v_and_b32_e32 v179, 0xffff0000, v185
	v_lshlrev_b32_e32 v180, 16, v186
	v_and_b32_e32 v181, 0xffff0000, v186
	v_lshlrev_b32_e32 v182, 16, v187
	v_and_b32_e32 v183, 0xffff0000, v187
	v_pk_fma_f32 v[142:143], v[142:143], v[62:63], v[176:177]
	v_pk_fma_f32 v[144:145], v[144:145], v[64:65], v[178:179]
	v_pk_fma_f32 v[138:139], v[138:139], v[58:59], v[180:181]
	v_pk_fma_f32 v[140:141], v[140:141], v[60:61], v[182:183]
	global_load_dwordx4 v[184:187], v170, s[92:93] offset:256
	v_cvt_pk_bf16_f32 v142, v142, v143
	v_cvt_pk_bf16_f32 v143, v144, v145
	v_cvt_pk_bf16_f32 v144, v138, v139
	v_cvt_pk_bf16_f32 v145, v140, v141
	global_store_dwordx4 v170, v[142:145], s[94:95]
	s_waitcnt vmcnt(11)
; __device__ __forceinline__ unsigned pk2(float lo, float hi) { f32x2 v = {lo, hi}; return __builtin_bit_cast(unsigned, __builtin_convertvector(v, bf16x2_t)); }
; __device__ __forceinline__ float bf_lo(unsigned w) { return __uint_as_float(w << 16); }
; __device__ __forceinline__ float bf_hi(unsigned w) { return __uint_as_float(w & 0xffff0000u); }
;     __device__ __forceinline__ void operator()(const f32x4 (&acc)[2][2][4][2], const Unit& u, int wr, int wc, int fr, int fq) const {
;     ...
;             for (int m = 0; m < 4; ++m) {
;                 const size_t ro = (size_t)(row0 + ai * HALF + m * 16) * DM + col0;
; #pragma unroll
;                 for (int bj = 0; bj < 2; ++bj) {
;                     f32x4 r0, r1;
;                     if (RB) { const u32x4 rw = *(const u32x4*)((const bf16_t*)resid + ro + bj * HALF);
;                         r0 = (f32x4){bf_lo(rw.x), bf_hi(rw.x), bf_lo(rw.y), bf_hi(rw.y)}; r1 = (f32x4){bf_lo(rw.z), bf_hi(rw.z), bf_lo(rw.w), bf_hi(rw.w)}; }
;                     else { r0 = *(const f32x4*)((const float*)resid + ro + bj * HALF); r1 = *(const f32x4*)((const float*)resid + ro + bj * HALF + 4); }
;                     const f32x4 v0 = r0 + gv[bj][0] * acc[ai][bj][m][0], v1 = r1 + gv[bj][1] * acc[ai][bj][m][1];
;                     if (OB) { u32x4 w; w.x = pk2(v0[0], v0[1]); w.y = pk2(v0[2], v0[3]); w.z = pk2(v1[0], v1[1]); w.w = pk2(v1[2], v1[3]); *(u32x4*)((bf16_t*)out + ro + bj * HALF) = w; }
;                     else { *(f32x4*)((float*)out + ro + bj * HALF) = v0; *(f32x4*)((float*)out + ro + bj * HALF + 4) = v1; }
;                 }
	v_lshlrev_b32_e32 v176, 16, v188
	v_and_b32_e32 v177, 0xffff0000, v188
	v_lshlrev_b32_e32 v178, 16, v189
	v_and_b32_e32 v179, 0xffff0000, v189
	v_lshlrev_b32_e32 v180, 16, v190
	v_and_b32_e32 v181, 0xffff0000, v190
	v_lshlrev_b32_e32 v182, 16, v191
	v_and_b32_e32 v183, 0xffff0000, v191
	v_pk_fma_f32 v[134:135], v[134:135], v[46:47], v[176:177]
	v_pk_fma_f32 v[136:137], v[136:137], v[48:49], v[178:179]
	v_pk_fma_f32 v[130:131], v[130:131], v[42:43], v[180:181]
	v_pk_fma_f32 v[132:133], v[132:133], v[44:45], v[182:183]
	s_add_u32 s92, s92, 0x10000
	s_addc_u32 s93, s93, 0
	global_load_dwordx4 v[188:191], v170, s[92:93]
	v_cvt_pk_bf16_f32 v134, v134, v135
	v_cvt_pk_bf16_f32 v135, v136, v137
	v_cvt_pk_bf16_f32 v136, v130, v131
	v_cvt_pk_bf16_f32 v137, v132, v133
	global_store_dwordx4 v170, v[134:137], s[94:95] offset:256
	s_waitcnt vmcnt(12)
	v_lshlrev_b32_e32 v176, 16, v192
	v_and_b32_e32 v177, 0xffff0000, v192
	v_lshlrev_b32_e32 v178, 16, v193
	v_and_b32_e32 v179, 0xffff0000, v193
	v_lshlrev_b32_e32 v180, 16, v194
	v_and_b32_e32 v181, 0xffff0000, v194
	v_lshlrev_b32_e32 v182, 16, v195
	v_and_b32_e32 v183, 0xffff0000, v195
	v_pk_fma_f32 v[126:127], v[126:127], v[62:63], v[176:177]
	v_pk_fma_f32 v[128:129], v[128:129], v[64:65], v[178:179]
	v_pk_fma_f32 v[122:123], v[122:123], v[58:59], v[180:181]
	v_pk_fma_f32 v[124:125], v[124:125], v[60:61], v[182:183]
	global_load_dwordx4 v[192:195], v170, s[92:93] offset:256
	s_add_u32 s94, s94, 0x10000
	s_addc_u32 s95, s95, 0
	v_cvt_pk_bf16_f32 v126, v126, v127
	v_cvt_pk_bf16_f32 v127, v128, v129
	v_cvt_pk_bf16_f32 v128, v122, v123
	v_cvt_pk_bf16_f32 v129, v124, v125
	global_store_dwordx4 v170, v[126:129], s[94:95]
	s_waitcnt vmcnt(13)
	v_lshlrev_b32_e32 v176, 16, v196
	v_and_b32_e32 v177, 0xffff0000, v196
	v_lshlrev_b32_e32 v178, 16, v197
	v_and_b32_e32 v179, 0xffff0000, v197
	v_lshlrev_b32_e32 v180, 16, v198
	v_and_b32_e32 v181, 0xffff0000, v198
	v_lshlrev_b32_e32 v182, 16, v199
	v_and_b32_e32 v183, 0xffff0000, v199
	v_pk_fma_f32 v[118:119], v[118:119], v[46:47], v[176:177]
	v_pk_fma_f32 v[120:121], v[120:121], v[48:49], v[178:179]
	v_pk_fma_f32 v[114:115], v[114:115], v[42:43], v[180:181]
	v_pk_fma_f32 v[116:117], v[116:117], v[44:45], v[182:183]
	s_add_u32 s92, s92, 0x10000
	s_addc_u32 s93, s93, 0
	global_load_dwordx4 v[196:199], v170, s[92:93]
	v_cvt_pk_bf16_f32 v118, v118, v119
	v_cvt_pk_bf16_f32 v119, v120, v121
	v_cvt_pk_bf16_f32 v120, v114, v115
	v_cvt_pk_bf16_f32 v121, v116, v117
	global_store_dwordx4 v170, v[118:121], s[94:95] offset:256
	s_waitcnt vmcnt(14)
	v_lshlrev_b32_e32 v176, 16, v210
	v_and_b32_e32 v177, 0xffff0000, v210
	v_lshlrev_b32_e32 v178, 16, v211
	v_and_b32_e32 v179, 0xffff0000, v211
	v_lshlrev_b32_e32 v180, 16, v212
	v_and_b32_e32 v181, 0xffff0000, v212
	v_lshlrev_b32_e32 v182, 16, v213
	v_and_b32_e32 v183, 0xffff0000, v213
	v_pk_fma_f32 v[110:111], v[110:111], v[62:63], v[176:177]
	v_pk_fma_f32 v[112:113], v[112:113], v[64:65], v[178:179]
	v_pk_fma_f32 v[106:107], v[106:107], v[58:59], v[180:181]
	v_pk_fma_f32 v[108:109], v[108:109], v[60:61], v[182:183]
	global_load_dwordx4 v[210:213], v170, s[92:93] offset:256
	s_add_u32 s94, s94, 0x10000
	s_addc_u32 s95, s95, 0
	v_cvt_pk_bf16_f32 v110, v110, v111
	v_cvt_pk_bf16_f32 v111, v112, v113
	v_cvt_pk_bf16_f32 v112, v106, v107
	v_cvt_pk_bf16_f32 v113, v108, v109
	global_store_dwordx4 v170, v[110:113], s[94:95]
	s_waitcnt vmcnt(15)
	v_lshlrev_b32_e32 v176, 16, v214
	v_and_b32_e32 v177, 0xffff0000, v214
	v_lshlrev_b32_e32 v178, 16, v215
	v_and_b32_e32 v179, 0xffff0000, v215
	v_lshlrev_b32_e32 v180, 16, v216
	v_and_b32_e32 v181, 0xffff0000, v216
	v_lshlrev_b32_e32 v182, 16, v217
	v_and_b32_e32 v183, 0xffff0000, v217
	v_pk_fma_f32 v[102:103], v[102:103], v[46:47], v[176:177]
	v_pk_fma_f32 v[104:105], v[104:105], v[48:49], v[178:179]
	v_pk_fma_f32 v[98:99], v[98:99], v[42:43], v[180:181]
	v_pk_fma_f32 v[100:101], v[100:101], v[44:45], v[182:183]
	v_cvt_pk_bf16_f32 v102, v102, v103
	v_cvt_pk_bf16_f32 v103, v104, v105
	v_cvt_pk_bf16_f32 v104, v98, v99
	v_cvt_pk_bf16_f32 v105, v100, v101
	global_store_dwordx4 v170, v[102:105], s[94:95] offset:256
	s_waitcnt vmcnt(15)
	v_lshlrev_b32_e32 v176, 16, v218
	v_and_b32_e32 v177, 0xffff0000, v218
	v_lshlrev_b32_e32 v178, 16, v219
	v_and_b32_e32 v179, 0xffff0000, v219
	v_lshlrev_b32_e32 v180, 16, v220
	v_and_b32_e32 v181, 0xffff0000, v220
	v_lshlrev_b32_e32 v182, 16, v221
	v_and_b32_e32 v183, 0xffff0000, v221
	v_pk_fma_f32 v[94:95], v[94:95], v[62:63], v[176:177]
	v_pk_fma_f32 v[96:97], v[96:97], v[64:65], v[178:179]
	v_pk_fma_f32 v[90:91], v[90:91], v[58:59], v[180:181]
	v_pk_fma_f32 v[92:93], v[92:93], v[60:61], v[182:183]
	s_add_u32 s94, s94, 0x10000
	s_addc_u32 s95, s95, 0
	v_cvt_pk_bf16_f32 v94, v94, v95
	v_cvt_pk_bf16_f32 v95, v96, v97
	v_cvt_pk_bf16_f32 v96, v90, v91
	v_cvt_pk_bf16_f32 v97, v92, v93
	global_store_dwordx4 v170, v[94:97], s[94:95]
	s_waitcnt vmcnt(15)
	v_lshlrev_b32_e32 v176, 16, v222
	v_and_b32_e32 v177, 0xffff0000, v222
	v_lshlrev_b32_e32 v178, 16, v223
	v_and_b32_e32 v179, 0xffff0000, v223
	v_lshlrev_b32_e32 v180, 16, v224
	v_and_b32_e32 v181, 0xffff0000, v224
	v_lshlrev_b32_e32 v182, 16, v225
	v_and_b32_e32 v183, 0xffff0000, v225
	v_pk_fma_f32 v[86:87], v[86:87], v[46:47], v[176:177]
	v_pk_fma_f32 v[88:89], v[88:89], v[48:49], v[178:179]
	v_pk_fma_f32 v[82:83], v[82:83], v[42:43], v[180:181]
	v_pk_fma_f32 v[84:85], v[84:85], v[44:45], v[182:183]
	v_cvt_pk_bf16_f32 v86, v86, v87
	v_cvt_pk_bf16_f32 v87, v88, v89
	v_cvt_pk_bf16_f32 v88, v82, v83
	v_cvt_pk_bf16_f32 v89, v84, v85
	global_store_dwordx4 v170, v[86:89], s[94:95] offset:256
	s_waitcnt vmcnt(15)
; __device__ __forceinline__ unsigned pk2(float lo, float hi) { f32x2 v = {lo, hi}; return __builtin_bit_cast(unsigned, __builtin_convertvector(v, bf16x2_t)); }
; __device__ __forceinline__ float bf_lo(unsigned w) { return __uint_as_float(w << 16); }
; __device__ __forceinline__ float bf_hi(unsigned w) { return __uint_as_float(w & 0xffff0000u); }
; #define PG8_WAIT_V(n) asm volatile("s_waitcnt vmcnt(" #n ")" ::: "memory")
; #define PG8_BAR __builtin_amdgcn_s_barrier()
;     __device__ __forceinline__ void operator()(const f32x4 (&acc)[2][2][4][2], const Unit& u, int wr, int wc, int fr, int fq) const {
;     ...
;             for (int m = 0; m < 4; ++m) {
;                 const size_t ro = (size_t)(row0 + ai * HALF + m * 16) * DM + col0;
; #pragma unroll
;                 for (int bj = 0; bj < 2; ++bj) {
;                     f32x4 r0, r1;
;                     if (RB) { const u32x4 rw = *(const u32x4*)((const bf16_t*)resid + ro + bj * HALF);
;                         r0 = (f32x4){bf_lo(rw.x), bf_hi(rw.x), bf_lo(rw.y), bf_hi(rw.y)}; r1 = (f32x4){bf_lo(rw.z), bf_hi(rw.z), bf_lo(rw.w), bf_hi(rw.w)}; }
;                     else { r0 = *(const f32x4*)((const float*)resid + ro + bj * HALF); r1 = *(const f32x4*)((const float*)resid + ro + bj * HALF + 4); }
;                     const f32x4 v0 = r0 + gv[bj][0] * acc[ai][bj][m][0], v1 = r1 + gv[bj][1] * acc[ai][bj][m][1];
;                     if (OB) { u32x4 w; w.x = pk2(v0[0], v0[1]); w.y = pk2(v0[2], v0[3]); w.z = pk2(v1[0], v1[1]); w.w = pk2(v1[2], v1[3]); *(u32x4*)((bf16_t*)out + ro + bj * HALF) = w; }
;                     else { *(f32x4*)((float*)out + ro + bj * HALF) = v0; *(f32x4*)((float*)out + ro + bj * HALF + 4) = v1; }
;                 }
; template <class Epi>
; __device__ __forceinline__ void gemm_phase(LAS unsigned char* lds, const Gemm g, const StaticOrder& S, const Epi& E, const int tid) {
;     ...
;         if (!has_next) break;
; #pragma unroll
;         for (int a = 0; a < 2; ++a)
; #pragma unroll
;             for (int b = 0; b < 2; ++b)
; #pragma unroll
;                 for (int m = 0; m < 4; ++m)
; #pragma unroll
;                     for (int n = 0; n < 2; ++n) acc[a][b][m][n] = (f32x4){0.f, 0.f, 0.f, 0.f};
;         cur = nxt; cA = nA; cB = nB; ++ui;
;     }
;     PG8_WAIT_V(0);
;     if (wr == 0) PG8_BAR;
	v_lshlrev_b32_e32 v176, 16, v226
	v_and_b32_e32 v177, 0xffff0000, v226
	v_lshlrev_b32_e32 v178, 16, v227
	v_and_b32_e32 v179, 0xffff0000, v227
	v_lshlrev_b32_e32 v180, 16, v228
	v_and_b32_e32 v181, 0xffff0000, v228
	v_lshlrev_b32_e32 v182, 16, v229
	v_and_b32_e32 v183, 0xffff0000, v229
	v_pk_fma_f32 v[78:79], v[78:79], v[62:63], v[176:177]
	v_pk_fma_f32 v[80:81], v[80:81], v[64:65], v[178:179]
	v_pk_fma_f32 v[74:75], v[74:75], v[58:59], v[180:181]
	v_pk_fma_f32 v[76:77], v[76:77], v[60:61], v[182:183]
	s_add_u32 s94, s94, 0x50000
	s_addc_u32 s95, s95, 0
	v_cvt_pk_bf16_f32 v78, v78, v79
	v_cvt_pk_bf16_f32 v79, v80, v81
	v_cvt_pk_bf16_f32 v80, v74, v75
	v_cvt_pk_bf16_f32 v81, v76, v77
	global_store_dwordx4 v170, v[78:81], s[94:95]
	s_waitcnt vmcnt(15)
	v_lshlrev_b32_e32 v176, 16, v230
	v_and_b32_e32 v177, 0xffff0000, v230
	v_lshlrev_b32_e32 v178, 16, v231
	v_and_b32_e32 v179, 0xffff0000, v231
	v_lshlrev_b32_e32 v180, 16, v232
	v_and_b32_e32 v181, 0xffff0000, v232
	v_lshlrev_b32_e32 v182, 16, v233
	v_and_b32_e32 v183, 0xffff0000, v233
	v_pk_fma_f32 v[70:71], v[70:71], v[46:47], v[176:177]
	v_pk_fma_f32 v[72:73], v[72:73], v[48:49], v[178:179]
	v_pk_fma_f32 v[66:67], v[66:67], v[42:43], v[180:181]
	v_pk_fma_f32 v[68:69], v[68:69], v[44:45], v[182:183]
	v_cvt_pk_bf16_f32 v70, v70, v71
	v_cvt_pk_bf16_f32 v71, v72, v73
	v_cvt_pk_bf16_f32 v72, v66, v67
	v_cvt_pk_bf16_f32 v73, v68, v69
	global_store_dwordx4 v170, v[70:73], s[94:95] offset:256
	s_waitcnt vmcnt(15)
	v_lshlrev_b32_e32 v176, 16, v234
	v_and_b32_e32 v177, 0xffff0000, v234
	v_lshlrev_b32_e32 v178, 16, v235
	v_and_b32_e32 v179, 0xffff0000, v235
	v_lshlrev_b32_e32 v180, 16, v236
	v_and_b32_e32 v181, 0xffff0000, v236
	v_lshlrev_b32_e32 v182, 16, v237
	v_and_b32_e32 v183, 0xffff0000, v237
	v_pk_fma_f32 v[54:55], v[54:55], v[62:63], v[176:177]
	v_pk_fma_f32 v[56:57], v[56:57], v[64:65], v[178:179]
	v_pk_fma_f32 v[50:51], v[50:51], v[58:59], v[180:181]
	v_pk_fma_f32 v[52:53], v[52:53], v[60:61], v[182:183]
	s_add_u32 s94, s94, 0x10000
	s_addc_u32 s95, s95, 0
	v_cvt_pk_bf16_f32 v54, v54, v55
	v_cvt_pk_bf16_f32 v55, v56, v57
	v_cvt_pk_bf16_f32 v56, v50, v51
	v_cvt_pk_bf16_f32 v57, v52, v53
	global_store_dwordx4 v170, v[54:57], s[94:95]
	s_waitcnt vmcnt(15)
	v_lshlrev_b32_e32 v176, 16, v184
	v_and_b32_e32 v177, 0xffff0000, v184
	v_lshlrev_b32_e32 v178, 16, v185
	v_and_b32_e32 v179, 0xffff0000, v185
	v_lshlrev_b32_e32 v180, 16, v186
	v_and_b32_e32 v181, 0xffff0000, v186
	v_lshlrev_b32_e32 v182, 16, v187
	v_and_b32_e32 v183, 0xffff0000, v187
	v_pk_fma_f32 v[38:39], v[38:39], v[46:47], v[176:177]
	v_pk_fma_f32 v[40:41], v[40:41], v[48:49], v[178:179]
	v_pk_fma_f32 v[34:35], v[34:35], v[42:43], v[180:181]
	v_pk_fma_f32 v[36:37], v[36:37], v[44:45], v[182:183]
	v_cvt_pk_bf16_f32 v38, v38, v39
	v_cvt_pk_bf16_f32 v39, v40, v41
	v_cvt_pk_bf16_f32 v40, v34, v35
	v_cvt_pk_bf16_f32 v41, v36, v37
	global_store_dwordx4 v170, v[38:41], s[94:95] offset:256
	s_waitcnt vmcnt(14)
	v_lshlrev_b32_e32 v176, 16, v188
	v_and_b32_e32 v177, 0xffff0000, v188
	v_lshlrev_b32_e32 v178, 16, v189
	v_and_b32_e32 v179, 0xffff0000, v189
	v_lshlrev_b32_e32 v180, 16, v190
	v_and_b32_e32 v181, 0xffff0000, v190
	v_lshlrev_b32_e32 v182, 16, v191
	v_and_b32_e32 v183, 0xffff0000, v191
	v_pk_fma_f32 v[30:31], v[30:31], v[62:63], v[176:177]
	v_pk_fma_f32 v[32:33], v[32:33], v[64:65], v[178:179]
	v_pk_fma_f32 v[26:27], v[26:27], v[58:59], v[180:181]
	v_pk_fma_f32 v[28:29], v[28:29], v[60:61], v[182:183]
	s_add_u32 s94, s94, 0x10000
	s_addc_u32 s95, s95, 0
	v_cvt_pk_bf16_f32 v30, v30, v31
	v_cvt_pk_bf16_f32 v31, v32, v33
	v_cvt_pk_bf16_f32 v32, v26, v27
	v_cvt_pk_bf16_f32 v33, v28, v29
	global_store_dwordx4 v170, v[30:33], s[94:95]
	s_waitcnt vmcnt(13)
	v_lshlrev_b32_e32 v176, 16, v192
	v_and_b32_e32 v177, 0xffff0000, v192
	v_lshlrev_b32_e32 v178, 16, v193
	v_and_b32_e32 v179, 0xffff0000, v193
	v_lshlrev_b32_e32 v180, 16, v194
	v_and_b32_e32 v181, 0xffff0000, v194
	v_lshlrev_b32_e32 v182, 16, v195
	v_and_b32_e32 v183, 0xffff0000, v195
	v_pk_fma_f32 v[22:23], v[22:23], v[46:47], v[176:177]
	v_pk_fma_f32 v[24:25], v[24:25], v[48:49], v[178:179]
	v_pk_fma_f32 v[18:19], v[18:19], v[42:43], v[180:181]
	v_pk_fma_f32 v[20:21], v[20:21], v[44:45], v[182:183]
	v_cvt_pk_bf16_f32 v22, v22, v23
	v_cvt_pk_bf16_f32 v23, v24, v25
	v_cvt_pk_bf16_f32 v24, v18, v19
	v_cvt_pk_bf16_f32 v25, v20, v21
	global_store_dwordx4 v170, v[22:25], s[94:95] offset:256
	s_waitcnt vmcnt(12)
	v_lshlrev_b32_e32 v176, 16, v196
	v_and_b32_e32 v177, 0xffff0000, v196
	v_lshlrev_b32_e32 v178, 16, v197
	v_and_b32_e32 v179, 0xffff0000, v197
	v_lshlrev_b32_e32 v180, 16, v198
	v_and_b32_e32 v181, 0xffff0000, v198
	v_lshlrev_b32_e32 v182, 16, v199
	v_and_b32_e32 v183, 0xffff0000, v199
	v_pk_fma_f32 v[14:15], v[14:15], v[62:63], v[176:177]
	v_pk_fma_f32 v[16:17], v[16:17], v[64:65], v[178:179]
	v_pk_fma_f32 v[10:11], v[10:11], v[58:59], v[180:181]
	v_pk_fma_f32 v[12:13], v[12:13], v[60:61], v[182:183]
	s_add_u32 s94, s94, 0x10000
	s_addc_u32 s95, s95, 0
	v_cvt_pk_bf16_f32 v14, v14, v15
	v_cvt_pk_bf16_f32 v15, v16, v17
	v_cvt_pk_bf16_f32 v16, v10, v11
	v_cvt_pk_bf16_f32 v17, v12, v13
	global_store_dwordx4 v170, v[14:17], s[94:95]
	s_waitcnt vmcnt(11)
	v_lshlrev_b32_e32 v176, 16, v210
	v_and_b32_e32 v177, 0xffff0000, v210
	v_lshlrev_b32_e32 v178, 16, v211
	v_and_b32_e32 v179, 0xffff0000, v211
	v_lshlrev_b32_e32 v180, 16, v212
	v_and_b32_e32 v181, 0xffff0000, v212
	v_lshlrev_b32_e32 v182, 16, v213
	v_and_b32_e32 v183, 0xffff0000, v213
	v_pk_fma_f32 v[6:7], v[6:7], v[46:47], v[176:177]
	v_pk_fma_f32 v[8:9], v[8:9], v[48:49], v[178:179]
	v_pk_fma_f32 v[2:3], v[2:3], v[42:43], v[180:181]
	v_pk_fma_f32 v[4:5], v[4:5], v[44:45], v[182:183]
	v_cvt_pk_bf16_f32 v6, v6, v7
	v_cvt_pk_bf16_f32 v7, v8, v9
	v_cvt_pk_bf16_f32 v8, v2, v3
	v_cvt_pk_bf16_f32 v9, v4, v5
	global_store_dwordx4 v170, v[6:9], s[94:95] offset:256
	s_mov_b32 s2, s12
	s_mov_b64 s[20:21], s[14:15]
	s_mov_b64 s[18:19], s[16:17]
	s_and_b64 vcc, exec, s[4:5]
	s_nop 1
	s_cbranch_vccz .LBB0_112
	s_waitcnt vmcnt(0)
	s_cmpk_gt_u32 s29, 0xff
	s_cbranch_scc1 .LBB0_123
	s_barrier

; #define PG8_STAGE(bufoff, gbase, voff) do { _Pragma("unroll") for (int _i = 0; _i < 2; ++_i) \
;         __builtin_amdgcn_global_load_lds((const unsigned*)((const char*)(gbase) + (voff)[_i]), (LAS unsigned*)(lds + (bufoff) + ldsw + _i * 8192), 16, 0, 0); } while (0)
; #define PG8_LDA(dst, b, h) do { _Pragma("unroll") for (int m = 0; m < 4; ++m) _Pragma("unroll") for (int k = 0; k < 2; ++k) dst[m][k] = *(const LAS bf16x8*)(lds + PG8_SA(b, h) + aoff + m * 2048 + k * 1024); } while (0)
; #define PG8_LDB(dst, b, h) do { _Pragma("unroll") for (int n = 0; n < 2; ++n) _Pragma("unroll") for (int k = 0; k < 2; ++k) dst[n][k] = *(const LAS bf16x8*)(lds + PG8_SB(b, h) + boff + n * 2048 + k * 1024); } while (0)
; #define PG8_MMA(ai, bj, At, Bt) do { __builtin_amdgcn_s_setprio(1); _Pragma("unroll") for (int m = 0; m < 4; ++m) _Pragma("unroll") for (int n = 0; n < 2; ++n) _Pragma("unroll") for (int k = 0; k < 2; ++k) \
;         acc[ai][bj][m][n] = __builtin_amdgcn_mfma_f32_16x16x32_bf16(Bt[n][k], At[m][k], acc[ai][bj][m][n], 0, 0, 0); __builtin_amdgcn_s_setprio(0); } while (0)
; #define PG8_WAIT_V(n) asm volatile("s_waitcnt vmcnt(" #n ")" ::: "memory")
; #define PG8_WAIT_L(n) asm volatile("s_waitcnt lgkmcnt(" #n ")" ::: "memory")
; #define PG8_BAR __builtin_amdgcn_s_barrier()
; template <class Epi>
; __device__ __forceinline__ void gemm_phase(LAS unsigned char* lds, const Gemm g, const StaticOrder& S, const Epi& E, const int tid) {
;     ...
;             const bool last = (t == nt - 2);
;             const char* a1 = cA + (size_t)(t + 1) * kstep;
;             const char* a2 = last ? nA : cA + (size_t)(t + 2) * kstep; const char* b2 = last ? nB : cB + (size_t)(t + 2) * kstep;
;             const char* a3 = a2 + kstep; const char* b3 = b2 + kstep;
;             PG8_LDB(B0, 0, 0); PG8_SCHED; PG8_LDA(At, 0, 0); PG8_STAGE(PG8_SA(1, 1), a1 + hstep, voffA);
;             PG8_WAIT_L(8); PG8_BAR; PG8_WAIT_L(0); PG8_MMA(0, 0, At, B0); PG8_BAR; PG8_SCHED;
;             PG8_LDB(B1, 0, 1); PG8_STAGE(PG8_SB(0, 0), b2, voffB);
;             PG8_BAR; PG8_WAIT_L(0); PG8_MMA(0, 1, At, B1); PG8_BAR;
;             PG8_LDA(At, 0, 1); PG8_STAGE(PG8_SA(0, 0), a2, voffA);
;             PG8_BAR; PG8_WAIT_L(0); PG8_MMA(1, 0, At, B0); PG8_BAR; PG8_SCHED;
;             PG8_STAGE(PG8_SB(0, 1), b2 + hstep, voffB);
;             PG8_WAIT_V(6); PG8_BAR; PG8_MMA(1, 1, At, B1); PG8_BAR;
.Lgprio4:
.LBB0_141:
	s_add_u32 s20, s18, 0xfff80080
	s_addc_u32 s21, s19, -1
	s_add_i32 s50, 0, 0x10000
	v_add_u32_e32 v86, s50, v173
	ds_read_b128 v[66:69], v86
	ds_read_b128 v[70:73], v86 offset:1024
	ds_read_b128 v[82:85], v86 offset:2048
	ds_read_b128 v[86:89], v86 offset:3072
	s_cmp_eq_u32 s49, 28
	s_cselect_b32 s23, s13, s21
	s_cselect_b32 s22, s44, s20
	s_cselect_b32 s21, s11, s48
	s_cselect_b32 s20, s45, s47
	s_add_i32 m0, s3, 0xc000
	ds_read_b128 v[176:179], v174
	ds_read_b128 v[180:183], v174 offset:1024
	ds_read_b128 v[184:187], v174 offset:2048
	ds_read_b128 v[188:191], v174 offset:3072
	ds_read_b128 v[192:195], v174 offset:4096
	ds_read_b128 v[196:199], v174 offset:5120
	ds_read_b128 v[210:213], v174 offset:6144
	ds_read_b128 v[214:217], v174 offset:7168
	global_load_lds_dwordx4 v168, s[18:19]
	v_lshl_add_u64 v[170:171], s[18:19], 0, v[166:167]
	s_add_i32 m0, s3, 0xe000
	s_nop 0
	global_load_lds_dwordx4 v[170:171], off
	s_waitcnt lgkmcnt(8)
	s_barrier
	s_waitcnt lgkmcnt(0)
	v_mfma_f32_16x16x32_bf16 v[142:145], v[66:69], v[176:179], v[142:145]
	v_mfma_f32_16x16x32_bf16 v[138:141], v[82:85], v[176:179], v[138:141]
	v_mfma_f32_16x16x32_bf16 v[126:129], v[66:69], v[184:187], v[126:129]
	v_mfma_f32_16x16x32_bf16 v[122:125], v[82:85], v[184:187], v[122:125]
	v_mfma_f32_16x16x32_bf16 v[110:113], v[66:69], v[192:195], v[110:113]
	v_mfma_f32_16x16x32_bf16 v[106:109], v[82:85], v[192:195], v[106:109]
	v_mfma_f32_16x16x32_bf16 v[94:97], v[66:69], v[210:213], v[94:97]
	v_mfma_f32_16x16x32_bf16 v[90:93], v[82:85], v[210:213], v[90:93]
	v_mfma_f32_16x16x32_bf16 v[142:145], v[70:73], v[180:183], v[142:145]
	v_mfma_f32_16x16x32_bf16 v[138:141], v[86:89], v[180:183], v[138:141]
	v_mfma_f32_16x16x32_bf16 v[126:129], v[70:73], v[188:191], v[126:129]
	v_mfma_f32_16x16x32_bf16 v[122:125], v[86:89], v[188:191], v[122:125]
	v_mfma_f32_16x16x32_bf16 v[110:113], v[70:73], v[196:199], v[110:113]
	v_mfma_f32_16x16x32_bf16 v[106:109], v[86:89], v[196:199], v[106:109]
	v_mfma_f32_16x16x32_bf16 v[94:97], v[70:73], v[214:217], v[94:97]
	v_mfma_f32_16x16x32_bf16 v[90:93], v[86:89], v[214:217], v[90:93]
	s_barrier
	s_add_i32 s54, 0, 0x14000
	v_add_u32_e32 v170, s54, v173
	s_add_i32 s50, s50, s31
	ds_read_b128 v[218:221], v170
	ds_read_b128 v[222:225], v170 offset:1024
	ds_read_b128 v[226:229], v170 offset:2048
	ds_read_b128 v[230:233], v170 offset:3072
	v_lshl_add_u64 v[170:171], s[20:21], 0, v[0:1]
	s_mov_b32 m0, s50
	v_lshl_add_u64 v[200:201], s[20:21], 0, v[164:165]
	global_load_lds_dwordx4 v[170:171], off
	s_add_i32 m0, s50, 0x2000
	s_nop 0
	global_load_lds_dwordx4 v[200:201], off
	s_barrier
	s_waitcnt lgkmcnt(0)
	v_mfma_f32_16x16x32_bf16 v[134:137], v[218:221], v[176:179], v[134:137]
	v_mfma_f32_16x16x32_bf16 v[130:133], v[226:229], v[176:179], v[130:133]
	v_mfma_f32_16x16x32_bf16 v[118:121], v[218:221], v[184:187], v[118:121]
	v_mfma_f32_16x16x32_bf16 v[114:117], v[226:229], v[184:187], v[114:117]
	v_mfma_f32_16x16x32_bf16 v[102:105], v[218:221], v[192:195], v[102:105]
	v_mfma_f32_16x16x32_bf16 v[98:101], v[226:229], v[192:195], v[98:101]
	v_mfma_f32_16x16x32_bf16 v[78:81], v[218:221], v[210:213], v[78:81]
	v_mfma_f32_16x16x32_bf16 v[74:77], v[226:229], v[210:213], v[74:77]
	v_mfma_f32_16x16x32_bf16 v[134:137], v[222:225], v[180:183], v[134:137]
	v_mfma_f32_16x16x32_bf16 v[130:133], v[230:233], v[180:183], v[130:133]
	v_mfma_f32_16x16x32_bf16 v[118:121], v[222:225], v[188:191], v[118:121]
	v_mfma_f32_16x16x32_bf16 v[114:117], v[230:233], v[188:191], v[114:117]
	v_mfma_f32_16x16x32_bf16 v[102:105], v[222:225], v[196:199], v[102:105]
	v_mfma_f32_16x16x32_bf16 v[98:101], v[230:233], v[196:199], v[98:101]
	v_mfma_f32_16x16x32_bf16 v[78:81], v[222:225], v[214:217], v[78:81]
	v_mfma_f32_16x16x32_bf16 v[74:77], v[230:233], v[214:217], v[74:77]
	s_mov_b32 m0, s3
	v_lshl_add_u64 v[234:235], s[22:23], 0, v[160:161]
	s_barrier
	ds_read_b128 v[176:179], v174 offset:16384
	ds_read_b128 v[180:183], v174 offset:17408
	ds_read_b128 v[184:187], v174 offset:18432
	ds_read_b128 v[188:191], v174 offset:19456
	ds_read_b128 v[192:195], v174 offset:20480
	ds_read_b128 v[196:199], v174 offset:21504
	ds_read_b128 v[210:213], v174 offset:22528
	ds_read_b128 v[214:217], v174 offset:23552
	global_load_lds_dwordx4 v[234:235], off
	v_lshl_add_u64 v[236:237], s[22:23], 0, v[162:163]
	s_mov_b32 m0, s34
	s_nop 0
	global_load_lds_dwordx4 v[236:237], off
	s_barrier
	s_waitcnt lgkmcnt(0)
	v_mfma_f32_16x16x32_bf16 v[62:65], v[66:69], v[176:179], v[62:65]
	v_mfma_f32_16x16x32_bf16 v[58:61], v[82:85], v[176:179], v[58:61]
	v_mfma_f32_16x16x32_bf16 v[46:49], v[66:69], v[184:187], v[46:49]
	v_mfma_f32_16x16x32_bf16 v[42:45], v[82:85], v[184:187], v[42:45]
	v_mfma_f32_16x16x32_bf16 v[30:33], v[66:69], v[192:195], v[30:33]
	v_mfma_f32_16x16x32_bf16 v[26:29], v[82:85], v[192:195], v[26:29]
	v_mfma_f32_16x16x32_bf16 v[14:17], v[66:69], v[210:213], v[14:17]
	v_mfma_f32_16x16x32_bf16 v[10:13], v[82:85], v[210:213], v[10:13]
	v_mfma_f32_16x16x32_bf16 v[62:65], v[70:73], v[180:183], v[62:65]
	v_mfma_f32_16x16x32_bf16 v[58:61], v[86:89], v[180:183], v[58:61]
	v_mfma_f32_16x16x32_bf16 v[46:49], v[70:73], v[188:191], v[46:49]
	v_mfma_f32_16x16x32_bf16 v[42:45], v[86:89], v[188:191], v[42:45]
	v_mfma_f32_16x16x32_bf16 v[30:33], v[70:73], v[196:199], v[30:33]
	v_mfma_f32_16x16x32_bf16 v[26:29], v[86:89], v[196:199], v[26:29]
	v_mfma_f32_16x16x32_bf16 v[14:17], v[70:73], v[214:217], v[14:17]
	v_mfma_f32_16x16x32_bf16 v[10:13], v[86:89], v[214:217], v[10:13]
	s_barrier
	s_add_u32 s52, s20, 0x80000
	s_addc_u32 s53, s21, 0
	s_add_i32 s50, s54, s31
	s_mov_b32 m0, s50
	s_nop 0
	global_load_lds_dwordx4 v0, s[52:53]
	s_add_i32 m0, s50, 0x2000
	s_nop 0
	global_load_lds_dwordx4 v164, s[52:53]
	s_waitcnt vmcnt(6)
	s_barrier
; #define PG8_STAGE(bufoff, gbase, voff) do { _Pragma("unroll") for (int _i = 0; _i < 2; ++_i) \
;         __builtin_amdgcn_global_load_lds((const unsigned*)((const char*)(gbase) + (voff)[_i]), (LAS unsigned*)(lds + (bufoff) + ldsw + _i * 8192), 16, 0, 0); } while (0)
; #define PG8_LDA(dst, b, h) do { _Pragma("unroll") for (int m = 0; m < 4; ++m) _Pragma("unroll") for (int k = 0; k < 2; ++k) dst[m][k] = *(const LAS bf16x8*)(lds + PG8_SA(b, h) + aoff + m * 2048 + k * 1024); } while (0)
; #define PG8_LDB(dst, b, h) do { _Pragma("unroll") for (int n = 0; n < 2; ++n) _Pragma("unroll") for (int k = 0; k < 2; ++k) dst[n][k] = *(const LAS bf16x8*)(lds + PG8_SB(b, h) + boff + n * 2048 + k * 1024); } while (0)
; #define PG8_MMA(ai, bj, At, Bt) do { __builtin_amdgcn_s_setprio(1); _Pragma("unroll") for (int m = 0; m < 4; ++m) _Pragma("unroll") for (int n = 0; n < 2; ++n) _Pragma("unroll") for (int k = 0; k < 2; ++k) \
;         acc[ai][bj][m][n] = __builtin_amdgcn_mfma_f32_16x16x32_bf16(Bt[n][k], At[m][k], acc[ai][bj][m][n], 0, 0, 0); __builtin_amdgcn_s_setprio(0); } while (0)
; #define PG8_WAIT_V(n) asm volatile("s_waitcnt vmcnt(" #n ")" ::: "memory")
; #define PG8_WAIT_L(n) asm volatile("s_waitcnt lgkmcnt(" #n ")" ::: "memory")
; #define PG8_BAR __builtin_amdgcn_s_barrier()
; #define PG8_SCHED __builtin_amdgcn_sched_barrier(0)
; template <class Epi>
; __device__ __forceinline__ void gemm_phase(LAS unsigned char* lds, const Gemm g, const StaticOrder& S, const Epi& E, const int tid) {
;     ...
;             PG8_WAIT_V(6); PG8_BAR; PG8_MMA(1, 1, At, B1); PG8_BAR;
;             PG8_LDB(B0, 1, 0); PG8_SCHED; PG8_LDA(At, 1, 0); PG8_STAGE(PG8_SA(0, 1), a2 + hstep, voffA);
;             PG8_WAIT_L(8); PG8_BAR; PG8_WAIT_L(0); PG8_MMA(0, 0, At, B0); PG8_BAR; PG8_SCHED;
;             PG8_LDB(B1, 1, 1); PG8_STAGE(PG8_SB(1, 0), b3, voffB);
;             PG8_BAR; PG8_WAIT_L(0); PG8_MMA(0, 1, At, B1); PG8_BAR;
;             PG8_LDA(At, 1, 1); PG8_STAGE(PG8_SA(1, 0), a3, voffA);
;             PG8_BAR; PG8_WAIT_L(0); PG8_MMA(1, 0, At, B0); PG8_BAR; PG8_SCHED;
	v_mfma_f32_16x16x32_bf16 v[54:57], v[218:221], v[176:179], v[54:57]
	v_mfma_f32_16x16x32_bf16 v[50:53], v[226:229], v[176:179], v[50:53]
	v_mfma_f32_16x16x32_bf16 v[38:41], v[218:221], v[184:187], v[38:41]
	v_mfma_f32_16x16x32_bf16 v[34:37], v[226:229], v[184:187], v[34:37]
	v_mfma_f32_16x16x32_bf16 v[22:25], v[218:221], v[192:195], v[22:25]
	v_mfma_f32_16x16x32_bf16 v[18:21], v[226:229], v[192:195], v[18:21]
	v_mfma_f32_16x16x32_bf16 v[6:9], v[218:221], v[210:213], v[6:9]
	v_mfma_f32_16x16x32_bf16 v[2:5], v[226:229], v[210:213], v[2:5]
	v_mfma_f32_16x16x32_bf16 v[54:57], v[222:225], v[180:183], v[54:57]
	v_mfma_f32_16x16x32_bf16 v[50:53], v[230:233], v[180:183], v[50:53]
	v_mfma_f32_16x16x32_bf16 v[38:41], v[222:225], v[188:191], v[38:41]
	v_mfma_f32_16x16x32_bf16 v[34:37], v[230:233], v[188:191], v[34:37]
	v_mfma_f32_16x16x32_bf16 v[22:25], v[222:225], v[196:199], v[22:25]
	v_mfma_f32_16x16x32_bf16 v[18:21], v[230:233], v[196:199], v[18:21]
	v_mfma_f32_16x16x32_bf16 v[6:9], v[222:225], v[214:217], v[6:9]
	v_mfma_f32_16x16x32_bf16 v[2:5], v[230:233], v[214:217], v[2:5]
	s_add_i32 s50, 0, 0x18000
	v_add_u32_e32 v86, s50, v173
	s_barrier
	ds_read_b128 v[66:69], v86
	ds_read_b128 v[70:73], v86 offset:1024
	ds_read_b128 v[82:85], v86 offset:2048
	ds_read_b128 v[86:89], v86 offset:3072
	s_add_u32 s22, s22, 0x80000
	s_addc_u32 s23, s23, 0
	s_mov_b32 m0, s35
	ds_read_b128 v[176:179], v174 offset:32768
	ds_read_b128 v[180:183], v174 offset:33792
	ds_read_b128 v[184:187], v174 offset:34816
	ds_read_b128 v[188:191], v174 offset:35840
	ds_read_b128 v[192:195], v174 offset:36864
	ds_read_b128 v[196:199], v174 offset:37888
	ds_read_b128 v[210:213], v174 offset:38912
	ds_read_b128 v[214:217], v174 offset:39936
	global_load_lds_dwordx4 v160, s[22:23]
	s_mov_b32 m0, s36
	s_nop 0
	global_load_lds_dwordx4 v162, s[22:23]
	s_waitcnt lgkmcnt(8)
	s_barrier
	s_waitcnt lgkmcnt(0)
	v_mfma_f32_16x16x32_bf16 v[142:145], v[66:69], v[176:179], v[142:145]
	v_mfma_f32_16x16x32_bf16 v[138:141], v[82:85], v[176:179], v[138:141]
	v_mfma_f32_16x16x32_bf16 v[126:129], v[66:69], v[184:187], v[126:129]
	v_mfma_f32_16x16x32_bf16 v[122:125], v[82:85], v[184:187], v[122:125]
	v_mfma_f32_16x16x32_bf16 v[110:113], v[66:69], v[192:195], v[110:113]
	v_mfma_f32_16x16x32_bf16 v[106:109], v[82:85], v[192:195], v[106:109]
	v_mfma_f32_16x16x32_bf16 v[94:97], v[66:69], v[210:213], v[94:97]
	v_mfma_f32_16x16x32_bf16 v[90:93], v[82:85], v[210:213], v[90:93]
	v_mfma_f32_16x16x32_bf16 v[142:145], v[70:73], v[180:183], v[142:145]
	v_mfma_f32_16x16x32_bf16 v[138:141], v[86:89], v[180:183], v[138:141]
	v_mfma_f32_16x16x32_bf16 v[126:129], v[70:73], v[188:191], v[126:129]
	v_mfma_f32_16x16x32_bf16 v[122:125], v[86:89], v[188:191], v[122:125]
	v_mfma_f32_16x16x32_bf16 v[110:113], v[70:73], v[196:199], v[110:113]
	v_mfma_f32_16x16x32_bf16 v[106:109], v[86:89], v[196:199], v[106:109]
	v_mfma_f32_16x16x32_bf16 v[94:97], v[70:73], v[214:217], v[94:97]
	v_mfma_f32_16x16x32_bf16 v[90:93], v[86:89], v[214:217], v[90:93]
	s_barrier
	s_add_i32 s22, 0, 0x1c000
	s_add_i32 s23, s50, s31
	v_add_u32_e32 v175, s22, v173
	v_lshl_add_u64 v[170:171], v[170:171], 0, s[56:57]
	s_mov_b32 m0, s23
	ds_read_b128 v[218:221], v175
	ds_read_b128 v[222:225], v175 offset:1024
	ds_read_b128 v[226:229], v175 offset:2048
	ds_read_b128 v[230:233], v175 offset:3072
	global_load_lds_dwordx4 v[170:171], off
	v_lshl_add_u64 v[170:171], v[200:201], 0, s[56:57]
	s_add_i32 m0, s23, 0x2000
	s_nop 0
	global_load_lds_dwordx4 v[170:171], off
	s_barrier
	s_waitcnt lgkmcnt(0)
	v_mfma_f32_16x16x32_bf16 v[134:137], v[218:221], v[176:179], v[134:137]
	v_mfma_f32_16x16x32_bf16 v[130:133], v[226:229], v[176:179], v[130:133]
	v_mfma_f32_16x16x32_bf16 v[118:121], v[218:221], v[184:187], v[118:121]
	v_mfma_f32_16x16x32_bf16 v[114:117], v[226:229], v[184:187], v[114:117]
	v_mfma_f32_16x16x32_bf16 v[102:105], v[218:221], v[192:195], v[102:105]
	v_mfma_f32_16x16x32_bf16 v[98:101], v[226:229], v[192:195], v[98:101]
	v_mfma_f32_16x16x32_bf16 v[78:81], v[218:221], v[210:213], v[78:81]
	v_mfma_f32_16x16x32_bf16 v[74:77], v[226:229], v[210:213], v[74:77]
	v_mfma_f32_16x16x32_bf16 v[134:137], v[222:225], v[180:183], v[134:137]
	v_mfma_f32_16x16x32_bf16 v[130:133], v[230:233], v[180:183], v[130:133]
	v_mfma_f32_16x16x32_bf16 v[118:121], v[222:225], v[188:191], v[118:121]
	v_mfma_f32_16x16x32_bf16 v[114:117], v[230:233], v[188:191], v[114:117]
	v_mfma_f32_16x16x32_bf16 v[102:105], v[222:225], v[196:199], v[102:105]
	v_mfma_f32_16x16x32_bf16 v[98:101], v[230:233], v[196:199], v[98:101]
	v_mfma_f32_16x16x32_bf16 v[78:81], v[222:225], v[214:217], v[78:81]
	v_mfma_f32_16x16x32_bf16 v[74:77], v[230:233], v[214:217], v[74:77]
	s_mov_b32 m0, s39
	v_lshl_add_u64 v[170:171], v[234:235], 0, s[56:57]
	s_barrier
	ds_read_b128 v[176:179], v174 offset:49152
	ds_read_b128 v[180:183], v174 offset:50176
	ds_read_b128 v[184:187], v174 offset:51200
	ds_read_b128 v[188:191], v174 offset:52224
	ds_read_b128 v[192:195], v174 offset:53248
	ds_read_b128 v[196:199], v174 offset:54272
	ds_read_b128 v[210:213], v174 offset:55296
	ds_read_b128 v[214:217], v174 offset:56320
	global_load_lds_dwordx4 v[170:171], off
	v_lshl_add_u64 v[170:171], v[236:237], 0, s[56:57]
	s_mov_b32 m0, s40
	s_nop 0
	global_load_lds_dwordx4 v[170:171], off
	s_barrier
; __device__ __forceinline__ unsigned pk2(float lo, float hi) { f32x2 v = {lo, hi}; return __builtin_bit_cast(unsigned, __builtin_convertvector(v, bf16x2_t)); }
; __device__ __forceinline__ float bf_lo(unsigned w) { return __uint_as_float(w << 16); }
;     __device__ __forceinline__ void operator()(const f32x4 (&acc)[2][2][4][2], const Unit& u, int wr, int wc, int fr, int fq) const {
;         asm volatile("" : "+v"(fr), "+v"(fq));
;         const int row0 = u.pm * BM + wr * 64 + fr, col0 = u.pn * BM + wc * 32 + 8 * fq;
;         const float* gp = gate + (size_t)(u.pm >> 5) * 12288 + col0;
;         f32x4 gv[2][2];
; #pragma unroll
;         for (int bj = 0; bj < 2; ++bj)
; #pragma unroll
;             for (int n = 0; n < 2; ++n) gv[bj][n] = *(const f32x4*)(gp + bj * HALF + 4 * n);
; #pragma unroll
;         for (int ai = 0; ai < 2; ++ai)
; #pragma unroll
;             for (int m = 0; m < 4; ++m) {
;                 const size_t ro = (size_t)(row0 + ai * HALF + m * 16) * DM + col0;
; #pragma unroll
;                 for (int bj = 0; bj < 2; ++bj) {
;                     f32x4 r0, r1;
;                     if (RB) { const u32x4 rw = *(const u32x4*)((const bf16_t*)resid + ro + bj * HALF);
;                         r0 = (f32x4){bf_lo(rw.x), bf_hi(rw.x), bf_lo(rw.y), bf_hi(rw.y)}; r1 = (f32x4){bf_lo(rw.z), bf_hi(rw.z), bf_lo(rw.w), bf_hi(rw.w)}; }
;                     else { r0 = *(const f32x4*)((const float*)resid + ro + bj * HALF); r1 = *(const f32x4*)((const float*)resid + ro + bj * HALF + 4); }
;                     const f32x4 v0 = r0 + gv[bj][0] * acc[ai][bj][m][0], v1 = r1 + gv[bj][1] * acc[ai][bj][m][1];
;                     if (OB) { u32x4 w; w.x = pk2(v0[0], v0[1]); w.y = pk2(v0[2], v0[3]); w.z = pk2(v1[0], v1[1]); w.w = pk2(v1[2], v1[3]); *(u32x4*)((bf16_t*)out + ro + bj * HALF) = w; }
;                     else { *(f32x4*)((float*)out + ro + bj * HALF) = v0; *(f32x4*)((float*)out + ro + bj * HALF + 4) = v1; }
;                 }
; template <class Epi>
; __device__ __forceinline__ void gemm_phase(LAS unsigned char* lds, const Gemm g, const StaticOrder& S, const Epi& E, const int tid) {
;     ...
;             PG8_BAR; PG8_WAIT_L(0); PG8_MMA(1, 0, At, B0); PG8_BAR; PG8_SCHED;
;             PG8_STAGE(PG8_SB(1, 1), b3 + hstep, voffB);
;             PG8_WAIT_V(6); PG8_BAR; PG8_MMA(1, 1, At, B1); PG8_BAR;
;         }
;         E(acc, cur, wr, wc, fr, fq);
	s_waitcnt lgkmcnt(0)
	v_mfma_f32_16x16x32_bf16 v[62:65], v[66:69], v[176:179], v[62:65]
	v_mfma_f32_16x16x32_bf16 v[58:61], v[82:85], v[176:179], v[58:61]
	v_mfma_f32_16x16x32_bf16 v[46:49], v[66:69], v[184:187], v[46:49]
	v_mfma_f32_16x16x32_bf16 v[42:45], v[82:85], v[184:187], v[42:45]
	v_mfma_f32_16x16x32_bf16 v[30:33], v[66:69], v[192:195], v[30:33]
	v_mfma_f32_16x16x32_bf16 v[26:29], v[82:85], v[192:195], v[26:29]
	v_mfma_f32_16x16x32_bf16 v[14:17], v[66:69], v[210:213], v[14:17]
	v_mfma_f32_16x16x32_bf16 v[10:13], v[82:85], v[210:213], v[10:13]
	v_mfma_f32_16x16x32_bf16 v[62:65], v[70:73], v[180:183], v[62:65]
	v_mfma_f32_16x16x32_bf16 v[58:61], v[86:89], v[180:183], v[58:61]
	v_mfma_f32_16x16x32_bf16 v[46:49], v[70:73], v[188:191], v[46:49]
	v_mfma_f32_16x16x32_bf16 v[42:45], v[86:89], v[188:191], v[42:45]
	v_mfma_f32_16x16x32_bf16 v[30:33], v[70:73], v[196:199], v[30:33]
	v_mfma_f32_16x16x32_bf16 v[26:29], v[86:89], v[196:199], v[26:29]
	v_mfma_f32_16x16x32_bf16 v[14:17], v[70:73], v[214:217], v[14:17]
	v_mfma_f32_16x16x32_bf16 v[10:13], v[86:89], v[214:217], v[10:13]
	s_barrier
	s_add_i32 s49, s49, 2
	s_add_u32 s47, s47, 0x100
	s_addc_u32 s48, s48, 0
	s_add_u32 s18, s18, 0x100
	s_addc_u32 s19, s19, 0
	s_add_u32 s20, s20, 0x80080
	s_addc_u32 s21, s21, 0
	s_add_i32 s22, s22, s31
	s_mov_b32 m0, s22
	s_nop 0
	global_load_lds_dwordx4 v0, s[20:21]
	s_add_i32 m0, s22, 0x2000
	s_nop 0
	global_load_lds_dwordx4 v164, s[20:21]
	s_waitcnt vmcnt(6)
	s_barrier
	v_mfma_f32_16x16x32_bf16 v[54:57], v[218:221], v[176:179], v[54:57]
	v_mfma_f32_16x16x32_bf16 v[50:53], v[226:229], v[176:179], v[50:53]
	v_mfma_f32_16x16x32_bf16 v[38:41], v[218:221], v[184:187], v[38:41]
	v_mfma_f32_16x16x32_bf16 v[34:37], v[226:229], v[184:187], v[34:37]
	v_mfma_f32_16x16x32_bf16 v[22:25], v[218:221], v[192:195], v[22:25]
	v_mfma_f32_16x16x32_bf16 v[18:21], v[226:229], v[192:195], v[18:21]
	v_mfma_f32_16x16x32_bf16 v[6:9], v[218:221], v[210:213], v[6:9]
	v_mfma_f32_16x16x32_bf16 v[2:5], v[226:229], v[210:213], v[2:5]
	v_mfma_f32_16x16x32_bf16 v[54:57], v[222:225], v[180:183], v[54:57]
	v_mfma_f32_16x16x32_bf16 v[50:53], v[230:233], v[180:183], v[50:53]
	v_mfma_f32_16x16x32_bf16 v[38:41], v[222:225], v[188:191], v[38:41]
	v_mfma_f32_16x16x32_bf16 v[34:37], v[230:233], v[188:191], v[34:37]
	v_mfma_f32_16x16x32_bf16 v[22:25], v[222:225], v[196:199], v[22:25]
	v_mfma_f32_16x16x32_bf16 v[18:21], v[230:233], v[196:199], v[18:21]
	v_mfma_f32_16x16x32_bf16 v[6:9], v[222:225], v[214:217], v[6:9]
	v_mfma_f32_16x16x32_bf16 v[2:5], v[230:233], v[214:217], v[2:5]
	s_cmp_gt_u32 s49, 29
	s_barrier
	s_cbranch_scc0 .LBB0_141
	s_setprio 0
	s_lshl_b32 s11, s2, 8
	s_lshl_b32 s13, s43, 8
	v_mov_b32_e32 v66, v172
	v_mov_b32_e32 v175, v159
	s_add_i32 s11, s11, s37
	s_or_b32 s13, s13, s38
	s_ashr_i32 s2, s2, 5
	s_mov_b32 s43, s10
	v_lshl_add_u32 v170, v66, 3, s13
	s_mul_hi_i32 s13, s2, 0xc000
	s_mul_i32 s2, s2, 0xc000
	v_add_u32_e32 v176, s11, v175
	s_add_u32 s18, s27, s2
	v_ashrrev_i32_e32 v177, 31, v176
	s_addc_u32 s19, s28, s13
	v_ashrrev_i32_e32 v171, 31, v170
	v_lshlrev_b64 v[176:177], 11, v[176:177]
	v_lshl_add_u64 v[70:71], v[170:171], 2, s[18:19]
	v_lshl_add_u64 v[170:171], v[176:177], 0, v[170:171]
	v_lshl_add_u64 v[184:185], v[170:171], 2, s[8:9]
	global_load_dwordx4 v[82:85], v[70:71], off offset:16
	global_load_dwordx4 v[86:89], v[70:71], off
	global_load_dwordx4 v[66:69], v[70:71], off offset:528
	s_nop 0
	global_load_dwordx4 v[70:73], v[70:71], off offset:512
	v_lshlrev_b32_e32 v175, 2, v170
	v_lshlrev_b32_e32 v200, 1, v170
	s_mov_b64 s[92:93], s[8:9]
	s_mov_b64 s[94:95], s[6:7]
	global_load_dwordx4 v[176:179], v175, s[92:93]
	global_load_dwordx4 v[180:183], v175, s[92:93] offset:16
	global_load_dwordx4 v[184:187], v175, s[92:93] offset:512
	global_load_dwordx4 v[188:191], v175, s[92:93] offset:528
	s_add_u32 s92, s92, 0x20000
	s_addc_u32 s93, s93, 0
	global_load_dwordx4 v[192:195], v175, s[92:93]
	global_load_dwordx4 v[196:199], v175, s[92:93] offset:16
	global_load_dwordx4 v[210:213], v175, s[92:93] offset:512
	global_load_dwordx4 v[214:217], v175, s[92:93] offset:528
	s_add_u32 s92, s92, 0x20000
	s_addc_u32 s93, s93, 0
	global_load_dwordx4 v[218:221], v175, s[92:93]
	global_load_dwordx4 v[222:225], v175, s[92:93] offset:16
	global_load_dwordx4 v[226:229], v175, s[92:93] offset:512
	global_load_dwordx4 v[230:233], v175, s[92:93] offset:528
	s_waitcnt vmcnt(10)
	v_pk_fma_f32 v[142:143], v[142:143], v[86:87], v[176:177]
	v_pk_fma_f32 v[144:145], v[144:145], v[88:89], v[178:179]
	v_pk_fma_f32 v[138:139], v[138:139], v[82:83], v[180:181]
	v_pk_fma_f32 v[140:141], v[140:141], v[84:85], v[182:183]
	s_add_u32 s92, s92, 0x20000
	s_addc_u32 s93, s93, 0
	global_load_dwordx4 v[176:179], v175, s[92:93]
	global_load_dwordx4 v[180:183], v175, s[92:93] offset:16
	v_cvt_pk_bf16_f32 v142, v142, v143
	v_cvt_pk_bf16_f32 v143, v144, v145
	v_cvt_pk_bf16_f32 v144, v138, v139
	v_cvt_pk_bf16_f32 v145, v140, v141
	global_store_dwordx4 v200, v[142:145], s[94:95]
	s_waitcnt vmcnt(11)
	v_pk_fma_f32 v[134:135], v[134:135], v[70:71], v[184:185]
	v_pk_fma_f32 v[136:137], v[136:137], v[72:73], v[186:187]
	v_pk_fma_f32 v[130:131], v[130:131], v[66:67], v[188:189]
	v_pk_fma_f32 v[132:133], v[132:133], v[68:69], v[190:191]
	global_load_dwordx4 v[184:187], v175, s[92:93] offset:512
	global_load_dwordx4 v[188:191], v175, s[92:93] offset:528
	v_cvt_pk_bf16_f32 v134, v134, v135
	v_cvt_pk_bf16_f32 v135, v136, v137
	v_cvt_pk_bf16_f32 v136, v130, v131
	v_cvt_pk_bf16_f32 v137, v132, v133
	global_store_dwordx4 v200, v[134:137], s[94:95] offset:256
	s_waitcnt vmcnt(12)
; __device__ __forceinline__ unsigned pk2(float lo, float hi) { f32x2 v = {lo, hi}; return __builtin_bit_cast(unsigned, __builtin_convertvector(v, bf16x2_t)); }
; __device__ __forceinline__ float bf_lo(unsigned w) { return __uint_as_float(w << 16); }
; __device__ __forceinline__ float bf_hi(unsigned w) { return __uint_as_float(w & 0xffff0000u); }
;     __device__ __forceinline__ void operator()(const f32x4 (&acc)[2][2][4][2], const Unit& u, int wr, int wc, int fr, int fq) const {
;     ...
;             for (int m = 0; m < 4; ++m) {
;                 const size_t ro = (size_t)(row0 + ai * HALF + m * 16) * DM + col0;
; #pragma unroll
;                 for (int bj = 0; bj < 2; ++bj) {
;                     f32x4 r0, r1;
;                     if (RB) { const u32x4 rw = *(const u32x4*)((const bf16_t*)resid + ro + bj * HALF);
;                         r0 = (f32x4){bf_lo(rw.x), bf_hi(rw.x), bf_lo(rw.y), bf_hi(rw.y)}; r1 = (f32x4){bf_lo(rw.z), bf_hi(rw.z), bf_lo(rw.w), bf_hi(rw.w)}; }
;                     else { r0 = *(const f32x4*)((const float*)resid + ro + bj * HALF); r1 = *(const f32x4*)((const float*)resid + ro + bj * HALF + 4); }
;                     const f32x4 v0 = r0 + gv[bj][0] * acc[ai][bj][m][0], v1 = r1 + gv[bj][1] * acc[ai][bj][m][1];
;                     if (OB) { u32x4 w; w.x = pk2(v0[0], v0[1]); w.y = pk2(v0[2], v0[3]); w.z = pk2(v1[0], v1[1]); w.w = pk2(v1[2], v1[3]); *(u32x4*)((bf16_t*)out + ro + bj * HALF) = w; }
;                     else { *(f32x4*)((float*)out + ro + bj * HALF) = v0; *(f32x4*)((float*)out + ro + bj * HALF + 4) = v1; }
;                 }
	v_pk_fma_f32 v[126:127], v[126:127], v[86:87], v[192:193]
	v_pk_fma_f32 v[128:129], v[128:129], v[88:89], v[194:195]
	v_pk_fma_f32 v[122:123], v[122:123], v[82:83], v[196:197]
	v_pk_fma_f32 v[124:125], v[124:125], v[84:85], v[198:199]
	s_add_u32 s92, s92, 0xa0000
	s_addc_u32 s93, s93, 0
	global_load_dwordx4 v[192:195], v175, s[92:93]
	global_load_dwordx4 v[196:199], v175, s[92:93] offset:16
	s_add_u32 s94, s94, 0x10000
	s_addc_u32 s95, s95, 0
	v_cvt_pk_bf16_f32 v126, v126, v127
	v_cvt_pk_bf16_f32 v127, v128, v129
	v_cvt_pk_bf16_f32 v128, v122, v123
	v_cvt_pk_bf16_f32 v129, v124, v125
	global_store_dwordx4 v200, v[126:129], s[94:95]
	s_waitcnt vmcnt(13)
	v_pk_fma_f32 v[118:119], v[118:119], v[70:71], v[210:211]
	v_pk_fma_f32 v[120:121], v[120:121], v[72:73], v[212:213]
	v_pk_fma_f32 v[114:115], v[114:115], v[66:67], v[214:215]
	v_pk_fma_f32 v[116:117], v[116:117], v[68:69], v[216:217]
	global_load_dwordx4 v[210:213], v175, s[92:93] offset:512
	global_load_dwordx4 v[214:217], v175, s[92:93] offset:528
	v_cvt_pk_bf16_f32 v118, v118, v119
	v_cvt_pk_bf16_f32 v119, v120, v121
	v_cvt_pk_bf16_f32 v120, v114, v115
	v_cvt_pk_bf16_f32 v121, v116, v117
	global_store_dwordx4 v200, v[118:121], s[94:95] offset:256
	s_waitcnt vmcnt(14)
	v_pk_fma_f32 v[110:111], v[110:111], v[86:87], v[218:219]
	v_pk_fma_f32 v[112:113], v[112:113], v[88:89], v[220:221]
	v_pk_fma_f32 v[106:107], v[106:107], v[82:83], v[222:223]
	v_pk_fma_f32 v[108:109], v[108:109], v[84:85], v[224:225]
	s_add_u32 s92, s92, 0x20000
	s_addc_u32 s93, s93, 0
	global_load_dwordx4 v[218:221], v175, s[92:93]
	global_load_dwordx4 v[222:225], v175, s[92:93] offset:16
	s_add_u32 s94, s94, 0x10000
	s_addc_u32 s95, s95, 0
	v_cvt_pk_bf16_f32 v110, v110, v111
	v_cvt_pk_bf16_f32 v111, v112, v113
	v_cvt_pk_bf16_f32 v112, v106, v107
	v_cvt_pk_bf16_f32 v113, v108, v109
	global_store_dwordx4 v200, v[110:113], s[94:95]
	s_waitcnt vmcnt(15)
	v_pk_fma_f32 v[102:103], v[102:103], v[70:71], v[226:227]
	v_pk_fma_f32 v[104:105], v[104:105], v[72:73], v[228:229]
	v_pk_fma_f32 v[98:99], v[98:99], v[66:67], v[230:231]
	v_pk_fma_f32 v[100:101], v[100:101], v[68:69], v[232:233]
	global_load_dwordx4 v[226:229], v175, s[92:93] offset:512
	global_load_dwordx4 v[230:233], v175, s[92:93] offset:528
	v_cvt_pk_bf16_f32 v102, v102, v103
	v_cvt_pk_bf16_f32 v103, v104, v105
	v_cvt_pk_bf16_f32 v104, v98, v99
	v_cvt_pk_bf16_f32 v105, v100, v101
	global_store_dwordx4 v200, v[102:105], s[94:95] offset:256
	s_waitcnt vmcnt(16)
	v_pk_fma_f32 v[94:95], v[94:95], v[86:87], v[176:177]
	v_pk_fma_f32 v[96:97], v[96:97], v[88:89], v[178:179]
	v_pk_fma_f32 v[90:91], v[90:91], v[82:83], v[180:181]
	v_pk_fma_f32 v[92:93], v[92:93], v[84:85], v[182:183]
	s_add_u32 s92, s92, 0x20000
	s_addc_u32 s93, s93, 0
	global_load_dwordx4 v[176:179], v175, s[92:93]
	global_load_dwordx4 v[180:183], v175, s[92:93] offset:16
	s_add_u32 s94, s94, 0x10000
	s_addc_u32 s95, s95, 0
	v_cvt_pk_bf16_f32 v94, v94, v95
	v_cvt_pk_bf16_f32 v95, v96, v97
	v_cvt_pk_bf16_f32 v96, v90, v91
	v_cvt_pk_bf16_f32 v97, v92, v93
	global_store_dwordx4 v200, v[94:97], s[94:95]
	s_waitcnt vmcnt(16)
	v_pk_fma_f32 v[78:79], v[78:79], v[70:71], v[184:185]
	v_pk_fma_f32 v[80:81], v[80:81], v[72:73], v[186:187]
	v_pk_fma_f32 v[74:75], v[74:75], v[66:67], v[188:189]
	v_pk_fma_f32 v[76:77], v[76:77], v[68:69], v[190:191]
	global_load_dwordx4 v[184:187], v175, s[92:93] offset:512
	global_load_dwordx4 v[188:191], v175, s[92:93] offset:528
	v_cvt_pk_bf16_f32 v78, v78, v79
	v_cvt_pk_bf16_f32 v79, v80, v81
	v_cvt_pk_bf16_f32 v80, v74, v75
	v_cvt_pk_bf16_f32 v81, v76, v77
	global_store_dwordx4 v200, v[78:81], s[94:95] offset:256
	s_waitcnt vmcnt(16)
; __device__ __forceinline__ unsigned pk2(float lo, float hi) { f32x2 v = {lo, hi}; return __builtin_bit_cast(unsigned, __builtin_convertvector(v, bf16x2_t)); }
; __device__ __forceinline__ float bf_lo(unsigned w) { return __uint_as_float(w << 16); }
; __device__ __forceinline__ float bf_hi(unsigned w) { return __uint_as_float(w & 0xffff0000u); }
; #define PG8_WAIT_V(n) asm volatile("s_waitcnt vmcnt(" #n ")" ::: "memory")
; #define PG8_BAR __builtin_amdgcn_s_barrier()
;     __device__ __forceinline__ void operator()(const f32x4 (&acc)[2][2][4][2], const Unit& u, int wr, int wc, int fr, int fq) const {
;     ...
;             for (int m = 0; m < 4; ++m) {
;                 const size_t ro = (size_t)(row0 + ai * HALF + m * 16) * DM + col0;
; #pragma unroll
;                 for (int bj = 0; bj < 2; ++bj) {
;                     f32x4 r0, r1;
;                     if (RB) { const u32x4 rw = *(const u32x4*)((const bf16_t*)resid + ro + bj * HALF);
;                         r0 = (f32x4){bf_lo(rw.x), bf_hi(rw.x), bf_lo(rw.y), bf_hi(rw.y)}; r1 = (f32x4){bf_lo(rw.z), bf_hi(rw.z), bf_lo(rw.w), bf_hi(rw.w)}; }
;                     else { r0 = *(const f32x4*)((const float*)resid + ro + bj * HALF); r1 = *(const f32x4*)((const float*)resid + ro + bj * HALF + 4); }
;                     const f32x4 v0 = r0 + gv[bj][0] * acc[ai][bj][m][0], v1 = r1 + gv[bj][1] * acc[ai][bj][m][1];
;                     if (OB) { u32x4 w; w.x = pk2(v0[0], v0[1]); w.y = pk2(v0[2], v0[3]); w.z = pk2(v1[0], v1[1]); w.w = pk2(v1[2], v1[3]); *(u32x4*)((bf16_t*)out + ro + bj * HALF) = w; }
;                     else { *(f32x4*)((float*)out + ro + bj * HALF) = v0; *(f32x4*)((float*)out + ro + bj * HALF + 4) = v1; }
;                 }
; template <class Epi>
; __device__ __forceinline__ void gemm_phase(LAS unsigned char* lds, const Gemm g, const StaticOrder& S, const Epi& E, const int tid) {
;     ...
;         if (!has_next) break;
; #pragma unroll
;         for (int a = 0; a < 2; ++a)
; #pragma unroll
;             for (int b = 0; b < 2; ++b)
; #pragma unroll
;                 for (int m = 0; m < 4; ++m)
; #pragma unroll
;                     for (int n = 0; n < 2; ++n) acc[a][b][m][n] = (f32x4){0.f, 0.f, 0.f, 0.f};
;         cur = nxt; cA = nA; cB = nB; ++ui;
;     }
;     PG8_WAIT_V(0);
;     if (wr == 0) PG8_BAR;
	v_pk_fma_f32 v[62:63], v[62:63], v[86:87], v[192:193]
	v_pk_fma_f32 v[64:65], v[64:65], v[88:89], v[194:195]
	v_pk_fma_f32 v[58:59], v[58:59], v[82:83], v[196:197]
	v_pk_fma_f32 v[60:61], v[60:61], v[84:85], v[198:199]
	s_add_u32 s92, s92, 0x20000
	s_addc_u32 s93, s93, 0
	global_load_dwordx4 v[192:195], v175, s[92:93]
	global_load_dwordx4 v[196:199], v175, s[92:93] offset:16
	s_add_u32 s94, s94, 0x50000
	s_addc_u32 s95, s95, 0
	v_cvt_pk_bf16_f32 v62, v62, v63
	v_cvt_pk_bf16_f32 v63, v64, v65
	v_cvt_pk_bf16_f32 v64, v58, v59
	v_cvt_pk_bf16_f32 v65, v60, v61
	global_store_dwordx4 v200, v[62:65], s[94:95]
	s_waitcnt vmcnt(16)
	v_pk_fma_f32 v[54:55], v[54:55], v[70:71], v[210:211]
	v_pk_fma_f32 v[56:57], v[56:57], v[72:73], v[212:213]
	v_pk_fma_f32 v[50:51], v[50:51], v[66:67], v[214:215]
	v_pk_fma_f32 v[52:53], v[52:53], v[68:69], v[216:217]
	global_load_dwordx4 v[210:213], v175, s[92:93] offset:512
	global_load_dwordx4 v[214:217], v175, s[92:93] offset:528
	v_cvt_pk_bf16_f32 v54, v54, v55
	v_cvt_pk_bf16_f32 v55, v56, v57
	v_cvt_pk_bf16_f32 v56, v50, v51
	v_cvt_pk_bf16_f32 v57, v52, v53
	global_store_dwordx4 v200, v[54:57], s[94:95] offset:256
	s_waitcnt vmcnt(16)
	v_pk_fma_f32 v[46:47], v[46:47], v[86:87], v[218:219]
	v_pk_fma_f32 v[48:49], v[48:49], v[88:89], v[220:221]
	v_pk_fma_f32 v[42:43], v[42:43], v[82:83], v[222:223]
	v_pk_fma_f32 v[44:45], v[44:45], v[84:85], v[224:225]
	s_add_u32 s94, s94, 0x10000
	s_addc_u32 s95, s95, 0
	v_cvt_pk_bf16_f32 v46, v46, v47
	v_cvt_pk_bf16_f32 v47, v48, v49
	v_cvt_pk_bf16_f32 v48, v42, v43
	v_cvt_pk_bf16_f32 v49, v44, v45
	global_store_dwordx4 v200, v[46:49], s[94:95]
	s_waitcnt vmcnt(14)
	v_pk_fma_f32 v[38:39], v[38:39], v[70:71], v[226:227]
	v_pk_fma_f32 v[40:41], v[40:41], v[72:73], v[228:229]
	v_pk_fma_f32 v[34:35], v[34:35], v[66:67], v[230:231]
	v_pk_fma_f32 v[36:37], v[36:37], v[68:69], v[232:233]
	v_cvt_pk_bf16_f32 v38, v38, v39
	v_cvt_pk_bf16_f32 v39, v40, v41
	v_cvt_pk_bf16_f32 v40, v34, v35
	v_cvt_pk_bf16_f32 v41, v36, v37
	global_store_dwordx4 v200, v[38:41], s[94:95] offset:256
	s_waitcnt vmcnt(12)
	v_pk_fma_f32 v[30:31], v[30:31], v[86:87], v[176:177]
	v_pk_fma_f32 v[32:33], v[32:33], v[88:89], v[178:179]
	v_pk_fma_f32 v[26:27], v[26:27], v[82:83], v[180:181]
	v_pk_fma_f32 v[28:29], v[28:29], v[84:85], v[182:183]
	s_add_u32 s94, s94, 0x10000
	s_addc_u32 s95, s95, 0
	v_cvt_pk_bf16_f32 v30, v30, v31
	v_cvt_pk_bf16_f32 v31, v32, v33
	v_cvt_pk_bf16_f32 v32, v26, v27
	v_cvt_pk_bf16_f32 v33, v28, v29
	global_store_dwordx4 v200, v[30:33], s[94:95]
	s_waitcnt vmcnt(10)
	v_pk_fma_f32 v[22:23], v[22:23], v[70:71], v[184:185]
	v_pk_fma_f32 v[24:25], v[24:25], v[72:73], v[186:187]
	v_pk_fma_f32 v[18:19], v[18:19], v[66:67], v[188:189]
	v_pk_fma_f32 v[20:21], v[20:21], v[68:69], v[190:191]
	v_cvt_pk_bf16_f32 v22, v22, v23
	v_cvt_pk_bf16_f32 v23, v24, v25
	v_cvt_pk_bf16_f32 v24, v18, v19
	v_cvt_pk_bf16_f32 v25, v20, v21
	global_store_dwordx4 v200, v[22:25], s[94:95] offset:256
	s_waitcnt vmcnt(8)
	v_pk_fma_f32 v[14:15], v[14:15], v[86:87], v[192:193]
	v_pk_fma_f32 v[16:17], v[16:17], v[88:89], v[194:195]
	v_pk_fma_f32 v[10:11], v[10:11], v[82:83], v[196:197]
	v_pk_fma_f32 v[12:13], v[12:13], v[84:85], v[198:199]
	s_add_u32 s94, s94, 0x10000
	s_addc_u32 s95, s95, 0
	v_cvt_pk_bf16_f32 v14, v14, v15
	v_cvt_pk_bf16_f32 v15, v16, v17
	v_cvt_pk_bf16_f32 v16, v10, v11
	v_cvt_pk_bf16_f32 v17, v12, v13
	global_store_dwordx4 v200, v[14:17], s[94:95]
	s_waitcnt vmcnt(6)
	v_pk_fma_f32 v[6:7], v[6:7], v[70:71], v[210:211]
	v_pk_fma_f32 v[8:9], v[8:9], v[72:73], v[212:213]
	v_pk_fma_f32 v[2:3], v[2:3], v[66:67], v[214:215]
	v_pk_fma_f32 v[4:5], v[4:5], v[68:69], v[216:217]
	v_cvt_pk_bf16_f32 v6, v6, v7
	v_cvt_pk_bf16_f32 v7, v8, v9
	v_cvt_pk_bf16_f32 v8, v2, v3
	v_cvt_pk_bf16_f32 v9, v4, v5
	global_store_dwordx4 v200, v[6:9], s[94:95] offset:256
	s_mov_b32 s2, s12
	s_mov_b64 s[20:21], s[14:15]
	s_mov_b64 s[18:19], s[16:17]
	s_and_b64 vcc, exec, s[4:5]
	s_nop 1
	s_cbranch_vccz .LBB0_134
	s_waitcnt vmcnt(0)
	s_cmpk_gt_u32 s29, 0xff
	s_cbranch_scc1 .LBB0_145
	s_barrier

; #define PG8_STAGE(bufoff, gbase, voff) do { _Pragma("unroll") for (int _i = 0; _i < 2; ++_i) \
;         __builtin_amdgcn_global_load_lds((const unsigned*)((const char*)(gbase) + (voff)[_i]), (LAS unsigned*)(lds + (bufoff) + ldsw + _i * 8192), 16, 0, 0); } while (0)
; #define PG8_LDA(dst, b, h) do { _Pragma("unroll") for (int m = 0; m < 4; ++m) _Pragma("unroll") for (int k = 0; k < 2; ++k) dst[m][k] = *(const LAS bf16x8*)(lds + PG8_SA(b, h) + aoff + m * 2048 + k * 1024); } while (0)
; #define PG8_LDB(dst, b, h) do { _Pragma("unroll") for (int n = 0; n < 2; ++n) _Pragma("unroll") for (int k = 0; k < 2; ++k) dst[n][k] = *(const LAS bf16x8*)(lds + PG8_SB(b, h) + boff + n * 2048 + k * 1024); } while (0)
; #define PG8_MMA(ai, bj, At, Bt) do { __builtin_amdgcn_s_setprio(1); _Pragma("unroll") for (int m = 0; m < 4; ++m) _Pragma("unroll") for (int n = 0; n < 2; ++n) _Pragma("unroll") for (int k = 0; k < 2; ++k) \
;         acc[ai][bj][m][n] = __builtin_amdgcn_mfma_f32_16x16x32_bf16(Bt[n][k], At[m][k], acc[ai][bj][m][n], 0, 0, 0); __builtin_amdgcn_s_setprio(0); } while (0)
; #define PG8_WAIT_V(n) asm volatile("s_waitcnt vmcnt(" #n ")" ::: "memory")
; #define PG8_WAIT_L(n) asm volatile("s_waitcnt lgkmcnt(" #n ")" ::: "memory")
; #define PG8_BAR __builtin_amdgcn_s_barrier()
; template <class Epi>
; __device__ __forceinline__ void gemm_phase(LAS unsigned char* lds, const Gemm g, const StaticOrder& S, const Epi& E, const int tid) {
;     ...
;             const bool last = (t == nt - 2);
;             const char* a1 = cA + (size_t)(t + 1) * kstep;
;             const char* a2 = last ? nA : cA + (size_t)(t + 2) * kstep; const char* b2 = last ? nB : cB + (size_t)(t + 2) * kstep;
;             const char* a3 = a2 + kstep; const char* b3 = b2 + kstep;
;             PG8_LDB(B0, 0, 0); PG8_SCHED; PG8_LDA(At, 0, 0); PG8_STAGE(PG8_SA(1, 1), a1 + hstep, voffA);
;             PG8_WAIT_L(8); PG8_BAR; PG8_WAIT_L(0); PG8_MMA(0, 0, At, B0); PG8_BAR; PG8_SCHED;
;             PG8_LDB(B1, 0, 1); PG8_STAGE(PG8_SB(0, 0), b2, voffB);
;             PG8_BAR; PG8_WAIT_L(0); PG8_MMA(0, 1, At, B1); PG8_BAR;
;             PG8_LDA(At, 0, 1); PG8_STAGE(PG8_SA(0, 0), a2, voffA);
;             PG8_BAR; PG8_WAIT_L(0); PG8_MMA(1, 0, At, B0); PG8_BAR; PG8_SCHED;
;             PG8_STAGE(PG8_SB(0, 1), b2 + hstep, voffB);
;             PG8_WAIT_V(6); PG8_BAR; PG8_MMA(1, 1, At, B1); PG8_BAR;
.Lgprio5:
.LBB0_286:
	s_add_u32 s8, s6, 0xfff80080
	s_addc_u32 s9, s7, -1
	s_add_i32 s37, 0, 0x10000
	v_add_u32_e32 v0, s37, v210
	ds_read_b128 v[130:133], v0
	ds_read_b128 v[134:137], v0 offset:1024
	ds_read_b128 v[138:141], v0 offset:2048
	ds_read_b128 v[142:145], v0 offset:3072
	s_cmp_eq_u32 s36, 28
	s_cselect_b32 s35, s3, s9
	s_cselect_b32 s34, s27, s8
	s_cselect_b32 s9, s25, s72
	s_cselect_b32 s8, s50, s66
	s_add_i32 m0, s21, 0xc000
	ds_read_b128 v[172:175], v211
	ds_read_b128 v[176:179], v211 offset:1024
	ds_read_b128 v[180:183], v211 offset:2048
	ds_read_b128 v[184:187], v211 offset:3072
	ds_read_b128 v[188:191], v211 offset:4096
	ds_read_b128 v[192:195], v211 offset:5120
	ds_read_b128 v[196:199], v211 offset:6144
	ds_read_b128 v[212:215], v211 offset:7168
	global_load_lds_dwordx4 v170, s[6:7]
	s_add_i32 m0, s21, 0xe000
	s_nop 0
	global_load_lds_dwordx4 v168, s[6:7]
	s_waitcnt lgkmcnt(8)
	s_barrier
	s_waitcnt lgkmcnt(0)
	v_mfma_f32_16x16x32_bf16 v[126:129], v[130:133], v[172:175], v[126:129]
	v_mfma_f32_16x16x32_bf16 v[122:125], v[138:141], v[172:175], v[122:125]
	v_mfma_f32_16x16x32_bf16 v[118:121], v[130:133], v[180:183], v[118:121]
	v_mfma_f32_16x16x32_bf16 v[114:117], v[138:141], v[180:183], v[114:117]
	v_mfma_f32_16x16x32_bf16 v[102:105], v[130:133], v[188:191], v[102:105]
	v_mfma_f32_16x16x32_bf16 v[98:101], v[138:141], v[188:191], v[98:101]
	v_mfma_f32_16x16x32_bf16 v[86:89], v[130:133], v[196:199], v[86:89]
	v_mfma_f32_16x16x32_bf16 v[82:85], v[138:141], v[196:199], v[82:85]
	v_mfma_f32_16x16x32_bf16 v[126:129], v[134:137], v[176:179], v[126:129]
	v_mfma_f32_16x16x32_bf16 v[122:125], v[142:145], v[176:179], v[122:125]
	v_mfma_f32_16x16x32_bf16 v[118:121], v[134:137], v[184:187], v[118:121]
	v_mfma_f32_16x16x32_bf16 v[114:117], v[142:145], v[184:187], v[114:117]
	v_mfma_f32_16x16x32_bf16 v[102:105], v[134:137], v[192:195], v[102:105]
	v_mfma_f32_16x16x32_bf16 v[98:101], v[142:145], v[192:195], v[98:101]
	v_mfma_f32_16x16x32_bf16 v[86:89], v[134:137], v[212:215], v[86:89]
	v_mfma_f32_16x16x32_bf16 v[82:85], v[142:145], v[212:215], v[82:85]
	s_barrier
	s_add_i32 s73, 0, 0x14000
	s_add_i32 s37, s37, s39
	v_add_u32_e32 v0, s73, v210
	v_lshl_add_u64 v[200:201], s[8:9], 0, v[162:163]
	s_mov_b32 m0, s37
	ds_read_b128 v[216:219], v0
	ds_read_b128 v[220:223], v0 offset:1024
	ds_read_b128 v[224:227], v0 offset:2048
	ds_read_b128 v[228:231], v0 offset:3072
	global_load_lds_dwordx4 v[200:201], off
	v_lshl_add_u64 v[232:233], s[8:9], 0, v[166:167]
	s_add_i32 m0, s37, 0x2000
	s_nop 0
	global_load_lds_dwordx4 v[232:233], off
	s_barrier
	s_waitcnt lgkmcnt(0)
	v_mfma_f32_16x16x32_bf16 v[110:113], v[216:219], v[172:175], v[110:113]
	v_mfma_f32_16x16x32_bf16 v[106:109], v[224:227], v[172:175], v[106:109]
	v_mfma_f32_16x16x32_bf16 v[94:97], v[216:219], v[180:183], v[94:97]
	v_mfma_f32_16x16x32_bf16 v[90:93], v[224:227], v[180:183], v[90:93]
	v_mfma_f32_16x16x32_bf16 v[78:81], v[216:219], v[188:191], v[78:81]
	v_mfma_f32_16x16x32_bf16 v[74:77], v[224:227], v[188:191], v[74:77]
	v_mfma_f32_16x16x32_bf16 v[70:73], v[216:219], v[196:199], v[70:73]
	v_mfma_f32_16x16x32_bf16 v[66:69], v[224:227], v[196:199], v[66:69]
	v_mfma_f32_16x16x32_bf16 v[110:113], v[220:223], v[176:179], v[110:113]
	v_mfma_f32_16x16x32_bf16 v[106:109], v[228:231], v[176:179], v[106:109]
	v_mfma_f32_16x16x32_bf16 v[94:97], v[220:223], v[184:187], v[94:97]
	v_mfma_f32_16x16x32_bf16 v[90:93], v[228:231], v[184:187], v[90:93]
	v_mfma_f32_16x16x32_bf16 v[78:81], v[220:223], v[192:195], v[78:81]
	v_mfma_f32_16x16x32_bf16 v[74:77], v[228:231], v[192:195], v[74:77]
	v_mfma_f32_16x16x32_bf16 v[70:73], v[220:223], v[212:215], v[70:73]
	v_mfma_f32_16x16x32_bf16 v[66:69], v[228:231], v[212:215], v[66:69]
	s_mov_b32 m0, s21
	v_lshl_add_u64 v[234:235], s[34:35], 0, v[160:161]
	s_barrier
	ds_read_b128 v[172:175], v211 offset:16384
	ds_read_b128 v[176:179], v211 offset:17408
	ds_read_b128 v[180:183], v211 offset:18432
	ds_read_b128 v[184:187], v211 offset:19456
	ds_read_b128 v[188:191], v211 offset:20480
	ds_read_b128 v[192:195], v211 offset:21504
	ds_read_b128 v[196:199], v211 offset:22528
	ds_read_b128 v[212:215], v211 offset:23552
	global_load_lds_dwordx4 v[234:235], off
	v_lshl_add_u64 v[236:237], s[34:35], 0, v[164:165]
	s_mov_b32 m0, s40
	s_nop 0
	global_load_lds_dwordx4 v[236:237], off
	s_barrier
	s_waitcnt lgkmcnt(0)
	v_mfma_f32_16x16x32_bf16 v[62:65], v[130:133], v[172:175], v[62:65]
	v_mfma_f32_16x16x32_bf16 v[58:61], v[138:141], v[172:175], v[58:61]
	v_mfma_f32_16x16x32_bf16 v[54:57], v[130:133], v[180:183], v[54:57]
	v_mfma_f32_16x16x32_bf16 v[50:53], v[138:141], v[180:183], v[50:53]
	v_mfma_f32_16x16x32_bf16 v[38:41], v[130:133], v[188:191], v[38:41]
	v_mfma_f32_16x16x32_bf16 v[34:37], v[138:141], v[188:191], v[34:37]
	v_mfma_f32_16x16x32_bf16 v[22:25], v[130:133], v[196:199], v[22:25]
	v_mfma_f32_16x16x32_bf16 v[18:21], v[138:141], v[196:199], v[18:21]
	v_mfma_f32_16x16x32_bf16 v[62:65], v[134:137], v[176:179], v[62:65]
	v_mfma_f32_16x16x32_bf16 v[58:61], v[142:145], v[176:179], v[58:61]
	v_mfma_f32_16x16x32_bf16 v[54:57], v[134:137], v[184:187], v[54:57]
	v_mfma_f32_16x16x32_bf16 v[50:53], v[142:145], v[184:187], v[50:53]
	v_mfma_f32_16x16x32_bf16 v[38:41], v[134:137], v[192:195], v[38:41]
	v_mfma_f32_16x16x32_bf16 v[34:37], v[142:145], v[192:195], v[34:37]
	v_mfma_f32_16x16x32_bf16 v[22:25], v[134:137], v[212:215], v[22:25]
	v_mfma_f32_16x16x32_bf16 v[18:21], v[142:145], v[212:215], v[18:21]
	s_barrier
	s_add_u32 s74, s8, 0x80000
	s_addc_u32 s75, s9, 0
	s_add_i32 s37, s73, s39
	s_mov_b32 m0, s37
	s_nop 0
	global_load_lds_dwordx4 v162, s[74:75]
	s_add_i32 m0, s37, 0x2000
	s_nop 0
	global_load_lds_dwordx4 v166, s[74:75]
	s_waitcnt vmcnt(6)
	s_barrier
; #define PG8_STAGE(bufoff, gbase, voff) do { _Pragma("unroll") for (int _i = 0; _i < 2; ++_i) \
;         __builtin_amdgcn_global_load_lds((const unsigned*)((const char*)(gbase) + (voff)[_i]), (LAS unsigned*)(lds + (bufoff) + ldsw + _i * 8192), 16, 0, 0); } while (0)
; #define PG8_LDA(dst, b, h) do { _Pragma("unroll") for (int m = 0; m < 4; ++m) _Pragma("unroll") for (int k = 0; k < 2; ++k) dst[m][k] = *(const LAS bf16x8*)(lds + PG8_SA(b, h) + aoff + m * 2048 + k * 1024); } while (0)
; #define PG8_LDB(dst, b, h) do { _Pragma("unroll") for (int n = 0; n < 2; ++n) _Pragma("unroll") for (int k = 0; k < 2; ++k) dst[n][k] = *(const LAS bf16x8*)(lds + PG8_SB(b, h) + boff + n * 2048 + k * 1024); } while (0)
; #define PG8_MMA(ai, bj, At, Bt) do { __builtin_amdgcn_s_setprio(1); _Pragma("unroll") for (int m = 0; m < 4; ++m) _Pragma("unroll") for (int n = 0; n < 2; ++n) _Pragma("unroll") for (int k = 0; k < 2; ++k) \
;         acc[ai][bj][m][n] = __builtin_amdgcn_mfma_f32_16x16x32_bf16(Bt[n][k], At[m][k], acc[ai][bj][m][n], 0, 0, 0); __builtin_amdgcn_s_setprio(0); } while (0)
; #define PG8_WAIT_V(n) asm volatile("s_waitcnt vmcnt(" #n ")" ::: "memory")
; #define PG8_WAIT_L(n) asm volatile("s_waitcnt lgkmcnt(" #n ")" ::: "memory")
; #define PG8_BAR __builtin_amdgcn_s_barrier()
; #define PG8_SCHED __builtin_amdgcn_sched_barrier(0)
; template <class Epi>
; __device__ __forceinline__ void gemm_phase(LAS unsigned char* lds, const Gemm g, const StaticOrder& S, const Epi& E, const int tid) {
;     ...
;             PG8_WAIT_V(6); PG8_BAR; PG8_MMA(1, 1, At, B1); PG8_BAR;
;             PG8_LDB(B0, 1, 0); PG8_SCHED; PG8_LDA(At, 1, 0); PG8_STAGE(PG8_SA(0, 1), a2 + hstep, voffA);
;             PG8_WAIT_L(8); PG8_BAR; PG8_WAIT_L(0); PG8_MMA(0, 0, At, B0); PG8_BAR; PG8_SCHED;
;             PG8_LDB(B1, 1, 1); PG8_STAGE(PG8_SB(1, 0), b3, voffB);
;             PG8_BAR; PG8_WAIT_L(0); PG8_MMA(0, 1, At, B1); PG8_BAR;
;             PG8_LDA(At, 1, 1); PG8_STAGE(PG8_SA(1, 0), a3, voffA);
;             PG8_BAR; PG8_WAIT_L(0); PG8_MMA(1, 0, At, B0); PG8_BAR; PG8_SCHED;
	v_mfma_f32_16x16x32_bf16 v[46:49], v[216:219], v[172:175], v[46:49]
	v_mfma_f32_16x16x32_bf16 v[42:45], v[224:227], v[172:175], v[42:45]
	v_mfma_f32_16x16x32_bf16 v[30:33], v[216:219], v[180:183], v[30:33]
	v_mfma_f32_16x16x32_bf16 v[26:29], v[224:227], v[180:183], v[26:29]
	v_mfma_f32_16x16x32_bf16 v[14:17], v[216:219], v[188:191], v[14:17]
	v_mfma_f32_16x16x32_bf16 v[10:13], v[224:227], v[188:191], v[10:13]
	v_mfma_f32_16x16x32_bf16 v[6:9], v[216:219], v[196:199], v[6:9]
	v_mfma_f32_16x16x32_bf16 v[2:5], v[224:227], v[196:199], v[2:5]
	v_mfma_f32_16x16x32_bf16 v[46:49], v[220:223], v[176:179], v[46:49]
	v_mfma_f32_16x16x32_bf16 v[42:45], v[228:231], v[176:179], v[42:45]
	v_mfma_f32_16x16x32_bf16 v[30:33], v[220:223], v[184:187], v[30:33]
	v_mfma_f32_16x16x32_bf16 v[26:29], v[228:231], v[184:187], v[26:29]
	v_mfma_f32_16x16x32_bf16 v[14:17], v[220:223], v[192:195], v[14:17]
	v_mfma_f32_16x16x32_bf16 v[10:13], v[228:231], v[192:195], v[10:13]
	v_mfma_f32_16x16x32_bf16 v[6:9], v[220:223], v[212:215], v[6:9]
	v_mfma_f32_16x16x32_bf16 v[2:5], v[228:231], v[212:215], v[2:5]
	s_add_i32 s37, 0, 0x18000
	v_add_u32_e32 v0, s37, v210
	s_barrier
	ds_read_b128 v[130:133], v0
	ds_read_b128 v[134:137], v0 offset:1024
	ds_read_b128 v[138:141], v0 offset:2048
	ds_read_b128 v[142:145], v0 offset:3072
	s_add_u32 s34, s34, 0x80000
	s_addc_u32 s35, s35, 0
	s_mov_b32 m0, s41
	ds_read_b128 v[172:175], v211 offset:32768
	ds_read_b128 v[176:179], v211 offset:33792
	ds_read_b128 v[180:183], v211 offset:34816
	ds_read_b128 v[184:187], v211 offset:35840
	ds_read_b128 v[188:191], v211 offset:36864
	ds_read_b128 v[192:195], v211 offset:37888
	ds_read_b128 v[196:199], v211 offset:38912
	ds_read_b128 v[212:215], v211 offset:39936
	global_load_lds_dwordx4 v160, s[34:35]
	s_mov_b32 m0, s42
	s_nop 0
	global_load_lds_dwordx4 v164, s[34:35]
	s_waitcnt lgkmcnt(8)
	s_barrier
	s_waitcnt lgkmcnt(0)
	v_mfma_f32_16x16x32_bf16 v[126:129], v[130:133], v[172:175], v[126:129]
	v_mfma_f32_16x16x32_bf16 v[122:125], v[138:141], v[172:175], v[122:125]
	v_mfma_f32_16x16x32_bf16 v[118:121], v[130:133], v[180:183], v[118:121]
	v_mfma_f32_16x16x32_bf16 v[114:117], v[138:141], v[180:183], v[114:117]
	v_mfma_f32_16x16x32_bf16 v[102:105], v[130:133], v[188:191], v[102:105]
	v_mfma_f32_16x16x32_bf16 v[98:101], v[138:141], v[188:191], v[98:101]
	v_mfma_f32_16x16x32_bf16 v[86:89], v[130:133], v[196:199], v[86:89]
	v_mfma_f32_16x16x32_bf16 v[82:85], v[138:141], v[196:199], v[82:85]
	v_mfma_f32_16x16x32_bf16 v[126:129], v[134:137], v[176:179], v[126:129]
	v_mfma_f32_16x16x32_bf16 v[122:125], v[142:145], v[176:179], v[122:125]
	v_mfma_f32_16x16x32_bf16 v[118:121], v[134:137], v[184:187], v[118:121]
	v_mfma_f32_16x16x32_bf16 v[114:117], v[142:145], v[184:187], v[114:117]
	v_mfma_f32_16x16x32_bf16 v[102:105], v[134:137], v[192:195], v[102:105]
	v_mfma_f32_16x16x32_bf16 v[98:101], v[142:145], v[192:195], v[98:101]
	v_mfma_f32_16x16x32_bf16 v[86:89], v[134:137], v[212:215], v[86:89]
	v_mfma_f32_16x16x32_bf16 v[82:85], v[142:145], v[212:215], v[82:85]
	s_barrier
	s_add_i32 s34, 0, 0x1c000
	s_add_i32 s35, s37, s39
	v_add_u32_e32 v0, s34, v210
	v_lshl_add_u64 v[200:201], v[200:201], 0, s[56:57]
	s_mov_b32 m0, s35
	ds_read_b128 v[216:219], v0
	ds_read_b128 v[220:223], v0 offset:1024
	ds_read_b128 v[224:227], v0 offset:2048
	ds_read_b128 v[228:231], v0 offset:3072
	global_load_lds_dwordx4 v[200:201], off
	v_lshl_add_u64 v[200:201], v[232:233], 0, s[56:57]
	s_add_i32 m0, s35, 0x2000
	s_nop 0
	global_load_lds_dwordx4 v[200:201], off
	s_barrier
	s_waitcnt lgkmcnt(0)
	v_mfma_f32_16x16x32_bf16 v[110:113], v[216:219], v[172:175], v[110:113]
	v_mfma_f32_16x16x32_bf16 v[106:109], v[224:227], v[172:175], v[106:109]
	v_mfma_f32_16x16x32_bf16 v[94:97], v[216:219], v[180:183], v[94:97]
	v_mfma_f32_16x16x32_bf16 v[90:93], v[224:227], v[180:183], v[90:93]
	v_mfma_f32_16x16x32_bf16 v[78:81], v[216:219], v[188:191], v[78:81]
	v_mfma_f32_16x16x32_bf16 v[74:77], v[224:227], v[188:191], v[74:77]
	v_mfma_f32_16x16x32_bf16 v[70:73], v[216:219], v[196:199], v[70:73]
	v_mfma_f32_16x16x32_bf16 v[66:69], v[224:227], v[196:199], v[66:69]
	v_mfma_f32_16x16x32_bf16 v[110:113], v[220:223], v[176:179], v[110:113]
	v_mfma_f32_16x16x32_bf16 v[106:109], v[228:231], v[176:179], v[106:109]
	v_mfma_f32_16x16x32_bf16 v[94:97], v[220:223], v[184:187], v[94:97]
	v_mfma_f32_16x16x32_bf16 v[90:93], v[228:231], v[184:187], v[90:93]
	v_mfma_f32_16x16x32_bf16 v[78:81], v[220:223], v[192:195], v[78:81]
	v_mfma_f32_16x16x32_bf16 v[74:77], v[228:231], v[192:195], v[74:77]
	v_mfma_f32_16x16x32_bf16 v[70:73], v[220:223], v[212:215], v[70:73]
	v_mfma_f32_16x16x32_bf16 v[66:69], v[228:231], v[212:215], v[66:69]
	s_mov_b32 m0, s49
	v_lshl_add_u64 v[200:201], v[234:235], 0, s[56:57]
	s_barrier
; __device__ __forceinline__ unsigned pk2(float lo, float hi) { f32x2 v = {lo, hi}; return __builtin_bit_cast(unsigned, __builtin_convertvector(v, bf16x2_t)); }
; #define PG8_STAGE(bufoff, gbase, voff) do { _Pragma("unroll") for (int _i = 0; _i < 2; ++_i) \
;         __builtin_amdgcn_global_load_lds((const unsigned*)((const char*)(gbase) + (voff)[_i]), (LAS unsigned*)(lds + (bufoff) + ldsw + _i * 8192), 16, 0, 0); } while (0)
;     __device__ __forceinline__ void operator()(const f32x4 (&acc)[2][2][4][2], const Unit& u, int wr, int wc, int fr, int fq) const {
;     ...
;         const int type = (u.pn >> 2) % 3, grp = u.pn / 12;
;         const int row0 = u.pm * BM + wr * 64 + fr, col0 = u.pn * BM + wc * 32 + 8 * fq;
;         if (type == 2) {
; #pragma unroll
;             for (int ai = 0; ai < 2; ++ai)
; #pragma unroll
;                 for (int m = 0; m < 4; ++m) {
;                     bf16_t* rowp = O + ((size_t)(2 * u.pn) * MTOK + (row0 + ai * HALF + m * 16)) * 128 + wc * 32 + 8 * fq;
; #pragma unroll
;                     for (int bj = 0; bj < 2; ++bj) { const f32x4 v0 = acc[ai][bj][m][0], v1 = acc[ai][bj][m][1];
;                         u32x4 w; w.x = pk2(v0[0], v0[1]); w.y = pk2(v0[2], v0[3]); w.z = pk2(v1[0], v1[1]); w.w = pk2(v1[2], v1[3]); *(u32x4*)(rowp + (size_t)bj * MTOK * 128) = w; }
;                 }
;             return;
;         }
; #pragma unroll
;         for (int ai = 0; ai < 2; ++ai)
; #pragma unroll
;             for (int m = 0; m < 4; ++m)
; #pragma unroll
;                 for (int bj = 0; bj < 2; ++bj) {
;                     const f32x4 a = acc[ai][bj][m][0], b = acc[ai][bj][m][1];
;                     float s = (a[0] * a[0] + a[1] * a[1]) + (a[2] * a[2] + a[3] * a[3]) + (b[0] * b[0] + b[1] * b[1]) + (b[2] * b[2] + b[3] * b[3]);
;                     s += __shfl_xor(s, 16); s += __shfl_xor(s, 32);
;                     if (fq == 0) T[((wr * 128 + ai * 64 + m * 16 + fr) * 2 + bj) * 4 + wc] = s;
; template <class Epi>
; __device__ __forceinline__ void gemm_phase(LAS unsigned char* lds, const Gemm g, const StaticOrder& S, const Epi& E, const int tid) {
;     ...
;             PG8_BAR; PG8_WAIT_L(0); PG8_MMA(1, 0, At, B0); PG8_BAR; PG8_SCHED;
;             PG8_STAGE(PG8_SB(1, 1), b3 + hstep, voffB);
;             PG8_WAIT_V(6); PG8_BAR; PG8_MMA(1, 1, At, B1); PG8_BAR;
;         }
;         E(acc, cur, wr, wc, fr, fq);
	ds_read_b128 v[172:175], v211 offset:49152
	ds_read_b128 v[176:179], v211 offset:50176
	ds_read_b128 v[180:183], v211 offset:51200
	ds_read_b128 v[184:187], v211 offset:52224
	ds_read_b128 v[188:191], v211 offset:53248
	ds_read_b128 v[192:195], v211 offset:54272
	ds_read_b128 v[196:199], v211 offset:55296
	ds_read_b128 v[212:215], v211 offset:56320
	global_load_lds_dwordx4 v[200:201], off
	v_lshl_add_u64 v[200:201], v[236:237], 0, s[56:57]
	s_mov_b32 m0, s52
	s_nop 0
	global_load_lds_dwordx4 v[200:201], off
	s_barrier
	s_waitcnt lgkmcnt(0)
	v_mfma_f32_16x16x32_bf16 v[62:65], v[130:133], v[172:175], v[62:65]
	v_mfma_f32_16x16x32_bf16 v[58:61], v[138:141], v[172:175], v[58:61]
	v_mfma_f32_16x16x32_bf16 v[54:57], v[130:133], v[180:183], v[54:57]
	v_mfma_f32_16x16x32_bf16 v[50:53], v[138:141], v[180:183], v[50:53]
	v_mfma_f32_16x16x32_bf16 v[38:41], v[130:133], v[188:191], v[38:41]
	v_mfma_f32_16x16x32_bf16 v[34:37], v[138:141], v[188:191], v[34:37]
	v_mfma_f32_16x16x32_bf16 v[22:25], v[130:133], v[196:199], v[22:25]
	v_mfma_f32_16x16x32_bf16 v[18:21], v[138:141], v[196:199], v[18:21]
	v_mfma_f32_16x16x32_bf16 v[62:65], v[134:137], v[176:179], v[62:65]
	v_mfma_f32_16x16x32_bf16 v[58:61], v[142:145], v[176:179], v[58:61]
	v_mfma_f32_16x16x32_bf16 v[54:57], v[134:137], v[184:187], v[54:57]
	v_mfma_f32_16x16x32_bf16 v[50:53], v[142:145], v[184:187], v[50:53]
	v_mfma_f32_16x16x32_bf16 v[38:41], v[134:137], v[192:195], v[38:41]
	v_mfma_f32_16x16x32_bf16 v[34:37], v[142:145], v[192:195], v[34:37]
	v_mfma_f32_16x16x32_bf16 v[22:25], v[134:137], v[212:215], v[22:25]
	v_mfma_f32_16x16x32_bf16 v[18:21], v[142:145], v[212:215], v[18:21]
	s_barrier
	s_add_i32 s36, s36, 2
	s_add_u32 s66, s66, 0x100
	s_addc_u32 s72, s72, 0
	s_add_u32 s6, s6, 0x100
	s_addc_u32 s7, s7, 0
	s_add_u32 s8, s8, 0x80080
	s_addc_u32 s9, s9, 0
	s_add_i32 s34, s34, s39
	s_mov_b32 m0, s34
	s_nop 0
	global_load_lds_dwordx4 v162, s[8:9]
	s_add_i32 m0, s34, 0x2000
	s_nop 0
	global_load_lds_dwordx4 v166, s[8:9]
	s_waitcnt vmcnt(6)
	s_barrier
	v_mfma_f32_16x16x32_bf16 v[46:49], v[216:219], v[172:175], v[46:49]
	v_mfma_f32_16x16x32_bf16 v[42:45], v[224:227], v[172:175], v[42:45]
	v_mfma_f32_16x16x32_bf16 v[30:33], v[216:219], v[180:183], v[30:33]
	v_mfma_f32_16x16x32_bf16 v[26:29], v[224:227], v[180:183], v[26:29]
	v_mfma_f32_16x16x32_bf16 v[14:17], v[216:219], v[188:191], v[14:17]
	v_mfma_f32_16x16x32_bf16 v[10:13], v[224:227], v[188:191], v[10:13]
	v_mfma_f32_16x16x32_bf16 v[6:9], v[216:219], v[196:199], v[6:9]
	v_mfma_f32_16x16x32_bf16 v[2:5], v[224:227], v[196:199], v[2:5]
	v_mfma_f32_16x16x32_bf16 v[46:49], v[220:223], v[176:179], v[46:49]
	v_mfma_f32_16x16x32_bf16 v[42:45], v[228:231], v[176:179], v[42:45]
	v_mfma_f32_16x16x32_bf16 v[30:33], v[220:223], v[184:187], v[30:33]
	v_mfma_f32_16x16x32_bf16 v[26:29], v[228:231], v[184:187], v[26:29]
	v_mfma_f32_16x16x32_bf16 v[14:17], v[220:223], v[192:195], v[14:17]
	v_mfma_f32_16x16x32_bf16 v[10:13], v[228:231], v[192:195], v[10:13]
	v_mfma_f32_16x16x32_bf16 v[6:9], v[220:223], v[212:215], v[6:9]
	v_mfma_f32_16x16x32_bf16 v[2:5], v[228:231], v[212:215], v[2:5]
	s_cmp_gt_u32 s36, 29
	s_barrier
	s_cbranch_scc0 .LBB0_286
	s_setprio 0
	s_ashr_i32 s3, s20, 2
	s_mul_hi_i32 s6, s3, 0x55555556
	s_lshr_b32 s7, s6, 31
	s_add_i32 s6, s6, s7
	s_mul_i32 s6, s6, 3
	s_lshl_b32 s2, s2, 8
	v_mov_b32_e32 v138, v159
	v_mov_b32_e32 v0, v209
	s_sub_i32 s6, s3, s6
	s_add_i32 s2, s2, s47
	s_cmp_eq_u32 s6, 2
	v_add_u32_e32 v174, s2, v138
	v_lshlrev_b32_e32 v172, 3, v0
	s_mov_b64 s[2:3], -1
	s_cbranch_scc1 .LBB0_376
	v_mul_f32_e32 v132, v127, v127
	v_mul_f32_e32 v133, v129, v129
	v_fmac_f32_e32 v132, v126, v126
	v_fmac_f32_e32 v133, v128, v128
	v_and_b32_e32 v131, 64, v204
	v_add_f32_e32 v132, v132, v133
	v_mul_f32_e32 v133, v123, v123
	v_xor_b32_e32 v130, 16, v204
	v_add_u32_e32 v131, 64, v131
	v_fmac_f32_e32 v133, v122, v122
	v_cmp_lt_i32_e32 vcc, v130, v131
	v_add_f32_e32 v132, v132, v133
	v_mul_f32_e32 v133, v125, v125
	v_cndmask_b32_e32 v130, v204, v130, vcc
	v_fmac_f32_e32 v133, v124, v124
	v_lshlrev_b32_e32 v130, 2, v130
	v_add_f32_e32 v132, v133, v132
	ds_bpermute_b32 v133, v130, v132
	v_xor_b32_e32 v134, 32, v204
	v_cmp_lt_i32_e32 vcc, v134, v131
	v_lshlrev_b32_e32 v175, 5, v138
	s_waitcnt lgkmcnt(0)
	v_add_f32_e32 v132, v132, v133
	v_cndmask_b32_e32 v131, v204, v134, vcc
	v_lshlrev_b32_e32 v212, 2, v131
	ds_bpermute_b32 v133, v212, v132
	v_cmp_eq_u32_e32 vcc, 0, v0
	v_add_u32_e32 v131, s63, v175
	s_and_saveexec_b64 s[2:3], vcc
	s_cbranch_execz .LBB0_290
	s_waitcnt lgkmcnt(0)
	v_add_f32_e32 v132, v132, v133
	ds_write_b32 v131, v132
